# mixer phase rebalance: the two ret_kv tiles of each compress block moved to blocks 256..511 (which re-run their ret_kv tile code for the moved tile first)
# baseline (speedup 1.0000x reference)
.LBB0_621:
	v_lshl_add_u64 v[16:17], v[12:13], 0, s[0:1]
	global_load_dwordx4 v[2:5], v[16:17], off offset:1072
	global_load_dwordx4 v[6:9], v[16:17], off offset:1056
	global_load_dwordx4 v[20:23], v[16:17], off offset:1040
	global_load_dwordx4 v[24:27], v[16:17], off offset:1024
	s_add_u32 s0, s0, 0x80
	s_addc_u32 s1, s1, 0
	s_cmp_lg_u32 s0, s65
	s_waitcnt vmcnt(0)
	v_lshlrev_b32_e32 v0, 16, v24
	v_mul_f32_e32 v19, v0, v0
	v_fmamk_f32 v19, v19, 0xbdd2d3e7, v129
	v_mul_f32_e32 v19, v19, v0
	v_exp_f32_e32 v19, v19
	v_and_b32_e32 v40, 0xffff0000, v27
	v_add_f32_e32 v19, 1.0, v19
	v_rcp_f32_e32 v19, v19
	s_nop 0
	v_mul_f32_e32 v29, v19, v0
	v_and_b32_e32 v0, 0xffff0000, v24
	v_mul_f32_e32 v19, v0, v0
	v_fmamk_f32 v19, v19, 0xbdd2d3e7, v129
	v_mul_f32_e32 v19, v19, v0
	v_exp_f32_e32 v19, v19
	v_mul_f32_e32 v28, v29, v29
	v_add_f32_e32 v19, 1.0, v19
	v_rcp_f32_e32 v19, v19
	s_nop 0
	v_mul_f32_e32 v33, v19, v0
	v_lshlrev_b32_e32 v0, 16, v25
	v_mul_f32_e32 v19, v0, v0
	v_fmamk_f32 v19, v19, 0xbdd2d3e7, v129
	v_mul_f32_e32 v19, v19, v0
	v_exp_f32_e32 v19, v19
	v_mul_f32_e32 v32, v33, v33
	v_add_f32_e32 v19, 1.0, v19
	v_rcp_f32_e32 v19, v19
	s_nop 0
	v_mul_f32_e32 v35, v19, v0
	v_and_b32_e32 v0, 0xffff0000, v25
	v_mul_f32_e32 v19, v0, v0
	v_fmamk_f32 v19, v19, 0xbdd2d3e7, v129
	v_mul_f32_e32 v19, v19, v0
	v_exp_f32_e32 v19, v19
	v_mul_f32_e32 v34, v35, v35
	v_add_f32_e32 v19, 1.0, v19
	v_rcp_f32_e32 v19, v19
	s_nop 0
	v_mul_f32_e32 v25, v19, v0
	v_lshlrev_b32_e32 v0, 16, v26
	v_mul_f32_e32 v19, v0, v0
	v_fmamk_f32 v19, v19, 0xbdd2d3e7, v129
	v_mul_f32_e32 v19, v19, v0
	v_exp_f32_e32 v19, v19
	v_mul_f32_e32 v24, v25, v25
	v_pk_add_f32 v[24:25], v[34:35], v[24:25]
	v_add_f32_e32 v19, 1.0, v19
	v_rcp_f32_e32 v19, v19
	s_nop 0
	v_mul_f32_e32 v37, v19, v0
	v_and_b32_e32 v0, 0xffff0000, v26
	v_mul_f32_e32 v19, v0, v0
	v_fmamk_f32 v19, v19, 0xbdd2d3e7, v129
	v_mul_f32_e32 v19, v19, v0
	v_exp_f32_e32 v19, v19
	v_mul_f32_e32 v26, v40, v40
	v_fmamk_f32 v26, v26, 0xbdd2d3e7, v129
	v_mul_f32_e32 v26, v26, v40
	v_add_f32_e32 v19, 1.0, v19
	v_rcp_f32_e32 v19, v19
	v_exp_f32_e32 v26, v26
	v_mul_f32_e32 v39, v19, v0
	v_lshlrev_b32_e32 v0, 16, v27
	v_mul_f32_e32 v19, v0, v0
	v_fmamk_f32 v19, v19, 0xbdd2d3e7, v129
	v_mul_f32_e32 v19, v19, v0
	v_exp_f32_e32 v19, v19
	v_add_f32_e32 v26, 1.0, v26
	v_rcp_f32_e32 v41, v26
	v_pk_add_f32 v[26:27], v[28:29], v[32:33]
	v_add_f32_e32 v19, 1.0, v19
	v_rcp_f32_e32 v19, v19
	v_mul_f32_e32 v36, v37, v37
	v_mul_f32_e32 v38, v39, v39
	v_pk_add_f32 v[14:15], v[14:15], v[26:27]
	v_mul_f32_e32 v27, v41, v40
	v_pk_add_f32 v[14:15], v[14:15], v[24:25]
	v_pk_add_f32 v[24:25], v[36:37], v[38:39]
	v_mul_f32_e32 v26, v27, v27
	v_pk_add_f32 v[14:15], v[14:15], v[24:25]
	v_mul_f32_e32 v25, v19, v0
	v_lshlrev_b32_e32 v0, 16, v20
	v_mul_f32_e32 v19, v0, v0
	v_fmamk_f32 v19, v19, 0xbdd2d3e7, v129
	v_mul_f32_e32 v19, v19, v0
	v_exp_f32_e32 v19, v19
	v_mul_f32_e32 v24, v25, v25
	v_pk_add_f32 v[24:25], v[24:25], v[26:27]
	v_and_b32_e32 v36, 0xffff0000, v23
	v_add_f32_e32 v19, 1.0, v19
	v_rcp_f32_e32 v19, v19
	v_pk_add_f32 v[14:15], v[14:15], v[24:25]
	v_mul_f32_e32 v25, v19, v0
	v_and_b32_e32 v0, 0xffff0000, v20
	v_mul_f32_e32 v19, v0, v0
	v_fmamk_f32 v19, v19, 0xbdd2d3e7, v129
	v_mul_f32_e32 v19, v19, v0
	v_exp_f32_e32 v19, v19
	v_mul_f32_e32 v24, v25, v25
	v_add_f32_e32 v19, 1.0, v19
	v_rcp_f32_e32 v19, v19
	s_nop 0
	v_mul_f32_e32 v27, v19, v0
	v_lshlrev_b32_e32 v0, 16, v21
	v_mul_f32_e32 v19, v0, v0
	v_fmamk_f32 v19, v19, 0xbdd2d3e7, v129
	v_mul_f32_e32 v19, v19, v0
	v_exp_f32_e32 v19, v19
	v_mul_f32_e32 v26, v27, v27
	v_add_f32_e32 v19, 1.0, v19
	v_rcp_f32_e32 v19, v19
	s_nop 0
	v_mul_f32_e32 v29, v19, v0
	v_and_b32_e32 v0, 0xffff0000, v21
	v_mul_f32_e32 v19, v0, v0
	v_fmamk_f32 v19, v19, 0xbdd2d3e7, v129
	v_mul_f32_e32 v19, v19, v0
	v_exp_f32_e32 v19, v19
	v_mul_f32_e32 v28, v29, v29
	v_add_f32_e32 v19, 1.0, v19
	v_rcp_f32_e32 v19, v19
	s_nop 0
	v_mul_f32_e32 v21, v19, v0
	v_lshlrev_b32_e32 v0, 16, v22
	v_mul_f32_e32 v19, v0, v0
	v_fmamk_f32 v19, v19, 0xbdd2d3e7, v129
	v_mul_f32_e32 v19, v19, v0
	v_exp_f32_e32 v19, v19
	v_mul_f32_e32 v20, v21, v21
	v_pk_add_f32 v[20:21], v[28:29], v[20:21]
	v_add_f32_e32 v19, 1.0, v19
	v_rcp_f32_e32 v19, v19
	s_nop 0
	v_mul_f32_e32 v33, v19, v0
	v_and_b32_e32 v0, 0xffff0000, v22
	v_mul_f32_e32 v19, v0, v0
	v_fmamk_f32 v19, v19, 0xbdd2d3e7, v129
	v_mul_f32_e32 v19, v19, v0
	v_exp_f32_e32 v19, v19
	v_mul_f32_e32 v22, v36, v36
	v_fmamk_f32 v22, v22, 0xbdd2d3e7, v129
	v_mul_f32_e32 v22, v22, v36
	v_add_f32_e32 v19, 1.0, v19
	v_rcp_f32_e32 v19, v19
	v_exp_f32_e32 v22, v22
	v_mul_f32_e32 v35, v19, v0
	v_lshlrev_b32_e32 v0, 16, v23
	v_mul_f32_e32 v19, v0, v0
	v_fmamk_f32 v19, v19, 0xbdd2d3e7, v129
	v_mul_f32_e32 v19, v19, v0
	v_exp_f32_e32 v19, v19
	v_add_f32_e32 v22, 1.0, v22
	v_rcp_f32_e32 v37, v22
	v_pk_add_f32 v[22:23], v[24:25], v[26:27]
	v_add_f32_e32 v19, 1.0, v19
	v_rcp_f32_e32 v19, v19
	v_mul_f32_e32 v32, v33, v33
	v_mul_f32_e32 v34, v35, v35
	v_pk_add_f32 v[14:15], v[14:15], v[22:23]
	v_mul_f32_e32 v23, v37, v36
	v_pk_add_f32 v[14:15], v[14:15], v[20:21]
	v_pk_add_f32 v[20:21], v[32:33], v[34:35]
	v_mul_f32_e32 v22, v23, v23
	v_pk_add_f32 v[14:15], v[14:15], v[20:21]
	v_mul_f32_e32 v21, v19, v0
	v_lshlrev_b32_e32 v0, 16, v6
	v_mul_f32_e32 v19, v0, v0
	v_fmamk_f32 v19, v19, 0xbdd2d3e7, v129
	v_mul_f32_e32 v19, v19, v0
	v_exp_f32_e32 v19, v19
	v_mul_f32_e32 v20, v21, v21
	v_pk_add_f32 v[20:21], v[20:21], v[22:23]
	v_and_b32_e32 v32, 0xffff0000, v9
	v_add_f32_e32 v19, 1.0, v19
	v_rcp_f32_e32 v19, v19
	v_pk_add_f32 v[14:15], v[14:15], v[20:21]
	v_mul_f32_e32 v21, v19, v0
	v_and_b32_e32 v0, 0xffff0000, v6
	v_mul_f32_e32 v6, v0, v0
	v_fmamk_f32 v6, v6, 0xbdd2d3e7, v129
	v_mul_f32_e32 v6, v6, v0
	v_exp_f32_e32 v6, v6
	v_mul_f32_e32 v20, v21, v21
	v_add_f32_e32 v6, 1.0, v6
	v_rcp_f32_e32 v6, v6
	s_nop 0
	v_mul_f32_e32 v23, v6, v0
	v_lshlrev_b32_e32 v0, 16, v7
	v_mul_f32_e32 v6, v0, v0
	v_fmamk_f32 v6, v6, 0xbdd2d3e7, v129
	v_mul_f32_e32 v6, v6, v0
	v_exp_f32_e32 v6, v6
	v_mul_f32_e32 v22, v23, v23
	v_add_f32_e32 v6, 1.0, v6
	v_rcp_f32_e32 v6, v6
	s_nop 0
	v_mul_f32_e32 v25, v6, v0
	v_and_b32_e32 v0, 0xffff0000, v7
	v_mul_f32_e32 v6, v0, v0
	v_fmamk_f32 v6, v6, 0xbdd2d3e7, v129
	v_mul_f32_e32 v6, v6, v0
	v_exp_f32_e32 v6, v6
	v_mul_f32_e32 v24, v25, v25
	v_add_f32_e32 v6, 1.0, v6
	v_rcp_f32_e32 v6, v6
	s_nop 0
	v_mul_f32_e32 v7, v6, v0
	v_lshlrev_b32_e32 v0, 16, v8
	v_mul_f32_e32 v19, v0, v0
	v_fmamk_f32 v19, v19, 0xbdd2d3e7, v129
	v_mul_f32_e32 v19, v19, v0
	v_exp_f32_e32 v19, v19
	v_mul_f32_e32 v6, v7, v7
	v_pk_add_f32 v[6:7], v[24:25], v[6:7]
	v_add_f32_e32 v19, 1.0, v19
	v_rcp_f32_e32 v19, v19
	s_nop 0
	v_mul_f32_e32 v27, v19, v0
	v_and_b32_e32 v0, 0xffff0000, v8
	v_mul_f32_e32 v8, v0, v0
	v_fmamk_f32 v8, v8, 0xbdd2d3e7, v129
	v_mul_f32_e32 v8, v8, v0
	v_exp_f32_e32 v8, v8
	v_mul_f32_e32 v26, v27, v27
	v_add_f32_e32 v8, 1.0, v8
	v_rcp_f32_e32 v8, v8
	s_nop 0
	v_mul_f32_e32 v29, v8, v0
	v_lshlrev_b32_e32 v0, 16, v9
	v_mul_f32_e32 v8, v0, v0
	v_fmamk_f32 v8, v8, 0xbdd2d3e7, v129
	v_mul_f32_e32 v8, v8, v0
	v_exp_f32_e32 v8, v8
	v_mul_f32_e32 v28, v29, v29
	v_add_f32_e32 v8, 1.0, v8
	v_rcp_f32_e32 v19, v8
	v_mul_f32_e32 v8, v32, v32
	v_fmamk_f32 v8, v8, 0xbdd2d3e7, v129
	v_mul_f32_e32 v8, v8, v32
	v_exp_f32_e32 v8, v8
	s_nop 0
	v_add_f32_e32 v8, 1.0, v8
	v_rcp_f32_e32 v33, v8
	v_pk_add_f32 v[8:9], v[20:21], v[22:23]
	s_nop 0
	v_pk_add_f32 v[8:9], v[14:15], v[8:9]
	v_mul_f32_e32 v15, v33, v32
	v_pk_add_f32 v[6:7], v[8:9], v[6:7]
	v_pk_add_f32 v[8:9], v[26:27], v[28:29]
	v_mul_f32_e32 v14, v15, v15
	v_pk_add_f32 v[6:7], v[6:7], v[8:9]
	v_mul_f32_e32 v9, v19, v0
	v_mul_f32_e32 v8, v9, v9
	v_pk_add_f32 v[8:9], v[8:9], v[14:15]
	v_lshlrev_b32_e32 v0, 16, v2
	v_pk_add_f32 v[6:7], v[6:7], v[8:9]
	v_mul_f32_e32 v8, v0, v0
	v_fmamk_f32 v8, v8, 0xbdd2d3e7, v129
	v_mul_f32_e32 v8, v8, v0
	v_exp_f32_e32 v8, v8
	v_and_b32_e32 v26, 0xffff0000, v5
	v_add_f32_e32 v8, 1.0, v8
	v_rcp_f32_e32 v8, v8
	s_nop 0
	v_mul_f32_e32 v9, v8, v0
	v_and_b32_e32 v0, 0xffff0000, v2
	v_mul_f32_e32 v2, v0, v0
	v_fmamk_f32 v2, v2, 0xbdd2d3e7, v129
	v_mul_f32_e32 v2, v2, v0
	v_exp_f32_e32 v2, v2
	v_mul_f32_e32 v8, v9, v9
	v_add_f32_e32 v2, 1.0, v2
	v_rcp_f32_e32 v2, v2
	s_nop 0
	v_mul_f32_e32 v15, v2, v0
	v_lshlrev_b32_e32 v0, 16, v3
	v_mul_f32_e32 v2, v0, v0
	v_fmamk_f32 v2, v2, 0xbdd2d3e7, v129
	v_mul_f32_e32 v2, v2, v0
	v_exp_f32_e32 v2, v2
	v_mul_f32_e32 v14, v15, v15
	v_add_f32_e32 v2, 1.0, v2
	v_rcp_f32_e32 v2, v2
	s_nop 0
	v_mul_f32_e32 v21, v2, v0
	v_and_b32_e32 v0, 0xffff0000, v3
	v_mul_f32_e32 v2, v0, v0
	v_fmamk_f32 v2, v2, 0xbdd2d3e7, v129
	v_mul_f32_e32 v2, v2, v0
	v_exp_f32_e32 v2, v2
	v_mul_f32_e32 v20, v21, v21
	v_add_f32_e32 v2, 1.0, v2
	v_rcp_f32_e32 v2, v2
	s_nop 0
	v_mul_f32_e32 v3, v2, v0
	v_lshlrev_b32_e32 v0, 16, v4
	v_mul_f32_e32 v19, v0, v0
	v_fmamk_f32 v19, v19, 0xbdd2d3e7, v129
	v_mul_f32_e32 v19, v19, v0
	v_exp_f32_e32 v19, v19
	v_mul_f32_e32 v2, v3, v3
	v_pk_add_f32 v[2:3], v[20:21], v[2:3]
	v_add_f32_e32 v19, 1.0, v19
	v_rcp_f32_e32 v19, v19
	s_nop 0
	v_mul_f32_e32 v23, v19, v0
	v_and_b32_e32 v0, 0xffff0000, v4
	v_mul_f32_e32 v4, v0, v0
	v_fmamk_f32 v4, v4, 0xbdd2d3e7, v129
	v_mul_f32_e32 v4, v4, v0
	v_exp_f32_e32 v4, v4
	v_mul_f32_e32 v22, v23, v23
	v_add_f32_e32 v4, 1.0, v4
	v_rcp_f32_e32 v4, v4
	s_nop 0
	v_mul_f32_e32 v25, v4, v0
	v_lshlrev_b32_e32 v0, 16, v5
	v_mul_f32_e32 v4, v0, v0
	v_fmamk_f32 v4, v4, 0xbdd2d3e7, v129
	v_mul_f32_e32 v4, v4, v0
	v_exp_f32_e32 v4, v4
	v_mul_f32_e32 v24, v25, v25
	v_add_f32_e32 v4, 1.0, v4
	v_rcp_f32_e32 v19, v4
	v_mul_f32_e32 v4, v26, v26
	v_fmamk_f32 v4, v4, 0xbdd2d3e7, v129
	v_mul_f32_e32 v4, v4, v26
	v_exp_f32_e32 v4, v4
	s_nop 0
	v_add_f32_e32 v4, 1.0, v4
	v_rcp_f32_e32 v27, v4
	v_pk_add_f32 v[4:5], v[8:9], v[14:15]
	s_nop 0
	v_pk_add_f32 v[4:5], v[6:7], v[4:5]
	v_mul_f32_e32 v7, v27, v26
	v_pk_add_f32 v[2:3], v[4:5], v[2:3]
	v_pk_add_f32 v[4:5], v[22:23], v[24:25]
	v_mul_f32_e32 v6, v7, v7
	v_pk_add_f32 v[2:3], v[2:3], v[4:5]
	v_mul_f32_e32 v5, v19, v0
	v_mul_f32_e32 v4, v5, v5
	v_pk_add_f32 v[4:5], v[4:5], v[6:7]
	s_nop 0
	v_pk_add_f32 v[24:25], v[2:3], v[4:5]
	global_load_dwordx4 v[2:5], v[16:17], off offset:1136
	global_load_dwordx4 v[6:9], v[16:17], off offset:1120
	global_load_dwordx4 v[20:23], v[16:17], off offset:1104
	s_nop 0
	global_load_dwordx4 v[14:17], v[16:17], off offset:1088
	s_waitcnt vmcnt(0)
	v_lshlrev_b32_e32 v0, 16, v14
	v_mul_f32_e32 v19, v0, v0
	v_fmamk_f32 v19, v19, 0xbdd2d3e7, v129
	v_mul_f32_e32 v19, v19, v0
	v_exp_f32_e32 v19, v19
	v_and_b32_e32 v38, 0xffff0000, v17
	v_add_f32_e32 v19, 1.0, v19
	v_rcp_f32_e32 v19, v19
	s_nop 0
	v_mul_f32_e32 v27, v19, v0
	v_and_b32_e32 v0, 0xffff0000, v14
	v_mul_f32_e32 v14, v0, v0
	v_fmamk_f32 v14, v14, 0xbdd2d3e7, v129
	v_mul_f32_e32 v14, v14, v0
	v_exp_f32_e32 v14, v14
	v_mul_f32_e32 v26, v27, v27
	v_add_f32_e32 v14, 1.0, v14
	v_rcp_f32_e32 v14, v14
	s_nop 0
	v_mul_f32_e32 v29, v14, v0
	v_lshlrev_b32_e32 v0, 16, v15
	v_mul_f32_e32 v14, v0, v0
	v_fmamk_f32 v14, v14, 0xbdd2d3e7, v129
	v_mul_f32_e32 v14, v14, v0
	v_exp_f32_e32 v14, v14
	v_mul_f32_e32 v28, v29, v29
	v_add_f32_e32 v14, 1.0, v14
	v_rcp_f32_e32 v14, v14
	s_nop 0
	v_mul_f32_e32 v33, v14, v0
	v_and_b32_e32 v0, 0xffff0000, v15
	v_mul_f32_e32 v14, v0, v0
	v_fmamk_f32 v14, v14, 0xbdd2d3e7, v129
	v_mul_f32_e32 v14, v14, v0
	v_exp_f32_e32 v14, v14
	v_mul_f32_e32 v32, v33, v33
	v_add_f32_e32 v14, 1.0, v14
	v_rcp_f32_e32 v14, v14
	s_nop 0
	v_mul_f32_e32 v15, v14, v0
	v_lshlrev_b32_e32 v0, 16, v16
	v_mul_f32_e32 v19, v0, v0
	v_fmamk_f32 v19, v19, 0xbdd2d3e7, v129
	v_mul_f32_e32 v19, v19, v0
	v_exp_f32_e32 v19, v19
	v_mul_f32_e32 v14, v15, v15
	v_pk_add_f32 v[14:15], v[32:33], v[14:15]
	v_add_f32_e32 v19, 1.0, v19
	v_rcp_f32_e32 v19, v19
	s_nop 0
	v_mul_f32_e32 v35, v19, v0
	v_and_b32_e32 v0, 0xffff0000, v16
	v_mul_f32_e32 v16, v0, v0
	v_fmamk_f32 v16, v16, 0xbdd2d3e7, v129
	v_mul_f32_e32 v16, v16, v0
	v_exp_f32_e32 v16, v16
	v_mul_f32_e32 v34, v35, v35
	v_add_f32_e32 v16, 1.0, v16
	v_rcp_f32_e32 v16, v16
	s_nop 0
	v_mul_f32_e32 v37, v16, v0
	v_lshlrev_b32_e32 v0, 16, v17
	v_mul_f32_e32 v16, v0, v0
	v_fmamk_f32 v16, v16, 0xbdd2d3e7, v129
	v_mul_f32_e32 v16, v16, v0
	v_exp_f32_e32 v16, v16
	v_mul_f32_e32 v36, v37, v37
	v_add_f32_e32 v16, 1.0, v16
	v_rcp_f32_e32 v19, v16
	v_mul_f32_e32 v16, v38, v38
	v_fmamk_f32 v16, v16, 0xbdd2d3e7, v129
	v_mul_f32_e32 v16, v16, v38
	v_exp_f32_e32 v16, v16
	s_nop 0
	v_add_f32_e32 v16, 1.0, v16
	v_rcp_f32_e32 v39, v16
	v_pk_add_f32 v[16:17], v[26:27], v[28:29]
	s_nop 0
	v_pk_add_f32 v[16:17], v[24:25], v[16:17]
	v_mul_f32_e32 v25, v39, v38
	v_pk_add_f32 v[14:15], v[16:17], v[14:15]
	v_pk_add_f32 v[16:17], v[34:35], v[36:37]
	v_mul_f32_e32 v24, v25, v25
	v_pk_add_f32 v[14:15], v[14:15], v[16:17]
	v_mul_f32_e32 v17, v19, v0
	v_mul_f32_e32 v16, v17, v17
	v_pk_add_f32 v[16:17], v[16:17], v[24:25]
	v_lshlrev_b32_e32 v0, 16, v20
	v_pk_add_f32 v[14:15], v[14:15], v[16:17]
	v_mul_f32_e32 v16, v0, v0
	v_fmamk_f32 v16, v16, 0xbdd2d3e7, v129
	v_mul_f32_e32 v16, v16, v0
	v_exp_f32_e32 v16, v16
	s_nop 0
	v_add_f32_e32 v16, 1.0, v16
	v_rcp_f32_e32 v16, v16
	s_nop 0
	v_mul_f32_e32 v17, v16, v0
	v_and_b32_e32 v0, 0xffff0000, v20
	v_mul_f32_e32 v16, v0, v0
	v_fmamk_f32 v16, v16, 0xbdd2d3e7, v129
	v_mul_f32_e32 v16, v16, v0
	v_exp_f32_e32 v16, v16
	s_nop 0
	v_add_f32_e32 v16, 1.0, v16
	v_rcp_f32_e32 v16, v16
	s_nop 0
	v_mul_f32_e32 v25, v16, v0
	v_lshlrev_b32_e32 v0, 16, v21
	v_mul_f32_e32 v19, v0, v0
	v_fmamk_f32 v19, v19, 0xbdd2d3e7, v129
	v_mul_f32_e32 v19, v19, v0
	v_exp_f32_e32 v19, v19
	v_mul_f32_e32 v16, v17, v17
	v_mul_f32_e32 v24, v25, v25
	v_pk_add_f32 v[16:17], v[16:17], v[24:25]
	v_add_f32_e32 v19, 1.0, v19
	v_rcp_f32_e32 v19, v19
	v_pk_add_f32 v[14:15], v[14:15], v[16:17]
	v_mul_f32_e32 v27, v19, v0
	v_and_b32_e32 v0, 0xffff0000, v21
	v_mul_f32_e32 v19, v0, v0
	v_fmamk_f32 v19, v19, 0xbdd2d3e7, v129
	v_mul_f32_e32 v19, v19, v0
	v_exp_f32_e32 v19, v19
	v_mul_f32_e32 v26, v27, v27
	v_add_f32_e32 v19, 1.0, v19
	v_rcp_f32_e32 v19, v19
	s_nop 0
	v_mul_f32_e32 v21, v19, v0
	v_lshlrev_b32_e32 v0, 16, v22
	v_mul_f32_e32 v19, v0, v0
	v_fmamk_f32 v19, v19, 0xbdd2d3e7, v129
	v_mul_f32_e32 v19, v19, v0
	v_exp_f32_e32 v19, v19
	v_mul_f32_e32 v20, v21, v21
	v_pk_add_f32 v[16:17], v[26:27], v[20:21]
	v_add_f32_e32 v19, 1.0, v19
	v_rcp_f32_e32 v19, v19
	v_pk_add_f32 v[14:15], v[14:15], v[16:17]
	v_mul_f32_e32 v29, v19, v0
	v_and_b32_e32 v0, 0xffff0000, v22
	v_mul_f32_e32 v19, v0, v0
	v_fmamk_f32 v19, v19, 0xbdd2d3e7, v129
	v_mul_f32_e32 v19, v19, v0
	v_exp_f32_e32 v19, v19
	v_and_b32_e32 v22, 0xffff0000, v23
	v_mul_f32_e32 v28, v29, v29
	v_add_f32_e32 v19, 1.0, v19
	v_rcp_f32_e32 v19, v19
	s_nop 0
	v_mul_f32_e32 v33, v19, v0
	v_lshlrev_b32_e32 v0, 16, v23
	v_mul_f32_e32 v19, v0, v0
	v_mul_f32_e32 v23, v22, v22
	v_fmamk_f32 v19, v19, 0xbdd2d3e7, v129
	v_fmamk_f32 v23, v23, 0xbdd2d3e7, v129
	v_mul_f32_e32 v19, v19, v0
	v_mul_f32_e32 v23, v23, v22
	v_exp_f32_e32 v19, v19
	v_exp_f32_e32 v23, v23
	v_mul_f32_e32 v32, v33, v33
	v_pk_add_f32 v[16:17], v[28:29], v[32:33]
	v_add_f32_e32 v19, 1.0, v19
	v_add_f32_e32 v23, 1.0, v23
	v_rcp_f32_e32 v19, v19
	v_rcp_f32_e32 v23, v23
	v_pk_add_f32 v[14:15], v[14:15], v[16:17]
	v_and_b32_e32 v28, 0xffff0000, v9
	v_mul_f32_e32 v17, v19, v0
	v_mul_f32_e32 v21, v23, v22
	v_mul_f32_e32 v16, v17, v17
	v_mul_f32_e32 v20, v21, v21
	v_pk_add_f32 v[16:17], v[16:17], v[20:21]
	v_lshlrev_b32_e32 v0, 16, v6
	v_pk_add_f32 v[14:15], v[14:15], v[16:17]
	v_mul_f32_e32 v16, v0, v0
	v_fmamk_f32 v16, v16, 0xbdd2d3e7, v129
	v_mul_f32_e32 v16, v16, v0
	v_exp_f32_e32 v16, v16
	s_nop 0
	v_add_f32_e32 v16, 1.0, v16
	v_rcp_f32_e32 v16, v16
	s_nop 0
	v_mul_f32_e32 v17, v16, v0
	v_and_b32_e32 v0, 0xffff0000, v6
	v_mul_f32_e32 v6, v0, v0
	v_fmamk_f32 v6, v6, 0xbdd2d3e7, v129
	v_mul_f32_e32 v6, v6, v0
	v_exp_f32_e32 v6, v6
	v_mul_f32_e32 v16, v17, v17
	v_add_f32_e32 v6, 1.0, v6
	v_rcp_f32_e32 v6, v6
	s_nop 0
	v_mul_f32_e32 v21, v6, v0
	v_lshlrev_b32_e32 v0, 16, v7
	v_mul_f32_e32 v6, v0, v0
	v_fmamk_f32 v6, v6, 0xbdd2d3e7, v129
	v_mul_f32_e32 v6, v6, v0
	v_exp_f32_e32 v6, v6
	v_mul_f32_e32 v20, v21, v21
	v_add_f32_e32 v6, 1.0, v6
	v_rcp_f32_e32 v6, v6
	s_nop 0
	v_mul_f32_e32 v23, v6, v0
	v_and_b32_e32 v0, 0xffff0000, v7
	v_mul_f32_e32 v6, v0, v0
	v_fmamk_f32 v6, v6, 0xbdd2d3e7, v129
	v_mul_f32_e32 v6, v6, v0
	v_exp_f32_e32 v6, v6
	v_mul_f32_e32 v22, v23, v23
	v_add_f32_e32 v6, 1.0, v6
	v_rcp_f32_e32 v6, v6
	s_nop 0
	v_mul_f32_e32 v7, v6, v0
	v_lshlrev_b32_e32 v0, 16, v8
	v_mul_f32_e32 v19, v0, v0
	v_fmamk_f32 v19, v19, 0xbdd2d3e7, v129
	v_mul_f32_e32 v19, v19, v0
	v_exp_f32_e32 v19, v19
	v_mul_f32_e32 v6, v7, v7
	v_pk_add_f32 v[6:7], v[22:23], v[6:7]
	v_add_f32_e32 v19, 1.0, v19
	v_rcp_f32_e32 v19, v19
	s_nop 0
	v_mul_f32_e32 v25, v19, v0
	v_and_b32_e32 v0, 0xffff0000, v8
	v_mul_f32_e32 v8, v0, v0
	v_fmamk_f32 v8, v8, 0xbdd2d3e7, v129
	v_mul_f32_e32 v8, v8, v0
	v_exp_f32_e32 v8, v8
	v_mul_f32_e32 v24, v25, v25
	v_add_f32_e32 v8, 1.0, v8
	v_rcp_f32_e32 v8, v8
	s_nop 0
	v_mul_f32_e32 v27, v8, v0
	v_lshlrev_b32_e32 v0, 16, v9
	v_mul_f32_e32 v8, v0, v0
	v_fmamk_f32 v8, v8, 0xbdd2d3e7, v129
	v_mul_f32_e32 v8, v8, v0
	v_exp_f32_e32 v8, v8
	v_mul_f32_e32 v26, v27, v27
	v_add_f32_e32 v8, 1.0, v8
	v_rcp_f32_e32 v19, v8
	v_mul_f32_e32 v8, v28, v28
	v_fmamk_f32 v8, v8, 0xbdd2d3e7, v129
	v_mul_f32_e32 v8, v8, v28
	v_exp_f32_e32 v8, v8
	s_nop 0
	v_add_f32_e32 v8, 1.0, v8
	v_rcp_f32_e32 v29, v8
	v_pk_add_f32 v[8:9], v[16:17], v[20:21]
	s_nop 0
	v_pk_add_f32 v[8:9], v[14:15], v[8:9]
	v_mul_f32_e32 v15, v29, v28
	v_pk_add_f32 v[6:7], v[8:9], v[6:7]
	v_pk_add_f32 v[8:9], v[24:25], v[26:27]
	v_mul_f32_e32 v14, v15, v15
	v_pk_add_f32 v[6:7], v[6:7], v[8:9]
	v_mul_f32_e32 v9, v19, v0
	v_mul_f32_e32 v8, v9, v9
	v_pk_add_f32 v[8:9], v[8:9], v[14:15]
	v_lshlrev_b32_e32 v0, 16, v2
	v_pk_add_f32 v[6:7], v[6:7], v[8:9]
	v_mul_f32_e32 v8, v0, v0
	v_fmamk_f32 v8, v8, 0xbdd2d3e7, v129
	v_mul_f32_e32 v8, v8, v0
	v_exp_f32_e32 v8, v8
	v_and_b32_e32 v24, 0xffff0000, v5
	v_add_f32_e32 v8, 1.0, v8
	v_rcp_f32_e32 v8, v8
	s_nop 0
	v_mul_f32_e32 v9, v8, v0
	v_and_b32_e32 v0, 0xffff0000, v2
	v_mul_f32_e32 v2, v0, v0
	v_fmamk_f32 v2, v2, 0xbdd2d3e7, v129
	v_mul_f32_e32 v2, v2, v0
	v_exp_f32_e32 v2, v2
	v_mul_f32_e32 v8, v9, v9
	v_add_f32_e32 v2, 1.0, v2
	v_rcp_f32_e32 v2, v2
	s_nop 0
	v_mul_f32_e32 v15, v2, v0
	v_lshlrev_b32_e32 v0, 16, v3
	v_mul_f32_e32 v2, v0, v0
	v_fmamk_f32 v2, v2, 0xbdd2d3e7, v129
	v_mul_f32_e32 v2, v2, v0
	v_exp_f32_e32 v2, v2
	v_mul_f32_e32 v14, v15, v15
	v_add_f32_e32 v2, 1.0, v2
	v_rcp_f32_e32 v2, v2
	s_nop 0
	v_mul_f32_e32 v17, v2, v0
	v_and_b32_e32 v0, 0xffff0000, v3
	v_mul_f32_e32 v2, v0, v0
	v_fmamk_f32 v2, v2, 0xbdd2d3e7, v129
	v_mul_f32_e32 v2, v2, v0
	v_exp_f32_e32 v2, v2
	v_mul_f32_e32 v16, v17, v17
	v_add_f32_e32 v2, 1.0, v2
	v_rcp_f32_e32 v2, v2
	s_nop 0
	v_mul_f32_e32 v3, v2, v0
	v_lshlrev_b32_e32 v0, 16, v4
	v_mul_f32_e32 v19, v0, v0
	v_fmamk_f32 v19, v19, 0xbdd2d3e7, v129
	v_mul_f32_e32 v19, v19, v0
	v_exp_f32_e32 v19, v19
	v_mul_f32_e32 v2, v3, v3
	v_pk_add_f32 v[2:3], v[16:17], v[2:3]
	v_add_f32_e32 v19, 1.0, v19
	v_rcp_f32_e32 v19, v19
	s_nop 0
	v_mul_f32_e32 v21, v19, v0
	v_and_b32_e32 v0, 0xffff0000, v4
	v_mul_f32_e32 v4, v0, v0
	v_fmamk_f32 v4, v4, 0xbdd2d3e7, v129
	v_mul_f32_e32 v4, v4, v0
	v_exp_f32_e32 v4, v4
	v_mul_f32_e32 v20, v21, v21
	v_add_f32_e32 v4, 1.0, v4
	v_rcp_f32_e32 v4, v4
	s_nop 0
	v_mul_f32_e32 v23, v4, v0
	v_lshlrev_b32_e32 v0, 16, v5
	v_mul_f32_e32 v4, v0, v0
	v_fmamk_f32 v4, v4, 0xbdd2d3e7, v129
	v_mul_f32_e32 v4, v4, v0
	v_exp_f32_e32 v4, v4
	v_mul_f32_e32 v22, v23, v23
	v_add_f32_e32 v4, 1.0, v4
	v_rcp_f32_e32 v19, v4
	v_mul_f32_e32 v4, v24, v24
	v_fmamk_f32 v4, v4, 0xbdd2d3e7, v129
	v_mul_f32_e32 v4, v4, v24
	v_exp_f32_e32 v4, v4
	s_nop 0
	v_add_f32_e32 v4, 1.0, v4
	v_rcp_f32_e32 v25, v4
	v_pk_add_f32 v[4:5], v[8:9], v[14:15]
	s_nop 0
	v_pk_add_f32 v[4:5], v[6:7], v[4:5]
	v_mul_f32_e32 v7, v25, v24
	v_pk_add_f32 v[2:3], v[4:5], v[2:3]
	v_pk_add_f32 v[4:5], v[20:21], v[22:23]
	v_mul_f32_e32 v6, v7, v7
	v_pk_add_f32 v[2:3], v[2:3], v[4:5]
	v_mul_f32_e32 v5, v19, v0
	v_mul_f32_e32 v4, v5, v5
	v_pk_add_f32 v[4:5], v[4:5], v[6:7]
	s_nop 0
	v_pk_add_f32 v[14:15], v[2:3], v[4:5]
	s_cbranch_scc1 .LBB0_621
	v_and_b32_e32 v171, 0xff, v194
	v_lshlrev_b32_e32 v171, 3, v171
	s_mul_i32 s66, s64, 0x12000
	s_add_i32 s66, s66, 0x11000
	s_xor_b32 s67, s64, 1
	s_mul_i32 s67, s67, 0x12000
	s_add_i32 s67, s67, 0x11000
	v_add_u32_e32 v172, s66, v171
	v_add_u32_e32 v173, s67, v171
	ds_write_b64 v172, v[14:15]
	s_waitcnt lgkmcnt(0)
	s_barrier
	ds_read_b64 v[174:175], v173
	s_waitcnt lgkmcnt(0)
	v_add_f32_e32 v14, v14, v174
	v_add_f32_e32 v15, v15, v175
	v_readlane_b32 s0, v254, 51
	s_lshl_b32 s88, s0, 9
	v_readlane_b32 s40, v251, 6
	s_lshl_b64 s[6:7], s[88:89], 2
	v_readlane_b32 s52, v251, 18
	v_readlane_b32 s53, v251, 19
	s_add_u32 s1, s52, s6
	s_addc_u32 s2, s53, s7
	s_lshl_b32 s0, s10, 7
	s_and_b32 s0, s0, 0x180
	s_lshl_b32 s5, s0, 2
	s_add_u32 s16, s1, s5
	v_readlane_b32 s54, v251, 20
	s_addc_u32 s17, s2, 0
	v_readlane_b32 s55, v251, 21
	s_add_u32 s1, s54, s6
	s_addc_u32 s2, s55, s7
	s_add_u32 s20, s1, s5
	s_addc_u32 s21, s2, 0
	s_lshl_b32 s8, s0, 1
	s_mov_b32 s9, s89
	v_lshl_add_u64 v[2:3], v[10:11], 0, s[8:9]
	v_lshlrev_b32_e32 v0, 7, v18
	v_lshl_add_u64 v[22:23], v[2:3], 0, v[0:1]
	global_load_dwordx4 v[10:13], v[22:23], off offset:1024
	v_lshlrev_b32_e32 v20, 8, v18
	global_load_dwordx2 v[28:29], v20, s[16:17]
	global_load_dwordx2 v[36:37], v20, s[20:21]
	global_load_dwordx2 v[40:41], v20, s[16:17] offset:16
	global_load_dwordx2 v[42:43], v20, s[16:17] offset:32
	global_load_dwordx2 v[24:25], v20, s[16:17] offset:48
	global_load_dwordx2 v[44:45], v20, s[20:21] offset:16
	global_load_dwordx2 v[46:47], v20, s[20:21] offset:32
	global_load_dwordx2 v[26:27], v20, s[20:21] offset:48
	v_xor_b32_e32 v2, 1, v234
	v_cmp_lt_i32_e32 vcc, v2, v235
	s_mov_b32 s2, 0x3b000000
	v_lshlrev_b32_e32 v34, 6, v18
	v_cndmask_b32_e32 v2, v234, v2, vcc
	v_lshlrev_b32_e32 v80, 2, v2
	ds_bpermute_b32 v3, v80, v15
	ds_bpermute_b32 v2, v80, v14
	v_mul_u32_u24_e32 v4, 0x4400, v18
	v_lshlrev_b32_e32 v33, 1, v31
	s_mov_b32 s11, 0x800000
	v_add3_u32 v38, s15, v4, v33
	s_waitcnt lgkmcnt(0)
	v_pk_add_f32 v[2:3], v[14:15], v[2:3]
	v_or_b32_e32 v4, 1, v34
	v_pk_mul_f32 v[18:19], v[2:3], s[2:3] op_sel_hi:[1,0]
	v_mul_u32_u24_e32 v4, 0x110, v4
	v_fma_f32 v2, -v19, v19, v18
	v_max_f32_e32 v2, 0, v2
	v_add_f32_e32 v2, 0x358637bd, v2
	v_mul_f32_e32 v3, 0x4b800000, v2
	v_cmp_gt_f32_e32 vcc, s11, v2
	v_add3_u32 v35, s15, v4, v33
	v_or_b32_e32 v78, 7, v34
	v_cndmask_b32_e32 v2, v2, v3, vcc
	v_rsq_f32_e32 v18, v2
	global_load_dwordx4 v[14:17], v[22:23], off offset:1040
	global_load_dwordx4 v[2:5], v[22:23], off offset:1072
	global_load_dwordx4 v[6:9], v[22:23], off offset:1056
	v_or_b32_e32 v81, 10, v34
	v_or_b32_e32 v79, 11, v34
	v_mul_f32_e32 v39, 0x45800000, v18
	v_cndmask_b32_e32 v39, v18, v39, vcc
	v_readlane_b32 s41, v251, 7
	v_readlane_b32 s42, v251, 8
	v_readlane_b32 s43, v251, 9
	v_readlane_b32 s44, v251, 10
	v_readlane_b32 s45, v251, 11
	v_readlane_b32 s46, v251, 12
	v_readlane_b32 s47, v251, 13
	v_readlane_b32 s48, v251, 14
	v_readlane_b32 s49, v251, 15
	v_readlane_b32 s50, v251, 16
	v_readlane_b32 s51, v251, 17
	s_or_b32 s88, s0, s88
	v_readlane_b32 s40, v251, 22
	v_readlane_b32 s41, v251, 23
	v_mov_b32_e32 v21, v1
	v_mul_u32_u24_e32 v84, 0x110, v31
	v_add3_u32 v0, s15, v84, v0
	v_or_b32_e32 v101, 31, v34
	v_cmp_gt_u32_e32 vcc, v31, v34
	v_or_b32_e32 v57, 48, v34
	v_and_b32_e32 v32, 15, v50
	v_readlane_b32 s44, v251, 26
	v_readlane_b32 s45, v251, 27
	v_readlane_b32 s46, v251, 28
	v_readlane_b32 s47, v251, 29
	v_readlane_b32 s48, v251, 30
	v_readlane_b32 s49, v251, 31
	v_readlane_b32 s50, v251, 32
	v_readlane_b32 s51, v251, 33
	v_readlane_b32 s52, v251, 34
	v_readlane_b32 s53, v251, 35
	v_readlane_b32 s54, v251, 36
	v_readlane_b32 s55, v251, 37
	v_readlane_b32 s44, v251, 54
	v_readlane_b32 s50, v251, 60
	v_readlane_b32 s51, v251, 61
	s_add_u32 s6, s50, s8
	s_addc_u32 s7, s51, 0
	v_readlane_b32 s42, v251, 24
	v_readlane_b32 s43, v251, 25
	v_readlane_b32 s52, v251, 62
	v_readlane_b32 s53, v251, 63
	v_readlane_b32 s54, v252, 0
	v_readlane_b32 s55, v252, 1
	v_readlane_b32 s45, v251, 55
	s_waitcnt vmcnt(11)
	v_lshlrev_b32_e32 v48, 16, v11
	v_and_b32_e32 v11, 0xffff0000, v11
	v_mul_f32_e32 v54, v11, v11
	v_fmamk_f32 v54, v54, 0xbdd2d3e7, v129
	v_mul_f32_e32 v54, v54, v11
	v_lshlrev_b32_e32 v18, 16, v10
	v_and_b32_e32 v10, 0xffff0000, v10
	v_mul_f32_e32 v51, v18, v18
	v_mul_f32_e32 v52, v10, v10
	v_fmamk_f32 v51, v51, 0xbdd2d3e7, v129
	v_exp_f32_e32 v54, v54
	v_fmamk_f32 v52, v52, 0xbdd2d3e7, v129
	v_mul_f32_e32 v51, v51, v18
	v_mul_f32_e32 v52, v52, v10
	v_exp_f32_e32 v51, v51
	v_add_f32_e32 v54, 1.0, v54
	v_exp_f32_e32 v52, v52
	v_rcp_f32_e32 v54, v54
	v_lshlrev_b32_e32 v49, 16, v12
	v_mul_f32_e32 v55, v49, v49
	v_fmamk_f32 v55, v55, 0xbdd2d3e7, v129
	v_add_f32_e32 v51, 1.0, v51
	v_mul_f32_e32 v55, v55, v49
	v_add_f32_e32 v52, 1.0, v52
	v_rcp_f32_e32 v51, v51
	v_fma_f32 v11, v54, v11, -v19
	v_rcp_f32_e32 v52, v52
	v_mul_f32_e32 v59, v39, v11
	v_and_b32_e32 v11, 0xffff0000, v12
	v_mul_f32_e32 v12, v11, v11
	v_exp_f32_e32 v55, v55
	v_fmamk_f32 v12, v12, 0xbdd2d3e7, v129
	v_fma_f32 v18, v51, v18, -v19
	v_mul_f32_e32 v12, v12, v11
	v_fma_f32 v10, v52, v10, -v19
	v_mul_f32_e32 v18, v39, v18
	v_mul_f32_e32 v10, v39, v10
	s_waitcnt vmcnt(9)
	v_fma_f32 v18, v28, v18, v36
	v_lshlrev_b32_e32 v28, 16, v13
	v_add_f32_e32 v55, 1.0, v55
	v_fmac_f32_e32 v37, v29, v10
	v_exp_f32_e32 v12, v12
	v_mul_f32_e32 v29, v28, v28
	v_rcp_f32_e32 v55, v55
	v_fmamk_f32 v29, v29, 0xbdd2d3e7, v129
	v_mul_f32_e32 v29, v29, v28
	v_cvt_pk_bf16_f32 v10, v18, s0
	v_add_f32_e32 v12, 1.0, v12
	v_cvt_pk_bf16_f32 v18, v37, s0
	ds_write_b16 v38, v10 offset:34816
	ds_write_b16 v35, v18 offset:34816
	v_fma_f32 v10, v55, v49, -v19
	v_rcp_f32_e32 v12, v12
	v_exp_f32_e32 v29, v29
	v_mul_f32_e32 v10, v39, v10
	s_waitcnt vmcnt(5)
	v_fma_f32 v10, v40, v10, v44
	v_cvt_pk_bf16_f32 v10, v10, s0
	ds_write_b16 v35, v10 offset:35632
	v_fma_f32 v10, v12, v11, -v19
	v_add_f32_e32 v11, 1.0, v29
	v_rcp_f32_e32 v11, v11
	v_mul_f32_e32 v10, v39, v10
	v_fmac_f32_e32 v45, v10, v41
	v_cvt_pk_bf16_f32 v10, v45, s0
	ds_write_b16 v35, v10 offset:35904
	v_fma_f32 v10, v11, v28, -v19
	v_and_b32_e32 v11, 0xffff0000, v13
	v_mul_f32_e32 v12, v11, v11
	v_fmamk_f32 v12, v12, 0xbdd2d3e7, v129
	v_mul_f32_e32 v12, v12, v11
	v_exp_f32_e32 v12, v12
	s_waitcnt vmcnt(2)
	v_lshlrev_b32_e32 v13, 16, v14
	v_mul_f32_e32 v28, v13, v13
	v_fmamk_f32 v28, v28, 0xbdd2d3e7, v129
	v_add_f32_e32 v12, 1.0, v12
	v_rcp_f32_e32 v12, v12
	v_mul_f32_e32 v28, v28, v13
	v_fma_f32 v11, v12, v11, -v19
	v_exp_f32_e32 v28, v28
	v_mul_f32_e32 v44, v39, v11
	v_and_b32_e32 v11, 0xffff0000, v14
	v_mul_f32_e32 v12, v11, v11
	v_fmamk_f32 v12, v12, 0xbdd2d3e7, v129
	v_mul_f32_e32 v12, v12, v11
	v_mul_f32_e32 v45, v39, v10
	v_add_f32_e32 v10, 1.0, v28
	v_rcp_f32_e32 v10, v10
	v_exp_f32_e32 v12, v12
	v_lshlrev_b32_e32 v29, 16, v16
	v_fma_f32 v10, v10, v13, -v19
	v_lshlrev_b32_e32 v13, 16, v15
	v_add_f32_e32 v12, 1.0, v12
	v_mul_f32_e32 v14, v13, v13
	v_rcp_f32_e32 v12, v12
	v_fmamk_f32 v14, v14, 0xbdd2d3e7, v129
	v_mul_f32_e32 v10, v39, v10
	v_mul_f32_e32 v14, v14, v13
	v_fma_f32 v10, v42, v10, v46
	v_cvt_pk_bf16_f32 v10, v10, s0
	v_exp_f32_e32 v14, v14
	ds_write_b16 v35, v10 offset:36720
	v_fma_f32 v10, v12, v11, -v19
	v_mul_f32_e32 v10, v39, v10
	v_fmac_f32_e32 v47, v43, v10
	v_cvt_pk_bf16_f32 v10, v47, s0
	v_and_b32_e32 v15, 0xffff0000, v15
	v_add_f32_e32 v11, 1.0, v14
	ds_write_b16 v35, v10 offset:36992
	v_mul_f32_e32 v10, v15, v15
	v_rcp_f32_e32 v11, v11
	v_fmamk_f32 v10, v10, 0xbdd2d3e7, v129
	v_mul_f32_e32 v10, v10, v15
	v_fma_f32 v14, v11, v13, -v19
	v_exp_f32_e32 v28, v10
	global_load_dwordx2 v[10:11], v20, s[16:17] offset:64
	global_load_dwordx2 v[12:13], v20, s[20:21] offset:64
	v_mul_f32_e32 v37, v29, v29
	v_fmamk_f32 v37, v37, 0xbdd2d3e7, v129
	v_add_f32_e32 v28, 1.0, v28
	v_mul_f32_e32 v37, v37, v29
	v_rcp_f32_e32 v28, v28
	v_exp_f32_e32 v37, v37
	v_fma_f32 v15, v28, v15, -v19
	v_mul_f32_e32 v46, v39, v15
	v_and_b32_e32 v15, 0xffff0000, v16
	v_mul_f32_e32 v16, v15, v15
	v_mul_f32_e32 v47, v39, v14
	v_add_f32_e32 v14, 1.0, v37
	v_fmamk_f32 v16, v16, 0xbdd2d3e7, v129
	v_rcp_f32_e32 v14, v14
	v_mul_f32_e32 v16, v16, v15
	v_exp_f32_e32 v16, v16
	v_fma_f32 v14, v14, v29, -v19
	v_mul_f32_e32 v14, v39, v14
	v_fma_f32 v14, v24, v14, v26
	v_lshlrev_b32_e32 v24, 16, v17
	v_add_f32_e32 v16, 1.0, v16
	v_mul_f32_e32 v26, v24, v24
	v_rcp_f32_e32 v16, v16
	v_fmamk_f32 v26, v26, 0xbdd2d3e7, v129
	v_mul_f32_e32 v26, v26, v24
	v_cvt_pk_bf16_f32 v14, v14, s0
	v_exp_f32_e32 v26, v26
	ds_write_b16 v35, v14 offset:37808
	v_fma_f32 v14, v16, v15, -v19
	v_mul_f32_e32 v14, v39, v14
	v_fmac_f32_e32 v27, v14, v25
	v_cvt_pk_bf16_f32 v14, v27, s0
	v_and_b32_e32 v25, 0xffff0000, v17
	v_add_f32_e32 v15, 1.0, v26
	ds_write_b16 v35, v14 offset:38080
	v_mul_f32_e32 v14, v25, v25
	v_rcp_f32_e32 v15, v15
	v_fmamk_f32 v14, v14, 0xbdd2d3e7, v129
	v_mul_f32_e32 v14, v14, v25
	v_fma_f32 v24, v15, v24, -v19
	v_exp_f32_e32 v26, v14
	global_load_dwordx2 v[14:15], v20, s[16:17] offset:80
	global_load_dwordx2 v[16:17], v20, s[20:21] offset:80
	s_waitcnt vmcnt(4)
	v_lshlrev_b32_e32 v27, 16, v6
	v_mul_f32_e32 v28, v27, v27
	v_fmamk_f32 v28, v28, 0xbdd2d3e7, v129
	v_mul_f32_e32 v28, v28, v27
	v_exp_f32_e32 v28, v28
	v_mul_f32_e32 v55, v39, v24
	v_mul_f32_e32 v53, v48, v48
	v_fmamk_f32 v53, v53, 0xbdd2d3e7, v129
	v_add_f32_e32 v24, 1.0, v28
	v_rcp_f32_e32 v24, v24
	v_and_b32_e32 v6, 0xffff0000, v6
	v_mul_f32_e32 v53, v53, v48
	v_fma_f32 v24, v24, v27, -v19
	v_mul_f32_e32 v40, v39, v24
	v_mul_f32_e32 v24, v6, v6
	v_fmamk_f32 v24, v24, 0xbdd2d3e7, v129
	v_mul_f32_e32 v24, v24, v6
	v_exp_f32_e32 v53, v53
	v_exp_f32_e32 v41, v24
	v_add_f32_e32 v53, 1.0, v53
	v_add_f32_e32 v26, 1.0, v26
	v_rcp_f32_e32 v53, v53
	v_rcp_f32_e32 v26, v26
	s_waitcnt vmcnt(2)
	v_fma_f32 v10, v10, v40, v12
	v_lshlrev_b32_e32 v40, 16, v7
	v_add_f32_e32 v12, 1.0, v41
	v_mul_f32_e32 v41, v40, v40
	v_fmamk_f32 v41, v41, 0xbdd2d3e7, v129
	v_mul_f32_e32 v41, v41, v40
	v_fma_f32 v48, v53, v48, -v19
	v_fma_f32 v25, v26, v25, -v19
	v_mul_f32_e32 v65, v39, v48
	v_mul_f32_e32 v54, v39, v25
	global_load_dwordx2 v[24:25], v20, s[16:17] offset:96
	global_load_dwordx2 v[28:29], v20, s[16:17] offset:112
	global_load_dwordx2 v[26:27], v20, s[20:21] offset:96
	global_load_dwordx2 v[48:49], v20, s[20:21] offset:112
	v_exp_f32_e32 v41, v41
	v_rcp_f32_e32 v12, v12
	v_cvt_pk_bf16_f32 v10, v10, s0
	ds_write_b16 v35, v10 offset:38896
	v_add_f32_e32 v10, 1.0, v41
	v_fma_f32 v6, v12, v6, -v19
	v_rcp_f32_e32 v10, v10
	v_mul_f32_e32 v6, v39, v6
	v_fmac_f32_e32 v13, v11, v6
	v_cvt_pk_bf16_f32 v6, v13, s0
	v_and_b32_e32 v7, 0xffff0000, v7
	ds_write_b16 v35, v6 offset:39168
	v_fma_f32 v6, v10, v40, -v19
	v_mul_f32_e32 v10, v7, v7
	v_fmamk_f32 v10, v10, 0xbdd2d3e7, v129
	v_mul_f32_e32 v10, v10, v7
	v_exp_f32_e32 v10, v10
	v_lshlrev_b32_e32 v11, 16, v8
	v_mul_f32_e32 v12, v11, v11
	v_fmamk_f32 v12, v12, 0xbdd2d3e7, v129
	v_mul_f32_e32 v12, v12, v11
	v_add_f32_e32 v10, 1.0, v10
	v_rcp_f32_e32 v10, v10
	v_exp_f32_e32 v12, v12
	v_mul_f32_e32 v53, v39, v6
	v_fma_f32 v7, v10, v7, -v19
	v_mul_f32_e32 v52, v39, v7
	v_and_b32_e32 v7, 0xffff0000, v8
	v_add_f32_e32 v6, 1.0, v12
	v_mul_f32_e32 v8, v7, v7
	v_rcp_f32_e32 v6, v6
	v_fmamk_f32 v8, v8, 0xbdd2d3e7, v129
	v_mul_f32_e32 v8, v8, v7
	v_lshlrev_b32_e32 v10, 16, v9
	v_fma_f32 v6, v6, v11, -v19
	v_exp_f32_e32 v8, v8
	v_mul_f32_e32 v11, v10, v10
	v_fmamk_f32 v11, v11, 0xbdd2d3e7, v129
	v_mul_f32_e32 v11, v11, v10
	v_add_f32_e32 v8, 1.0, v8
	v_rcp_f32_e32 v8, v8
	v_exp_f32_e32 v11, v11
	v_mul_f32_e32 v6, v39, v6
	s_waitcnt vmcnt(4)
	v_fma_f32 v6, v14, v6, v16
	v_cvt_pk_bf16_f32 v6, v6, s0
	ds_write_b16 v35, v6 offset:39984
	v_fma_f32 v6, v8, v7, -v19
	v_add_f32_e32 v7, 1.0, v11
	v_rcp_f32_e32 v7, v7
	v_mul_f32_e32 v6, v39, v6
	v_fmac_f32_e32 v17, v6, v15
	v_cvt_pk_bf16_f32 v6, v17, s0
	ds_write_b16 v35, v6 offset:40256
	v_fma_f32 v6, v7, v10, -v19
	v_and_b32_e32 v7, 0xffff0000, v9
	v_lshlrev_b32_e32 v9, 16, v2
	v_mul_f32_e32 v10, v9, v9
	v_fmamk_f32 v10, v10, 0xbdd2d3e7, v129
	v_mul_f32_e32 v8, v7, v7
	v_mul_f32_e32 v10, v10, v9
	v_fmamk_f32 v8, v8, 0xbdd2d3e7, v129
	v_mul_f32_e32 v8, v8, v7
	v_exp_f32_e32 v10, v10
	v_exp_f32_e32 v8, v8
	v_mul_f32_e32 v58, v39, v6
	v_add_f32_e32 v6, 1.0, v10
	global_load_dwordx4 v[10:13], v[22:23], off offset:1104
	global_load_dwordx4 v[14:17], v[22:23], off offset:1088
	v_add_f32_e32 v8, 1.0, v8
	v_rcp_f32_e32 v8, v8
	v_and_b32_e32 v2, 0xffff0000, v2
	v_rcp_f32_e32 v6, v6
	v_or_b32_e32 v18, 4, v34
	v_fma_f32 v7, v8, v7, -v19
	v_mul_f32_e32 v56, v39, v7
	v_mul_f32_e32 v7, v2, v2
	v_fmamk_f32 v7, v7, 0xbdd2d3e7, v129
	v_mul_f32_e32 v7, v7, v2
	v_exp_f32_e32 v7, v7
	v_lshlrev_b32_e32 v8, 16, v3
	v_fma_f32 v6, v6, v9, -v19
	v_mul_f32_e32 v9, v8, v8
	v_add_f32_e32 v7, 1.0, v7
	v_rcp_f32_e32 v7, v7
	v_fmamk_f32 v9, v9, 0xbdd2d3e7, v129
	v_mul_f32_e32 v9, v9, v8
	v_fma_f32 v2, v7, v2, -v19
	v_mul_f32_e32 v6, v39, v6
	v_mul_f32_e32 v2, v39, v2
	s_waitcnt vmcnt(3)
	v_fma_f32 v6, v24, v6, v26
	v_exp_f32_e32 v9, v9
	v_fmac_f32_e32 v27, v25, v2
	v_cvt_pk_bf16_f32 v6, v6, s0
	v_cvt_pk_bf16_f32 v2, v27, s0
	ds_write_b16 v35, v6 offset:41072
	ds_write_b16 v35, v2 offset:41344
	global_load_dwordx2 v[24:25], v20, s[16:17] offset:128
	global_load_dwordx2 v[26:27], v20, s[20:21] offset:128
	v_add_f32_e32 v6, 1.0, v9
	v_rcp_f32_e32 v6, v6
	v_and_b32_e32 v3, 0xffff0000, v3
	v_lshlrev_b32_e32 v7, 16, v4
	v_or_b32_e32 v36, 8, v34
	v_fma_f32 v2, v6, v8, -v19
	v_mul_f32_e32 v6, v3, v3
	v_fmamk_f32 v6, v6, 0xbdd2d3e7, v129
	v_mul_f32_e32 v6, v6, v3
	v_exp_f32_e32 v6, v6
	v_mul_f32_e32 v8, v7, v7
	v_fmamk_f32 v8, v8, 0xbdd2d3e7, v129
	v_mul_f32_e32 v8, v8, v7
	v_add_f32_e32 v6, 1.0, v6
	v_rcp_f32_e32 v6, v6
	v_exp_f32_e32 v8, v8
	v_mul_f32_e32 v64, v39, v2
	v_fma_f32 v3, v6, v3, -v19
	v_mul_f32_e32 v63, v39, v3
	v_and_b32_e32 v3, 0xffff0000, v4
	v_add_f32_e32 v2, 1.0, v8
	v_mul_f32_e32 v4, v3, v3
	v_rcp_f32_e32 v2, v2
	v_fmamk_f32 v4, v4, 0xbdd2d3e7, v129
	v_mul_f32_e32 v4, v4, v3
	v_fma_f32 v2, v2, v7, -v19
	v_exp_f32_e32 v4, v4
	v_mul_f32_e32 v2, v39, v2
	s_waitcnt vmcnt(4)
	v_fma_f32 v2, v28, v2, v48
	v_cvt_pk_bf16_f32 v2, v2, s0
	ds_write_b16 v35, v2 offset:42160
	v_add_f32_e32 v2, 1.0, v4
	v_lshlrev_b32_e32 v4, 16, v5
	v_mul_f32_e32 v6, v4, v4
	v_fmamk_f32 v6, v6, 0xbdd2d3e7, v129
	v_rcp_f32_e32 v2, v2
	v_mul_f32_e32 v6, v6, v4
	v_exp_f32_e32 v6, v6
	v_fma_f32 v2, v2, v3, -v19
	v_mul_f32_e32 v2, v39, v2
	v_fmac_f32_e32 v49, v2, v29
	v_add_f32_e32 v2, 1.0, v6
	v_cvt_pk_bf16_f32 v6, v49, s0
	ds_write_b16 v35, v6 offset:42432
	global_load_dwordx2 v[60:61], v20, s[16:17] offset:144
	global_load_dwordx2 v[66:67], v20, s[20:21] offset:144
	v_and_b32_e32 v3, 0xffff0000, v5
	v_mul_f32_e32 v5, v3, v3
	v_fmamk_f32 v5, v5, 0xbdd2d3e7, v129
	v_mul_f32_e32 v5, v5, v3
	v_rcp_f32_e32 v2, v2
	v_exp_f32_e32 v5, v5
	s_waitcnt vmcnt(4)
	v_lshlrev_b32_e32 v28, 16, v14
	v_and_b32_e32 v14, 0xffff0000, v14
	v_fma_f32 v2, v2, v4, -v19
	v_add_f32_e32 v4, 1.0, v5
	v_mul_f32_e32 v5, v28, v28
	v_fmamk_f32 v5, v5, 0xbdd2d3e7, v129
	v_mul_f32_e32 v5, v5, v28
	v_rcp_f32_e32 v4, v4
	v_exp_f32_e32 v5, v5
	v_mul_f32_e32 v69, v39, v2
	v_fma_f32 v2, v4, v3, -v19
	v_mul_f32_e32 v68, v39, v2
	v_add_f32_e32 v2, 1.0, v5
	v_rcp_f32_e32 v29, v2
	global_load_dwordx4 v[2:5], v[22:23], off offset:1136
	global_load_dwordx4 v[6:9], v[22:23], off offset:1120
	v_or_b32_e32 v37, 12, v34
	v_or_b32_e32 v38, 16, v34
	v_fma_f32 v22, v29, v28, -v19
	v_mul_f32_e32 v48, v39, v22
	v_mul_f32_e32 v22, v14, v14
	v_fmamk_f32 v22, v22, 0xbdd2d3e7, v129
	v_mul_f32_e32 v22, v22, v14
	v_exp_f32_e32 v49, v22
	global_load_dwordx2 v[74:75], v20, s[16:17] offset:160
	global_load_dwordx2 v[22:23], v20, s[16:17] offset:176
	global_load_dwordx2 v[76:77], v20, s[20:21] offset:160
	global_load_dwordx2 v[28:29], v20, s[20:21] offset:176
	s_waitcnt vmcnt(8)
	v_fma_f32 v24, v24, v48, v26
	v_lshlrev_b32_e32 v48, 16, v15
	v_add_f32_e32 v26, 1.0, v49
	v_mul_f32_e32 v49, v48, v48
	v_fmamk_f32 v49, v49, 0xbdd2d3e7, v129
	v_mul_f32_e32 v49, v49, v48
	v_exp_f32_e32 v49, v49
	v_rcp_f32_e32 v26, v26
	v_cvt_pk_bf16_f32 v24, v24, s0
	ds_write_b16 v35, v24 offset:43248
	v_add_f32_e32 v24, 1.0, v49
	v_fma_f32 v14, v26, v14, -v19
	v_rcp_f32_e32 v24, v24
	v_mul_f32_e32 v14, v39, v14
	v_fmac_f32_e32 v27, v25, v14
	v_cvt_pk_bf16_f32 v14, v27, s0
	v_and_b32_e32 v15, 0xffff0000, v15
	ds_write_b16 v35, v14 offset:43520
	v_fma_f32 v14, v24, v48, -v19
	v_mul_f32_e32 v24, v15, v15
	v_fmamk_f32 v24, v24, 0xbdd2d3e7, v129
	v_mul_f32_e32 v24, v24, v15
	v_exp_f32_e32 v24, v24
	v_lshlrev_b32_e32 v25, 16, v16
	v_mul_f32_e32 v26, v25, v25
	v_fmamk_f32 v26, v26, 0xbdd2d3e7, v129
	v_mul_f32_e32 v26, v26, v25
	v_add_f32_e32 v24, 1.0, v24
	v_rcp_f32_e32 v24, v24
	v_exp_f32_e32 v26, v26
	v_mul_f32_e32 v73, v39, v14
	v_fma_f32 v15, v24, v15, -v19
	v_mul_f32_e32 v72, v39, v15
	v_and_b32_e32 v15, 0xffff0000, v16
	v_add_f32_e32 v14, 1.0, v26
	v_mul_f32_e32 v16, v15, v15
	v_rcp_f32_e32 v14, v14
	v_fmamk_f32 v16, v16, 0xbdd2d3e7, v129
	v_mul_f32_e32 v16, v16, v15
	v_lshlrev_b32_e32 v24, 16, v17
	v_fma_f32 v14, v14, v25, -v19
	v_exp_f32_e32 v16, v16
	v_mul_f32_e32 v25, v24, v24
	v_fmamk_f32 v25, v25, 0xbdd2d3e7, v129
	v_mul_f32_e32 v25, v25, v24
	v_add_f32_e32 v16, 1.0, v16
	v_rcp_f32_e32 v16, v16
	v_exp_f32_e32 v25, v25
	v_mul_f32_e32 v14, v39, v14
	s_waitcnt vmcnt(6)
	v_fma_f32 v14, v60, v14, v66
	v_cvt_pk_bf16_f32 v14, v14, s0
	ds_write_b16 v35, v14 offset:44336
	v_fma_f32 v14, v16, v15, -v19
	v_add_f32_e32 v15, 1.0, v25
	v_rcp_f32_e32 v15, v15
	v_mul_f32_e32 v14, v39, v14
	v_fmac_f32_e32 v67, v14, v61
	v_cvt_pk_bf16_f32 v14, v67, s0
	ds_write_b16 v35, v14 offset:44608
	v_fma_f32 v14, v15, v24, -v19
	v_and_b32_e32 v15, 0xffff0000, v17
	v_mul_f32_e32 v16, v15, v15
	v_fmamk_f32 v16, v16, 0xbdd2d3e7, v129
	v_mul_f32_e32 v16, v16, v15
	v_exp_f32_e32 v16, v16
	v_lshlrev_b32_e32 v17, 16, v10
	v_mul_f32_e32 v24, v17, v17
	v_fmamk_f32 v24, v24, 0xbdd2d3e7, v129
	v_mul_f32_e32 v24, v24, v17
	v_add_f32_e32 v16, 1.0, v16
	v_rcp_f32_e32 v16, v16
	v_exp_f32_e32 v24, v24
	v_and_b32_e32 v10, 0xffff0000, v10
	v_mul_f32_e32 v71, v39, v14
	v_fma_f32 v15, v16, v15, -v19
	v_add_f32_e32 v14, 1.0, v24
	v_mul_f32_e32 v70, v39, v15
	v_mul_f32_e32 v15, v10, v10
	v_rcp_f32_e32 v14, v14
	v_fmamk_f32 v15, v15, 0xbdd2d3e7, v129
	v_mul_f32_e32 v15, v15, v10
	v_fma_f32 v14, v14, v17, -v19
	v_exp_f32_e32 v15, v15
	v_mul_f32_e32 v14, v39, v14
	s_waitcnt vmcnt(1)
	v_fma_f32 v14, v74, v14, v76
	v_cvt_pk_bf16_f32 v14, v14, s0
	ds_write_b16 v35, v14 offset:45424
	v_add_f32_e32 v14, 1.0, v15
	v_lshlrev_b32_e32 v15, 16, v11
	v_rcp_f32_e32 v14, v14
	v_mul_f32_e32 v16, v15, v15
	v_fmamk_f32 v16, v16, 0xbdd2d3e7, v129
	v_mul_f32_e32 v16, v16, v15
	v_and_b32_e32 v11, 0xffff0000, v11
	v_fma_f32 v10, v14, v10, -v19
	v_mul_f32_e32 v14, v11, v11
	v_exp_f32_e32 v16, v16
	v_fmamk_f32 v14, v14, 0xbdd2d3e7, v129
	v_mul_f32_e32 v14, v14, v11
	v_mul_f32_e32 v10, v39, v10
	v_fmac_f32_e32 v77, v75, v10
	v_add_f32_e32 v10, 1.0, v16
	v_exp_f32_e32 v14, v14
	v_rcp_f32_e32 v10, v10
	v_cvt_pk_bf16_f32 v16, v77, s0
	ds_write_b16 v35, v16 offset:45696
	v_add_f32_e32 v14, 1.0, v14
	v_fma_f32 v10, v10, v15, -v19
	v_rcp_f32_e32 v14, v14
	v_lshlrev_b32_e32 v15, 16, v12
	v_mul_f32_e32 v16, v15, v15
	v_fmamk_f32 v16, v16, 0xbdd2d3e7, v129
	v_mul_f32_e32 v16, v16, v15
	v_mul_f32_e32 v67, v39, v10
	v_fma_f32 v10, v14, v11, -v19
	v_and_b32_e32 v11, 0xffff0000, v12
	v_mul_f32_e32 v12, v11, v11
	v_exp_f32_e32 v16, v16
	v_fmamk_f32 v12, v12, 0xbdd2d3e7, v129
	v_mul_f32_e32 v12, v12, v11
	v_mul_f32_e32 v66, v39, v10
	v_add_f32_e32 v10, 1.0, v16
	v_exp_f32_e32 v12, v12
	v_rcp_f32_e32 v10, v10
	v_or_b32_e32 v76, 2, v34
	v_lshlrev_b32_e32 v14, 2, v76
	v_add_f32_e32 v12, 1.0, v12
	v_fma_f32 v10, v10, v15, -v19
	v_rcp_f32_e32 v12, v12
	v_mul_f32_e32 v10, v39, v10
	s_waitcnt vmcnt(0)
	v_fma_f32 v10, v22, v10, v28
	v_cvt_pk_bf16_f32 v10, v10, s0
	ds_write_b16 v35, v10 offset:46512
	v_fma_f32 v10, v12, v11, -v19
	v_lshlrev_b32_e32 v11, 16, v13
	v_mul_f32_e32 v12, v11, v11
	v_fmamk_f32 v12, v12, 0xbdd2d3e7, v129
	v_mul_f32_e32 v12, v12, v11
	v_exp_f32_e32 v12, v12
	v_mul_f32_e32 v10, v39, v10
	v_fmac_f32_e32 v29, v10, v23
	v_cvt_pk_bf16_f32 v10, v29, s0
	global_load_dword v15, v14, s[16:17]
	s_nop 0
	global_load_dword v14, v14, s[20:21]
	ds_write_b16 v35, v10 offset:46784
	v_add_f32_e32 v10, 1.0, v12
	v_rcp_f32_e32 v10, v10
	v_or_b32_e32 v77, 3, v34
	v_lshlrev_b32_e32 v12, 2, v77
	global_load_dword v16, v12, s[16:17]
	global_load_dword v17, v12, s[20:21]
	v_fma_f32 v10, v10, v11, -v19
	v_and_b32_e32 v11, 0xffff0000, v13
	v_mul_f32_e32 v12, v11, v11
	v_fmamk_f32 v12, v12, 0xbdd2d3e7, v129
	v_mul_f32_e32 v12, v12, v11
	v_lshlrev_b32_e32 v13, 16, v6
	v_exp_f32_e32 v12, v12
	v_mul_f32_e32 v22, v13, v13
	v_fmamk_f32 v22, v22, 0xbdd2d3e7, v129
	v_mul_f32_e32 v22, v22, v13
	v_add_f32_e32 v12, 1.0, v12
	v_exp_f32_e32 v22, v22
	v_rcp_f32_e32 v12, v12
	v_mul_f32_e32 v75, v39, v10
	v_and_b32_e32 v6, 0xffff0000, v6
	v_add_f32_e32 v10, 1.0, v22
	v_fma_f32 v11, v12, v11, -v19
	v_rcp_f32_e32 v10, v10
	v_mul_f32_e32 v74, v39, v11
	v_mul_f32_e32 v11, v6, v6
	v_fmamk_f32 v11, v11, 0xbdd2d3e7, v129
	v_mul_f32_e32 v11, v11, v6
	v_fma_f32 v10, v10, v13, -v19
	v_exp_f32_e32 v22, v11
	v_mul_f32_e32 v82, v39, v10
	global_load_dwordx2 v[10:11], v20, s[16:17] offset:192
	global_load_dwordx2 v[12:13], v20, s[20:21] offset:192
	v_lshlrev_b32_e32 v23, 16, v7
	v_mul_f32_e32 v24, v23, v23
	v_and_b32_e32 v7, 0xffff0000, v7
	v_fmamk_f32 v24, v24, 0xbdd2d3e7, v129
	v_mul_f32_e32 v25, v7, v7
	v_mul_f32_e32 v24, v24, v23
	v_fmamk_f32 v25, v25, 0xbdd2d3e7, v129
	v_mul_f32_e32 v25, v25, v7
	v_add_f32_e32 v22, 1.0, v22
	v_rcp_f32_e32 v22, v22
	v_exp_f32_e32 v24, v24
	v_exp_f32_e32 v25, v25
	v_fma_f32 v6, v22, v6, -v19
	v_add_f32_e32 v22, 1.0, v24
	v_rcp_f32_e32 v22, v22
	v_add_f32_e32 v24, 1.0, v25
	v_rcp_f32_e32 v24, v24
	v_mul_f32_e32 v83, v39, v6
	v_fma_f32 v6, v22, v23, -v19
	v_mul_f32_e32 v62, v39, v6
	v_fma_f32 v6, v24, v7, -v19
	v_lshlrev_b32_e32 v91, 16, v8
	v_mul_f32_e32 v61, v39, v6
	v_or_b32_e32 v6, s88, v31
	v_lshlrev_b32_e32 v6, 7, v6
	v_mov_b32_e32 v7, v1
	v_lshl_add_u64 v[6:7], v[6:7], 2, s[40:41]
	v_lshl_add_u64 v[6:7], v[6:7], 0, v[20:21]
	v_and_b32_e32 v8, 0xffff0000, v8
	v_mul_f32_e32 v98, v8, v8
	v_fmamk_f32 v98, v98, 0xbdd2d3e7, v129
	v_mul_f32_e32 v98, v98, v8
	v_exp_f32_e32 v98, v98
	v_and_b32_e32 v99, 0xffff0000, v9
	v_and_b32_e32 v105, 0xffff0000, v5
	s_waitcnt vmcnt(4)
	v_fmac_f32_e32 v14, v15, v65
	v_mul_u32_u24_e32 v15, 0x110, v76
	v_cvt_pk_bf16_f32 v14, v14, s0
	v_add3_u32 v15, s15, v15, v33
	v_or_b32_e32 v65, 6, v34
	ds_write_b16 v15, v14 offset:34816
	v_lshlrev_b32_e32 v14, 2, v65
	global_load_dword v85, v14, s[16:17]
	global_load_dword v86, v14, s[20:21]
	s_waitcnt vmcnt(4)
	v_fmac_f32_e32 v17, v16, v59
	v_lshlrev_b32_e32 v14, 2, v78
	v_mul_u32_u24_e32 v15, 0x110, v77
	global_load_dword v87, v14, s[16:17]
	global_load_dword v88, v14, s[20:21]
	v_cvt_pk_bf16_f32 v14, v17, s0
	v_add3_u32 v15, s15, v15, v33
	ds_write_b16 v15, v14 offset:34816
	v_lshlrev_b32_e32 v14, 2, v81
	global_load_dwordx2 v[22:23], v20, s[16:17] offset:208
	global_load_dwordx2 v[24:25], v20, s[20:21] offset:208
	global_load_dword v89, v14, s[16:17]
	global_load_dword v90, v14, s[20:21]
	v_lshlrev_b32_e32 v14, 2, v79
	global_load_dword v92, v14, s[16:17]
	global_load_dword v93, v14, s[20:21]
	v_mul_f32_e32 v14, v91, v91
	v_fmamk_f32 v14, v14, 0xbdd2d3e7, v129
	v_mul_f32_e32 v14, v14, v91
	v_or_b32_e32 v59, 14, v34
	v_lshlrev_b32_e32 v15, 2, v59
	global_load_dword v94, v15, s[16:17]
	global_load_dword v95, v15, s[20:21]
	v_exp_f32_e32 v96, v14
	global_load_dwordx2 v[14:15], v20, s[16:17] offset:224
	global_load_dwordx2 v[16:17], v20, s[16:17] offset:240
	global_load_dwordx2 v[26:27], v20, s[20:21] offset:224
	s_nop 0
	global_load_dwordx2 v[20:21], v20, s[20:21] offset:240
	v_or_b32_e32 v40, 20, v34
	v_or_b32_e32 v41, 24, v34
	v_or_b32_e32 v42, 28, v34
	v_or_b32_e32 v43, 32, v34
	v_or_b32_e32 v48, 36, v34
	v_or_b32_e32 v49, 40, v34
	v_or_b32_e32 v51, 44, v34
	v_or_b32_e32 v60, 52, v34
	s_waitcnt vmcnt(16)
	v_fma_f32 v10, v10, v82, v12
	v_cvt_pk_bf16_f32 v12, v10, s0
	v_or_b32_e32 v10, 15, v34
	v_add_f32_e32 v82, 1.0, v96
	v_lshlrev_b32_e32 v96, 2, v10
	global_load_dword v97, v96, s[16:17]
	s_nop 0
	global_load_dword v96, v96, s[20:21]
	v_rcp_f32_e32 v82, v82
	ds_write_b16 v35, v12 offset:47600
	v_fmac_f32_e32 v13, v11, v83
	v_cvt_pk_bf16_f32 v11, v13, s0
	v_fma_f32 v12, v82, v91, -v19
	v_lshlrev_b32_e32 v91, 16, v9
	v_add_f32_e32 v82, 1.0, v98
	v_mul_f32_e32 v98, v91, v91
	v_fmamk_f32 v98, v98, 0xbdd2d3e7, v129
	v_mul_f32_e32 v98, v98, v91
	v_rcp_f32_e32 v82, v82
	v_exp_f32_e32 v98, v98
	v_mul_f32_e32 v12, v39, v12
	v_mul_u32_u24_e32 v13, 0x110, v81
	v_fma_f32 v8, v82, v8, -v19
	v_add_f32_e32 v82, 1.0, v98
	v_rcp_f32_e32 v82, v82
	v_mul_f32_e32 v100, v39, v8
	v_add3_u32 v13, s15, v13, v33
	v_mul_f32_e32 v9, v99, v99
	v_fma_f32 v8, v82, v91, -v19
	v_mul_u32_u24_e32 v82, 0x110, v65
	v_add3_u32 v82, s15, v82, v33
	v_fmamk_f32 v9, v9, 0xbdd2d3e7, v129
	v_mul_f32_e32 v9, v9, v99
	v_exp_f32_e32 v9, v9
	v_or_b32_e32 v91, 26, v34
	v_or_b32_e32 v29, 56, v34
	v_or_b32_e32 v28, 60, v34
	v_add_f32_e32 v9, 1.0, v9
	v_rcp_f32_e32 v98, v9
	v_mul_f32_e32 v9, v39, v8
	v_readlane_b32 s46, v251, 56
	v_readlane_b32 s47, v251, 57
	v_fma_f32 v8, v98, v99, -v19
	v_or_b32_e32 v98, 30, v34
	v_mul_f32_e32 v8, v39, v8
	v_readlane_b32 s48, v251, 58
	v_readlane_b32 s49, v251, 59
	s_waitcnt vmcnt(16)
	v_fmac_f32_e32 v86, v45, v85
	v_cvt_pk_bf16_f32 v45, v86, s0
	ds_write_b16 v82, v45 offset:34816
	v_mul_u32_u24_e32 v45, 0x110, v78
	s_waitcnt vmcnt(14)
	v_fmac_f32_e32 v88, v44, v87
	v_cvt_pk_bf16_f32 v44, v88, s0
	v_add3_u32 v45, s15, v45, v33
	ds_write_b16 v45, v44 offset:34816
	ds_write_b16 v35, v11 offset:47872
	s_waitcnt vmcnt(12)
	v_fma_f32 v11, v22, v12, v24
	s_waitcnt vmcnt(10)
	v_fmac_f32_e32 v90, v89, v47
	v_cvt_pk_bf16_f32 v12, v90, s0
	ds_write_b16 v13, v12 offset:34816
	s_waitcnt vmcnt(8)
	v_fmac_f32_e32 v93, v92, v46
	v_mul_u32_u24_e32 v13, 0x110, v79
	v_cvt_pk_bf16_f32 v12, v93, s0
	v_add3_u32 v13, s15, v13, v33
	v_cvt_pk_bf16_f32 v11, v11, s0
	ds_write_b16 v13, v12 offset:34816
	ds_write_b16 v35, v11 offset:48688
	v_lshlrev_b32_e32 v13, 16, v2
	v_mul_f32_e32 v22, v13, v13
	v_fmamk_f32 v22, v22, 0xbdd2d3e7, v129
	v_mul_f32_e32 v22, v22, v13
	v_exp_f32_e32 v22, v22
	v_fmac_f32_e32 v25, v100, v23
	v_cvt_pk_bf16_f32 v11, v25, s0
	s_waitcnt vmcnt(6)
	v_fmac_f32_e32 v95, v55, v94
	v_mul_u32_u24_e32 v12, 0x110, v59
	ds_write_b16 v35, v11 offset:48960
	v_cvt_pk_bf16_f32 v11, v95, s0
	v_add3_u32 v12, s15, v12, v33
	ds_write_b16 v12, v11 offset:34816
	v_add_f32_e32 v12, 1.0, v22
	v_rcp_f32_e32 v12, v12
	s_waitcnt vmcnt(0)
	v_fmac_f32_e32 v96, v54, v97
	v_mul_u32_u24_e32 v22, 0x110, v10
	v_cvt_pk_bf16_f32 v11, v96, s0
	v_add3_u32 v22, s15, v22, v33
	v_and_b32_e32 v2, 0xffff0000, v2
	ds_write_b16 v22, v11 offset:34816
	v_fma_f32 v11, v12, v13, -v19
	v_mul_f32_e32 v12, v2, v2
	v_lshlrev_b32_e32 v13, 16, v3
	v_fmamk_f32 v12, v12, 0xbdd2d3e7, v129
	v_mul_f32_e32 v22, v13, v13
	v_mul_f32_e32 v12, v12, v2
	v_fmamk_f32 v22, v22, 0xbdd2d3e7, v129
	v_mul_f32_e32 v22, v22, v13
	v_exp_f32_e32 v12, v12
	v_exp_f32_e32 v22, v22
	v_mul_f32_e32 v11, v39, v11
	v_add_f32_e32 v12, 1.0, v12
	v_fma_f32 v11, v14, v11, v26
	v_rcp_f32_e32 v12, v12
	v_add_f32_e32 v14, 1.0, v22
	v_rcp_f32_e32 v14, v14
	v_and_b32_e32 v3, 0xffff0000, v3
	v_fma_f32 v2, v12, v2, -v19
	v_mul_f32_e32 v12, v39, v2
	v_fma_f32 v2, v14, v13, -v19
	v_mul_f32_e32 v13, v3, v3
	v_fmamk_f32 v13, v13, 0xbdd2d3e7, v129
	v_mul_f32_e32 v13, v13, v3
	v_or_b32_e32 v86, 18, v34
	v_or_b32_e32 v87, 19, v34
	v_lshlrev_b32_e32 v14, 2, v86
	v_lshlrev_b32_e32 v22, 2, v87
	global_load_dword v26, v14, s[16:17]
	s_nop 0
	global_load_dword v14, v14, s[20:21]
	s_nop 0
	global_load_dword v54, v22, s[16:17]
	global_load_dword v55, v22, s[20:21]
	v_lshlrev_b32_e32 v22, 16, v4
	v_exp_f32_e32 v13, v13
	v_mul_f32_e32 v23, v22, v22
	v_fmamk_f32 v23, v23, 0xbdd2d3e7, v129
	v_mul_f32_e32 v23, v23, v22
	v_add_f32_e32 v13, 1.0, v13
	v_rcp_f32_e32 v13, v13
	v_exp_f32_e32 v23, v23
	v_or_b32_e32 v88, 22, v34
	v_lshlrev_b32_e32 v24, 2, v88
	v_fma_f32 v3, v13, v3, -v19
	v_add_f32_e32 v13, 1.0, v23
	global_load_dword v82, v24, s[16:17]
	global_load_dword v83, v24, s[20:21]
	v_or_b32_e32 v89, 23, v34
	v_rcp_f32_e32 v13, v13
	v_and_b32_e32 v4, 0xffff0000, v4
	v_lshlrev_b32_e32 v24, 2, v89
	v_mul_f32_e32 v23, v4, v4
	global_load_dword v84, v24, s[16:17]
	global_load_dword v85, v24, s[20:21]
	v_fmamk_f32 v23, v23, 0xbdd2d3e7, v129
	v_mul_f32_e32 v23, v23, v4
	v_fma_f32 v13, v13, v22, -v19
	v_lshlrev_b32_e32 v22, 2, v91
	global_load_dword v92, v22, s[16:17]
	global_load_dword v93, v22, s[20:21]
	v_or_b32_e32 v94, 27, v34
	v_exp_f32_e32 v23, v23
	v_lshlrev_b32_e32 v22, 2, v94
	global_load_dword v95, v22, s[16:17]
	global_load_dword v96, v22, s[20:21]
	v_lshlrev_b32_e32 v97, 16, v5
	v_lshlrev_b32_e32 v22, 2, v98
	global_load_dword v99, v22, s[16:17]
	global_load_dword v100, v22, s[20:21]
	v_mul_f32_e32 v22, 0x3d372713, v97
	v_mul_f32_e32 v90, v39, v13
	v_add_f32_e32 v13, 1.0, v23
	v_lshlrev_b32_e32 v23, 2, v101
	v_mul_f32_e32 v22, v22, v97
	global_load_dword v102, v23, s[16:17]
	global_load_dword v103, v23, s[20:21]
	v_fma_f32 v22, v22, v97, v97
	v_mul_f32_e32 v22, 0xbfcc422a, v22
	v_mul_f32_e32 v104, 0x3fb8aa3b, v22
	global_load_dwordx4 v[22:25], v[6:7], off offset:16
	global_load_dwordx4 v[44:47], v[6:7], off
	v_rcp_f32_e32 v13, v13
	v_exp_f32_e32 v104, v104
	v_mul_f32_e32 v5, v105, v105
	v_fmamk_f32 v5, v5, 0xbdd2d3e7, v129
	v_mul_f32_e32 v5, v5, v105
	v_fma_f32 v4, v13, v4, -v19
	v_add_f32_e32 v13, 1.0, v104
	v_rcp_f32_e32 v13, v13
	v_exp_f32_e32 v5, v5
	v_mul_f32_e32 v106, v39, v4
	v_cvt_pk_bf16_f32 v11, v11, s0
	v_fma_f32 v4, v13, v97, -v19
	v_add_f32_e32 v5, 1.0, v5
	v_rcp_f32_e32 v104, v5
	v_fmac_f32_e32 v27, v15, v12
	v_mul_f32_e32 v5, v39, v4
	v_fma_f32 v16, v16, v90, v20
	v_fma_f32 v4, v104, v105, -v19
	v_mul_u32_u24_e32 v19, 0x110, v88
	v_add3_u32 v19, s15, v19, v33
	v_cvt_pk_bf16_f32 v16, v16, s0
	v_fmac_f32_e32 v21, v106, v17
	v_mul_f32_e32 v2, v39, v2
	v_mul_f32_e32 v3, v39, v3
	v_mul_f32_e32 v4, v39, v4
	v_mul_u32_u24_e32 v17, 0x110, v91
	v_add3_u32 v17, s15, v17, v33
	v_readlane_b32 s56, v252, 2
	v_readlane_b32 s57, v252, 3
	v_readlane_b32 s58, v252, 4
	v_readlane_b32 s59, v252, 5
	s_waitcnt vmcnt(16)
	v_fmac_f32_e32 v14, v26, v53
	v_cvt_pk_bf16_f32 v13, v14, s0
	v_mul_u32_u24_e32 v14, 0x110, v86
	v_add3_u32 v14, s15, v14, v33
	ds_write_b16 v14, v13 offset:34816
	s_waitcnt vmcnt(14)
	v_fmac_f32_e32 v55, v54, v52
	v_mul_u32_u24_e32 v14, 0x110, v87
	v_cvt_pk_bf16_f32 v13, v55, s0
	v_add3_u32 v14, s15, v14, v33
	ds_write_b16 v14, v13 offset:34816
	ds_write_b16 v35, v11 offset:49776
	v_cvt_pk_bf16_f32 v11, v27, s0
	ds_write_b16 v35, v11 offset:50048
	global_load_dwordx4 v[12:15], v[6:7], off offset:48
	global_load_dwordx4 v[52:55], v[6:7], off offset:32
	s_waitcnt vmcnt(14)
	v_fmac_f32_e32 v83, v58, v82
	v_cvt_pk_bf16_f32 v11, v83, s0
	ds_write_b16 v19, v11 offset:34816
	v_mul_u32_u24_e32 v19, 0x110, v89
	v_add3_u32 v19, s15, v19, v33
	v_or_b32_e32 v58, 35, v34
	s_waitcnt vmcnt(12)
	v_fmac_f32_e32 v85, v56, v84
	v_cvt_pk_bf16_f32 v11, v85, s0
	v_or_b32_e32 v56, 34, v34
	ds_write_b16 v19, v11 offset:34816
	v_lshlrev_b32_e32 v11, 2, v56
	v_lshlrev_b32_e32 v19, 2, v58
	global_load_dword v39, v11, s[16:17]
	s_nop 0
	global_load_dword v11, v11, s[20:21]
	s_nop 0
	global_load_dword v90, v19, s[16:17]
	global_load_dword v97, v19, s[20:21]
	ds_write_b16 v35, v16 offset:50864
	v_cvt_pk_bf16_f32 v16, v21, s0
	s_waitcnt vmcnt(14)
	v_fmac_f32_e32 v93, v92, v64
	ds_write_b16 v35, v16 offset:51136
	v_cvt_pk_bf16_f32 v16, v93, s0
	ds_write_b16 v17, v16 offset:34816
	s_waitcnt vmcnt(12)
	v_fmac_f32_e32 v96, v95, v63
	v_mul_u32_u24_e32 v17, 0x110, v94
	v_cvt_pk_bf16_f32 v16, v96, s0
	v_add3_u32 v17, s15, v17, v33
	ds_write_b16 v17, v16 offset:34816
	s_waitcnt vmcnt(10)
	v_fmac_f32_e32 v100, v69, v99
	v_mul_u32_u24_e32 v17, 0x110, v98
	v_cvt_pk_bf16_f32 v16, v100, s0
	v_add3_u32 v17, s15, v17, v33
	ds_write_b16 v17, v16 offset:34816
	s_waitcnt vmcnt(8)
	v_fmac_f32_e32 v103, v68, v102
	v_mul_u32_u24_e32 v17, 0x110, v101
	v_cvt_pk_bf16_f32 v16, v103, s0
	v_add3_u32 v17, s15, v17, v33
	ds_write_b16 v17, v16 offset:34816
	s_waitcnt vmcnt(6)
	v_cndmask_b32_e32 v16, 0, v45, vcc
	v_cmp_le_u32_e32 vcc, v34, v31
	v_or_b32_e32 v35, 38, v34
	v_or_b32_e32 v68, 39, v34
	v_cndmask_b32_e32 v17, 0, v44, vcc
	v_cvt_pk_bf16_f32 v16, v17, v16
	v_lshlrev_b32_e32 v17, 2, v35
	global_load_dword v63, v17, s[16:17]
	global_load_dword v64, v17, s[20:21]
	v_lshlrev_b32_e32 v19, 2, v68
	global_load_dword v69, v19, s[16:17]
	global_load_dword v92, v19, s[20:21]
	v_cvt_pk_bf16_f32 v17, v46, v47
	v_cmp_le_u32_e32 vcc, v76, v31
	global_load_dwordx4 v[44:47], v[6:7], off offset:80
	global_load_dwordx4 v[82:85], v[6:7], off offset:64
	v_cndmask_b32_e32 v19, 0, v17, vcc
	v_lshrrev_b32_e32 v17, 16, v17
	v_cmp_le_u32_e32 vcc, v77, v31
	v_or_b32_e32 v77, 47, v34
	s_waitcnt vmcnt(8)
	v_fmac_f32_e32 v11, v39, v73
	v_cndmask_b32_e32 v17, 0, v17, vcc
	v_cmp_gt_u32_e32 vcc, v31, v18
	v_perm_b32 v17, v17, v19, s19
	v_cvt_pk_bf16_f32 v11, v11, s0
	v_cndmask_b32_e32 v19, 0, v23, vcc
	v_cmp_le_u32_e32 vcc, v18, v31
	s_waitcnt vmcnt(6)
	v_fmac_f32_e32 v97, v90, v72
	s_waitcnt vmcnt(4)
	v_fmac_f32_e32 v64, v71, v63
	v_cndmask_b32_e32 v18, 0, v22, vcc
	v_cvt_pk_bf16_f32 v18, v18, v19
	v_cvt_pk_bf16_f32 v19, v24, v25
	v_cmp_le_u32_e32 vcc, v65, v31
	s_waitcnt vmcnt(2)
	v_fmac_f32_e32 v92, v70, v69
	v_cndmask_b32_e32 v20, 0, v19, vcc
	v_lshrrev_b32_e32 v19, 16, v19
	v_cmp_le_u32_e32 vcc, v78, v31
	s_nop 1
	v_cndmask_b32_e32 v19, 0, v19, vcc
	v_perm_b32 v19, v19, v20, s19
	ds_write_b128 v0, v[16:19]
	global_load_dwordx4 v[20:23], v[6:7], off offset:112
	global_load_dwordx4 v[24:27], v[6:7], off offset:96
	v_cmp_gt_u32_e32 vcc, v31, v36
	s_nop 1
	v_cndmask_b32_e32 v16, 0, v53, vcc
	v_cmp_le_u32_e32 vcc, v36, v31
	s_nop 1
	v_cndmask_b32_e32 v17, 0, v52, vcc
	v_cvt_pk_bf16_f32 v16, v17, v16
	v_cvt_pk_bf16_f32 v17, v54, v55
	v_cmp_le_u32_e32 vcc, v81, v31
	v_or_b32_e32 v52, 42, v34
	v_or_b32_e32 v55, 43, v34
	v_cndmask_b32_e32 v18, 0, v17, vcc
	v_lshrrev_b32_e32 v17, 16, v17
	v_cmp_le_u32_e32 vcc, v79, v31
	v_lshlrev_b32_e32 v19, 2, v55
	v_and_or_b32 v81, v30, 64, v32
	v_cndmask_b32_e32 v17, 0, v17, vcc
	v_perm_b32 v17, v17, v18, s19
	v_mul_u32_u24_e32 v18, 0x110, v56
	v_add3_u32 v18, s15, v18, v33
	ds_write_b16 v18, v11 offset:34816
	v_lshlrev_b32_e32 v18, 2, v52
	global_load_dword v53, v18, s[16:17]
	global_load_dword v54, v18, s[20:21]
	v_mul_u32_u24_e32 v18, 0x110, v58
	v_cvt_pk_bf16_f32 v11, v97, s0
	v_add3_u32 v18, s15, v18, v33
	v_cmp_gt_u32_e32 vcc, v31, v37
	global_load_dword v65, v19, s[16:17]
	global_load_dword v72, v19, s[20:21]
	ds_write_b16 v18, v11 offset:34816
	v_cndmask_b32_e32 v11, 0, v13, vcc
	v_cmp_le_u32_e32 vcc, v37, v31
	s_waitcnt vmcnt(2)
	v_fmac_f32_e32 v54, v53, v67
	v_cndmask_b32_e32 v12, 0, v12, vcc
	v_cvt_pk_bf16_f32 v18, v12, v11
	v_cvt_pk_bf16_f32 v11, v14, v15
	v_cmp_le_u32_e32 vcc, v59, v31
	v_or_b32_e32 v59, 46, v34
	s_waitcnt vmcnt(0)
	v_fmac_f32_e32 v72, v65, v66
	v_cndmask_b32_e32 v12, 0, v11, vcc
	v_lshrrev_b32_e32 v11, 16, v11
	v_cmp_le_u32_e32 vcc, v10, v31
	s_nop 1
	v_cndmask_b32_e32 v10, 0, v11, vcc
	v_perm_b32 v19, v10, v12, s19
	v_lshlrev_b32_e32 v10, 2, v59
	global_load_dword v73, v10, s[16:17]
	global_load_dword v76, v10, s[20:21]
	ds_write_b128 v0, v[16:19] offset:16
	v_lshlrev_b32_e32 v10, 2, v77
	v_mul_u32_u24_e32 v11, 0x110, v35
	global_load_dword v78, v10, s[16:17]
	global_load_dword v79, v10, s[20:21]
	v_cvt_pk_bf16_f32 v10, v64, s0
	v_add3_u32 v11, s15, v11, v33
	ds_write_b16 v11, v10 offset:34816
	global_load_dwordx4 v[10:13], v[6:7], off offset:144
	global_load_dwordx4 v[14:17], v[6:7], off offset:128
	v_mul_u32_u24_e32 v19, 0x110, v68
	v_cvt_pk_bf16_f32 v18, v92, s0
	v_add3_u32 v19, s15, v19, v33
	v_cmp_gt_u32_e32 vcc, v31, v38
	ds_write_b16 v19, v18 offset:34816
	s_waitcnt vmcnt(4)
	v_fmac_f32_e32 v76, v75, v73
	v_cndmask_b32_e32 v18, 0, v83, vcc
	v_cmp_le_u32_e32 vcc, v38, v31
	s_waitcnt vmcnt(2)
	v_fmac_f32_e32 v79, v74, v78
	v_cndmask_b32_e32 v19, 0, v82, vcc
	v_cvt_pk_bf16_f32 v36, v19, v18
	v_cvt_pk_bf16_f32 v18, v84, v85
	v_cmp_le_u32_e32 vcc, v86, v31
	v_or_b32_e32 v82, s4, v81
	s_nop 0
	v_cndmask_b32_e32 v19, 0, v18, vcc
	v_lshrrev_b32_e32 v18, 16, v18
	v_cmp_le_u32_e32 vcc, v87, v31
	s_nop 1
	v_cndmask_b32_e32 v18, 0, v18, vcc
	v_cmp_gt_u32_e32 vcc, v31, v40
	v_perm_b32 v37, v18, v19, s19
	s_nop 0
	v_cndmask_b32_e32 v18, 0, v45, vcc
	v_cmp_le_u32_e32 vcc, v40, v31
	s_nop 1
	v_cndmask_b32_e32 v19, 0, v44, vcc
	v_cvt_pk_bf16_f32 v38, v19, v18
	v_cvt_pk_bf16_f32 v18, v46, v47
	v_cmp_le_u32_e32 vcc, v88, v31
	s_nop 1
	v_cndmask_b32_e32 v19, 0, v18, vcc
	v_lshrrev_b32_e32 v18, 16, v18
	v_cmp_le_u32_e32 vcc, v89, v31
	s_nop 1
	v_cndmask_b32_e32 v18, 0, v18, vcc
	v_cmp_gt_u32_e32 vcc, v31, v41
	v_perm_b32 v39, v18, v19, s19
	ds_write_b128 v0, v[36:39] offset:32
	v_cndmask_b32_e32 v18, 0, v25, vcc
	v_cmp_le_u32_e32 vcc, v41, v31
	v_mul_u32_u24_e32 v41, 0x110, v52
	v_add3_u32 v41, s15, v41, v33
	v_cndmask_b32_e32 v19, 0, v24, vcc
	v_cvt_pk_bf16_f32 v18, v19, v18
	v_cvt_pk_bf16_f32 v19, v26, v27
	global_load_dwordx4 v[24:27], v[6:7], off offset:176
	global_load_dwordx4 v[36:39], v[6:7], off offset:160
	v_cmp_le_u32_e32 vcc, v91, v31
	s_nop 1
	v_cndmask_b32_e32 v40, 0, v19, vcc
	v_lshrrev_b32_e32 v19, 16, v19
	v_cmp_le_u32_e32 vcc, v94, v31
	s_nop 1
	v_cndmask_b32_e32 v19, 0, v19, vcc
	v_cmp_gt_u32_e32 vcc, v31, v42
	v_perm_b32 v19, v19, v40, s19
	v_cvt_pk_bf16_f32 v40, v54, s0
	v_cndmask_b32_e32 v21, 0, v21, vcc
	v_cmp_le_u32_e32 vcc, v42, v31
	ds_write_b16 v41, v40 offset:34816
	v_mul_u32_u24_e32 v41, 0x110, v55
	v_cndmask_b32_e32 v20, 0, v20, vcc
	v_cvt_pk_bf16_f32 v20, v20, v21
	v_cvt_pk_bf16_f32 v21, v22, v23
	v_cmp_le_u32_e32 vcc, v98, v31
	v_cvt_pk_bf16_f32 v40, v72, s0
	v_add3_u32 v41, s15, v41, v33
	v_cndmask_b32_e32 v22, 0, v21, vcc
	v_lshrrev_b32_e32 v21, 16, v21
	v_cmp_le_u32_e32 vcc, v101, v31
	ds_write_b16 v41, v40 offset:34816
	v_mul_u32_u24_e32 v23, 0x110, v77
	v_cndmask_b32_e32 v21, 0, v21, vcc
	v_perm_b32 v21, v21, v22, s19
	ds_write_b128 v0, v[18:21] offset:48
	v_mul_u32_u24_e32 v19, 0x110, v59
	v_cvt_pk_bf16_f32 v18, v76, s0
	v_add3_u32 v19, s15, v19, v33
	v_cmp_gt_u32_e32 vcc, v31, v43
	ds_write_b16 v19, v18 offset:34816
	v_cvt_pk_bf16_f32 v22, v79, s0
	v_add3_u32 v23, s15, v23, v33
	s_waitcnt vmcnt(2)
	v_cndmask_b32_e32 v15, 0, v15, vcc
	v_cmp_le_u32_e32 vcc, v43, v31
	global_load_dwordx4 v[18:21], v[6:7], off offset:208
	global_load_dwordx4 v[44:47], v[6:7], off offset:192
	ds_write_b16 v23, v22 offset:34816
	v_cndmask_b32_e32 v14, 0, v14, vcc
	v_or_b32_e32 v23, 50, v34
	v_cvt_pk_bf16_f32 v14, v14, v15
	v_cvt_pk_bf16_f32 v15, v16, v17
	v_or_b32_e32 v22, 51, v34
	v_lshlrev_b32_e32 v17, 2, v23
	v_cmp_le_u32_e32 vcc, v56, v31
	global_load_dword v40, v17, s[16:17]
	global_load_dword v41, v17, s[20:21]
	v_lshlrev_b32_e32 v17, 2, v22
	v_cndmask_b32_e32 v16, 0, v15, vcc
	v_lshrrev_b32_e32 v15, 16, v15
	global_load_dword v42, v17, s[16:17]
	global_load_dword v43, v17, s[20:21]
	v_cmp_le_u32_e32 vcc, v58, v31
	s_waitcnt vmcnt(2)
	v_fmac_f32_e32 v41, v40, v62
	v_cndmask_b32_e32 v15, 0, v15, vcc
	v_cmp_gt_u32_e32 vcc, v31, v48
	v_perm_b32 v15, v15, v16, s19
	s_waitcnt vmcnt(0)
	v_fmac_f32_e32 v43, v42, v61
	v_cndmask_b32_e32 v11, 0, v11, vcc
	v_cmp_le_u32_e32 vcc, v48, v31
	v_or_b32_e32 v48, 54, v34
	s_nop 0
	v_cndmask_b32_e32 v10, 0, v10, vcc
	v_cvt_pk_bf16_f32 v16, v10, v11
	v_cvt_pk_bf16_f32 v10, v12, v13
	v_cmp_le_u32_e32 vcc, v35, v31
	v_or_b32_e32 v35, 55, v34
	s_nop 0
	v_cndmask_b32_e32 v11, 0, v10, vcc
	v_lshrrev_b32_e32 v10, 16, v10
	v_cmp_le_u32_e32 vcc, v68, v31
	s_nop 1
	v_cndmask_b32_e32 v10, 0, v10, vcc
	v_perm_b32 v17, v10, v11, s19
	v_lshlrev_b32_e32 v10, 2, v48
	global_load_dword v53, v10, s[16:17]
	global_load_dword v54, v10, s[20:21]
	v_lshlrev_b32_e32 v10, 2, v35
	global_load_dword v56, v10, s[16:17]
	global_load_dword v58, v10, s[20:21]
	v_cmp_gt_u32_e32 vcc, v31, v49
	ds_write_b128 v0, v[14:17] offset:64
	s_waitcnt vmcnt(2)
	v_fmac_f32_e32 v54, v9, v53
	v_cndmask_b32_e32 v10, 0, v37, vcc
	v_cmp_le_u32_e32 vcc, v49, v31
	v_or_b32_e32 v49, 59, v34
	v_cvt_pk_bf16_f32 v9, v54, s0
	v_cndmask_b32_e32 v11, 0, v36, vcc
	v_cvt_pk_bf16_f32 v10, v11, v10
	v_cvt_pk_bf16_f32 v11, v38, v39
	v_cmp_le_u32_e32 vcc, v52, v31
	global_load_dwordx4 v[14:17], v[6:7], off offset:240
	global_load_dwordx4 v[36:39], v[6:7], off offset:224
	v_cndmask_b32_e32 v12, 0, v11, vcc
	v_lshrrev_b32_e32 v11, 16, v11
	v_cmp_le_u32_e32 vcc, v55, v31
	v_or_b32_e32 v52, 58, v34
	s_waitcnt vmcnt(2)
	v_fmac_f32_e32 v58, v8, v56
	v_cndmask_b32_e32 v6, 0, v11, vcc
	v_perm_b32 v11, v6, v12, s19
	v_lshlrev_b32_e32 v6, 2, v52
	global_load_dword v55, v6, s[16:17]
	global_load_dword v63, v6, s[20:21]
	v_lshlrev_b32_e32 v6, 2, v49
	v_cmp_gt_u32_e32 vcc, v31, v51
	global_load_dword v64, v6, s[16:17]
	global_load_dword v65, v6, s[20:21]
	v_cndmask_b32_e32 v6, 0, v25, vcc
	v_cmp_le_u32_e32 vcc, v51, v31
	s_waitcnt vmcnt(2)
	v_fmac_f32_e32 v63, v55, v2
	v_cndmask_b32_e32 v7, 0, v24, vcc
	v_cvt_pk_bf16_f32 v12, v7, v6
	v_cvt_pk_bf16_f32 v6, v26, v27
	v_cmp_le_u32_e32 vcc, v59, v31
	v_mul_u32_u24_e32 v26, 0x110, v22
	v_cvt_pk_bf16_f32 v27, v41, s0
	v_cndmask_b32_e32 v7, 0, v6, vcc
	v_lshrrev_b32_e32 v6, 16, v6
	v_cmp_le_u32_e32 vcc, v77, v31
	v_add3_u32 v26, s15, v26, v33
	v_cvt_pk_bf16_f32 v2, v63, s0
	v_cndmask_b32_e32 v6, 0, v6, vcc
	v_perm_b32 v13, v6, v7, s19
	ds_write_b128 v0, v[10:13] offset:80
	v_or_b32_e32 v11, 62, v34
	v_or_b32_e32 v10, 63, v34
	v_lshlrev_b32_e32 v7, 2, v11
	global_load_dword v12, v7, s[16:17]
	global_load_dword v13, v7, s[20:21]
	v_lshlrev_b32_e32 v7, 2, v10
	global_load_dword v24, v7, s[16:17]
	global_load_dword v25, v7, s[20:21]
	v_cmp_gt_u32_e32 vcc, v31, v57
	s_waitcnt vmcnt(4)
	v_fmac_f32_e32 v65, v64, v3
	s_waitcnt vmcnt(2)
	v_fmac_f32_e32 v13, v5, v12
	v_cndmask_b32_e32 v6, 0, v45, vcc
	v_cmp_le_u32_e32 vcc, v57, v31
	v_cvt_pk_bf16_f32 v5, v13, s0
	s_waitcnt vmcnt(0)
	v_fmac_f32_e32 v25, v4, v24
	v_cndmask_b32_e32 v7, 0, v44, vcc
	v_cvt_pk_bf16_f32 v6, v7, v6
	v_mul_u32_u24_e32 v7, 0x110, v23
	v_add3_u32 v7, s15, v7, v33
	ds_write_b16 v7, v27 offset:34816
	v_cvt_pk_bf16_f32 v7, v43, s0
	ds_write_b16 v26, v7 offset:34816
	v_cvt_pk_bf16_f32 v7, v46, v47
	v_cmp_le_u32_e32 vcc, v23, v31
	s_nop 1
	v_cndmask_b32_e32 v23, 0, v7, vcc
	v_lshrrev_b32_e32 v7, 16, v7
	v_cmp_le_u32_e32 vcc, v22, v31
	s_nop 1
	v_cndmask_b32_e32 v7, 0, v7, vcc
	v_perm_b32 v7, v7, v23, s19
	v_cmp_gt_u32_e32 vcc, v31, v60
	ds_write_b64 v0, v[6:7] offset:96
	s_nop 0
	v_cndmask_b32_e32 v6, 0, v19, vcc
	v_cmp_le_u32_e32 vcc, v60, v31
	s_nop 1
	v_cndmask_b32_e32 v7, 0, v18, vcc
	v_cvt_pk_bf16_f32 v6, v7, v6
	v_mul_u32_u24_e32 v7, 0x110, v48
	v_add3_u32 v7, s15, v7, v33
	v_mul_u32_u24_e32 v18, 0x110, v35
	v_add3_u32 v18, s15, v18, v33
	ds_write_b16 v7, v9 offset:34816
	v_cvt_pk_bf16_f32 v7, v58, s0
	ds_write_b16 v18, v7 offset:34816
	v_cvt_pk_bf16_f32 v7, v20, v21
	v_cmp_le_u32_e32 vcc, v48, v31
	s_nop 1
	v_cndmask_b32_e32 v8, 0, v7, vcc
	v_lshrrev_b32_e32 v7, 16, v7
	v_cmp_le_u32_e32 vcc, v35, v31
	s_nop 1
	v_cndmask_b32_e32 v7, 0, v7, vcc
	v_perm_b32 v7, v7, v8, s19
	v_cmp_gt_u32_e32 vcc, v31, v29
	ds_write_b64 v0, v[6:7] offset:104
	v_mul_u32_u24_e32 v8, 0x110, v49
	v_cndmask_b32_e32 v6, 0, v37, vcc
	v_cmp_le_u32_e32 vcc, v29, v31
	v_add3_u32 v8, s15, v8, v33
	s_nop 0
	v_cndmask_b32_e32 v7, 0, v36, vcc
	v_cvt_pk_bf16_f32 v6, v7, v6
	v_mul_u32_u24_e32 v7, 0x110, v52
	v_add3_u32 v7, s15, v7, v33
	ds_write_b16 v7, v2 offset:34816
	v_cvt_pk_bf16_f32 v2, v65, s0
	ds_write_b16 v8, v2 offset:34816
	v_cvt_pk_bf16_f32 v2, v38, v39
	v_cmp_le_u32_e32 vcc, v52, v31
	s_nop 1
	v_cndmask_b32_e32 v3, 0, v2, vcc
	v_lshrrev_b32_e32 v2, 16, v2
	v_cmp_le_u32_e32 vcc, v49, v31
	s_nop 1
	v_cndmask_b32_e32 v2, 0, v2, vcc
	v_cmp_gt_u32_e32 vcc, v31, v28
	v_perm_b32 v7, v2, v3, s19
	ds_write_b64 v0, v[6:7] offset:112
	v_cndmask_b32_e32 v2, 0, v15, vcc
	v_cmp_le_u32_e32 vcc, v28, v31
	v_mul_u32_u24_e32 v6, 0x110, v10
	v_add3_u32 v6, s15, v6, v33
	v_cndmask_b32_e32 v3, 0, v14, vcc
	v_cvt_pk_bf16_f32 v2, v3, v2
	v_mul_u32_u24_e32 v3, 0x110, v11
	v_add3_u32 v3, s15, v3, v33
	ds_write_b16 v3, v5 offset:34816
	v_cvt_pk_bf16_f32 v3, v25, s0
	ds_write_b16 v6, v3 offset:34816
	v_cvt_pk_bf16_f32 v3, v16, v17
	v_cmp_le_u32_e32 vcc, v11, v31
	v_mul_u32_u24_e32 v7, 0x88, v81
	v_lshlrev_b32_e32 v81, 2, v81
	v_cndmask_b32_e32 v4, 0, v3, vcc
	v_lshrrev_b32_e32 v3, 16, v3
	v_cmp_le_u32_e32 vcc, v10, v31
	s_nop 1
	v_cndmask_b32_e32 v3, 0, v3, vcc
	v_perm_b32 v3, v3, v4, s19
	ds_write_b64 v0, v[2:3] offset:120
	v_bfe_u32 v0, v50, 4, 2
	v_and_b32_e32 v2, 0x4f, v50
	v_lshl_add_u32 v6, v0, 4, s15
	v_mul_u32_u24_e32 v2, 0x88, v2
	v_lshl_add_u32 v51, v2, 1, v6
	s_waitcnt lgkmcnt(0)
	s_barrier
	ds_read_b128 v[2:5], v51 offset:34816
	ds_read_b128 v[72:75], v51 offset:34880
	ds_read_b128 v[14:17], v51 offset:39168
	ds_read_b128 v[76:79], v51 offset:39232
	ds_read_b128 v[22:25], v51 offset:43520
	ds_read_b128 v[84:87], v51 offset:43584
	ds_read_b128 v[30:33], v51 offset:47872
	ds_read_b128 v[88:91], v51 offset:47936
	v_lshl_add_u32 v83, v7, 1, v6
	ds_read_b128 v[6:9], v83
	ds_read_b128 v[34:37], v83 offset:4352
	ds_read_b128 v[52:55], v83 offset:8704
	ds_read_b128 v[68:71], v83 offset:13056
	s_waitcnt lgkmcnt(3)
	v_mfma_f32_16x16x32_bf16 v[10:13], v[2:5], v[6:9], 0
	ds_read_b128 v[100:103], v51 offset:48000
	v_and_b32_e32 v50, 64, v50
	v_mfma_f32_16x16x32_bf16 v[18:21], v[14:17], v[6:9], 0
	v_mfma_f32_16x16x32_bf16 v[26:29], v[22:25], v[6:9], 0
	v_mfma_f32_16x16x32_bf16 v[6:9], v[30:33], v[6:9], 0
	s_waitcnt lgkmcnt(3)
	v_mfma_f32_16x16x32_bf16 v[38:41], v[2:5], v[34:37], 0
	v_mfma_f32_16x16x32_bf16 v[42:45], v[14:17], v[34:37], 0
	v_mfma_f32_16x16x32_bf16 v[46:49], v[22:25], v[34:37], 0
	v_mfma_f32_16x16x32_bf16 v[34:37], v[30:33], v[34:37], 0
	s_waitcnt lgkmcnt(2)
	v_mfma_f32_16x16x32_bf16 v[56:59], v[2:5], v[52:55], 0
	v_mfma_f32_16x16x32_bf16 v[60:63], v[14:17], v[52:55], 0
	v_mfma_f32_16x16x32_bf16 v[64:67], v[22:25], v[52:55], 0
	v_mfma_f32_16x16x32_bf16 v[52:55], v[30:33], v[52:55], 0
	s_waitcnt lgkmcnt(1)
	v_mfma_f32_16x16x32_bf16 v[2:5], v[2:5], v[68:71], 0
	v_mfma_f32_16x16x32_bf16 v[14:17], v[14:17], v[68:71], 0
	v_mfma_f32_16x16x32_bf16 v[22:25], v[22:25], v[68:71], 0
	v_mfma_f32_16x16x32_bf16 v[30:33], v[30:33], v[68:71], 0
	ds_read_b128 v[68:71], v83 offset:64
	s_waitcnt lgkmcnt(0)
	v_mfma_f32_16x16x32_bf16 v[10:13], v[72:75], v[68:71], v[10:13]
	v_mfma_f32_16x16x32_bf16 v[18:21], v[76:79], v[68:71], v[18:21]
	v_mfma_f32_16x16x32_bf16 v[26:29], v[84:87], v[68:71], v[26:29]
	v_mfma_f32_16x16x32_bf16 v[6:9], v[88:91], v[68:71], v[6:9]
	ds_read_b128 v[68:71], v83 offset:4416
	s_waitcnt lgkmcnt(0)
	v_mfma_f32_16x16x32_bf16 v[38:41], v[72:75], v[68:71], v[38:41]
	v_mfma_f32_16x16x32_bf16 v[42:45], v[76:79], v[68:71], v[42:45]
	v_mfma_f32_16x16x32_bf16 v[46:49], v[84:87], v[68:71], v[46:49]
	v_mfma_f32_16x16x32_bf16 v[34:37], v[88:91], v[68:71], v[34:37]
	ds_read_b128 v[68:71], v83 offset:8768
	s_waitcnt lgkmcnt(0)
	v_mfma_f32_16x16x32_bf16 v[92:95], v[76:79], v[68:71], v[60:63]
	s_nop 2
	ds_read_b128 v[60:63], v83 offset:13120
	v_mfma_f32_16x16x32_bf16 v[56:59], v[72:75], v[68:71], v[56:59]
	v_mfma_f32_16x16x32_bf16 v[96:99], v[84:87], v[68:71], v[64:67]
	v_mfma_f32_16x16x32_bf16 v[52:55], v[88:91], v[68:71], v[52:55]
	s_nop 1
	ds_read_b128 v[66:69], v51 offset:34944
	s_waitcnt lgkmcnt(1)
	v_mfma_f32_16x16x32_bf16 v[2:5], v[72:75], v[60:63], v[2:5]
	v_mfma_f32_16x16x32_bf16 v[70:73], v[88:91], v[60:63], v[30:33]
	s_nop 2
	ds_read_b128 v[30:33], v83 offset:128
	v_mfma_f32_16x16x32_bf16 v[14:17], v[76:79], v[60:63], v[14:17]
	s_waitcnt lgkmcnt(0)
	v_mfma_f32_16x16x32_bf16 v[74:77], v[66:69], v[30:33], v[10:13]
	s_nop 2
	ds_read_b128 v[10:13], v51 offset:39296
	v_mfma_f32_16x16x32_bf16 v[22:25], v[84:87], v[60:63], v[22:25]
	v_mfma_f32_16x16x32_bf16 v[104:107], v[100:103], v[30:33], v[6:9]
	s_nop 2
	ds_read_b128 v[6:9], v83 offset:4480
	s_waitcnt lgkmcnt(1)
	v_mfma_f32_16x16x32_bf16 v[84:87], v[10:13], v[30:33], v[18:21]
	s_nop 2
	ds_read_b128 v[18:21], v51 offset:43648
	s_waitcnt lgkmcnt(1)
	v_mfma_f32_16x16x32_bf16 v[108:111], v[66:69], v[6:9], v[38:41]
	v_mfma_f32_16x16x32_bf16 v[112:115], v[10:13], v[6:9], v[42:45]
	s_waitcnt lgkmcnt(0)
	v_mfma_f32_16x16x32_bf16 v[116:119], v[18:21], v[6:9], v[46:49]
	v_mfma_f32_16x16x32_bf16 v[62:65], v[100:103], v[6:9], v[34:37]
	ds_read_b128 v[6:9], v83 offset:8832
	s_waitcnt lgkmcnt(0)
	v_mfma_f32_16x16x32_bf16 v[42:45], v[100:103], v[6:9], v[52:55]
	s_nop 2
	ds_read_b128 v[52:55], v83 offset:13184
	v_mfma_f32_16x16x32_bf16 v[88:91], v[18:21], v[30:33], v[26:29]
	ds_read_b128 v[30:33], v51 offset:35008
	v_mfma_f32_16x16x32_bf16 v[46:49], v[18:21], v[6:9], v[96:99]
	s_waitcnt lgkmcnt(1)
	v_mfma_f32_16x16x32_bf16 v[26:29], v[66:69], v[52:55], v[2:5]
	v_mfma_f32_16x16x32_bf16 v[2:5], v[18:21], v[52:55], v[22:25]
	ds_read_b128 v[18:21], v51 offset:39360
	v_mfma_f32_16x16x32_bf16 v[38:41], v[66:69], v[6:9], v[56:59]
	v_mfma_f32_16x16x32_bf16 v[34:37], v[10:13], v[6:9], v[92:95]
	v_mfma_f32_16x16x32_bf16 v[6:9], v[10:13], v[52:55], v[14:17]
	v_mfma_f32_16x16x32_bf16 v[10:13], v[100:103], v[52:55], v[70:73]
	ds_read_b128 v[52:55], v83 offset:192
	ds_read_b128 v[22:25], v51 offset:43712
	ds_read_b128 v[14:17], v51 offset:48064
	v_lshlrev_b32_e32 v70, 3, v0
	v_lshlrev_b32_e32 v0, 1, v50
	v_lshl_add_u64 v[50:51], s[6:7], 0, v[0:1]
	v_mov_b32_e32 v71, v1
	s_waitcnt lgkmcnt(2)
	v_mfma_f32_16x16x32_bf16 v[92:95], v[30:33], v[52:55], v[74:77]
	ds_read_b128 v[100:103], v83 offset:4544
	s_nop 1
	v_lshl_add_u64 v[74:75], v[50:51], 0, v[70:71]
	v_mad_u64_u32 v[72:73], s[0:1], v82, s3, v[74:75]
	v_mfma_f32_16x16x32_bf16 v[96:99], v[18:21], v[52:55], v[84:87]
	s_lshl_b64 s[0:1], s[88:89], 2
	s_add_u32 s12, s42, s0
	s_addc_u32 s13, s43, s1
	s_waitcnt lgkmcnt(2)
	v_mfma_f32_16x16x32_bf16 v[86:89], v[22:25], v[52:55], v[88:91]
	global_load_dword v85, v81, s[12:13]
	v_or_b32_e32 v84, 16, v82
	v_mad_u64_u32 v[78:79], s[0:1], v84, s3, v[74:75]
	global_load_dwordx2 v[90:91], v[72:73], off
	s_waitcnt lgkmcnt(1)
	v_mfma_f32_16x16x32_bf16 v[66:69], v[14:17], v[52:55], v[104:107]
	s_cmpk_gt_u32 s10, 0xff
	s_waitcnt vmcnt(1)
	v_add_f32_e32 v87, v87, v85
	global_load_dwordx2 v[104:105], v[72:73], off offset:32
	s_waitcnt lgkmcnt(0)
	v_mfma_f32_16x16x32_bf16 v[58:61], v[30:33], v[100:103], v[108:111]
	global_load_dwordx2 v[106:107], v[72:73], off offset:64
	s_nop 1
	global_load_dwordx2 v[108:109], v[72:73], off offset:96
	s_waitcnt vmcnt(3)
	v_lshlrev_b32_e32 v72, 16, v90
	v_mul_f32_e32 v73, v72, v72
	v_and_b32_e32 v90, 0xffff0000, v90
	v_fmamk_f32 v73, v73, 0xbdd2d3e7, v129
	v_mul_f32_e32 v76, v90, v90
	v_mul_f32_e32 v73, v73, v72
	v_fmamk_f32 v76, v76, 0xbdd2d3e7, v129
	v_mul_f32_e32 v76, v76, v90
	v_exp_f32_e32 v73, v73
	v_exp_f32_e32 v110, v76
	v_add_f32_e32 v86, v86, v85
	v_add_f32_e32 v73, 1.0, v73
	v_rcp_f32_e32 v73, v73
	v_add_f32_e32 v110, 1.0, v110
	v_rcp_f32_e32 v110, v110
	v_add_f32_e32 v88, v88, v85
	v_mul_f32_e32 v72, v73, v72
	v_add_f32_e32 v73, v92, v85
	v_mul_f32_e32 v72, v72, v73
	v_mul_f32_e32 v73, v110, v90
	v_add_f32_e32 v90, v93, v85
	v_lshlrev_b32_e32 v92, 16, v91
	v_mul_f32_e32 v73, v73, v90
	v_mul_f32_e32 v90, v92, v92
	v_and_b32_e32 v91, 0xffff0000, v91
	v_fmamk_f32 v90, v90, 0xbdd2d3e7, v129
	v_mul_f32_e32 v93, v91, v91
	v_mul_f32_e32 v90, v90, v92
	v_fmamk_f32 v93, v93, 0xbdd2d3e7, v129
	v_mul_f32_e32 v93, v93, v91
	v_exp_f32_e32 v90, v90
	v_exp_f32_e32 v93, v93
	v_add_f32_e32 v89, v89, v85
	v_add_f32_e32 v90, 1.0, v90
	v_rcp_f32_e32 v110, v90
	v_cvt_pk_bf16_f32 v90, v72, v73
	v_add_f32_e32 v72, 1.0, v93
	v_rcp_f32_e32 v72, v72
	v_mul_f32_e32 v73, v110, v92
	v_add_f32_e32 v92, v94, v85
	v_mul_f32_e32 v73, v73, v92
	v_mul_f32_e32 v72, v72, v91
	v_add_f32_e32 v91, v95, v85
	v_mul_f32_e32 v72, v72, v91
	v_cvt_pk_bf16_f32 v91, v73, v72
	v_mov_b64_e32 v[72:73], s[50:51]
	v_mad_u64_u32 v[92:93], s[0:1], v82, s3, v[72:73]
	v_lshl_add_u64 v[92:93], v[92:93], 0, s[8:9]
	v_lshl_add_u64 v[92:93], v[92:93], 0, v[0:1]
	v_lshl_add_u64 v[92:93], v[92:93], 0, v[70:71]
	global_store_dwordx2 v[92:93], v[90:91], off
	v_add_f32_e32 v67, v67, v85
	v_add_f32_e32 v66, v66, v85
	global_load_dwordx2 v[76:77], v[78:79], off
	v_add_f32_e32 v68, v68, v85
	v_add_f32_e32 v69, v69, v85
	v_mfma_f32_16x16x32_bf16 v[54:57], v[18:21], v[100:103], v[112:115]
	s_waitcnt vmcnt(4)
	v_lshlrev_b32_e32 v94, 16, v104
	v_mul_f32_e32 v95, v94, v94
	v_and_b32_e32 v104, 0xffff0000, v104
	v_fmamk_f32 v95, v95, 0xbdd2d3e7, v129
	v_mul_f32_e32 v110, v104, v104
	v_mul_f32_e32 v95, v95, v94
	v_fmamk_f32 v110, v110, 0xbdd2d3e7, v129
	v_mul_f32_e32 v110, v110, v104
	v_exp_f32_e32 v95, v95
	v_exp_f32_e32 v110, v110
	v_mfma_f32_16x16x32_bf16 v[50:53], v[22:25], v[100:103], v[116:119]
	v_add_f32_e32 v95, 1.0, v95
	v_rcp_f32_e32 v95, v95
	v_add_f32_e32 v90, 1.0, v110
	v_rcp_f32_e32 v90, v90
	v_mfma_f32_16x16x32_bf16 v[62:65], v[14:17], v[100:103], v[62:65]
	v_mul_f32_e32 v91, v95, v94
	v_add_f32_e32 v94, v96, v85
	v_mul_f32_e32 v91, v91, v94
	v_mul_f32_e32 v90, v90, v104
	v_add_f32_e32 v94, v97, v85
	v_mul_f32_e32 v90, v90, v94
	v_lshlrev_b32_e32 v94, 16, v105
	v_mul_f32_e32 v95, v94, v94
	v_and_b32_e32 v96, 0xffff0000, v105
	v_fmamk_f32 v95, v95, 0xbdd2d3e7, v129
	v_mul_f32_e32 v97, v96, v96
	v_mul_f32_e32 v95, v95, v94
	v_fmamk_f32 v97, v97, 0xbdd2d3e7, v129
	v_mul_f32_e32 v97, v97, v96
	v_exp_f32_e32 v95, v95
	v_exp_f32_e32 v97, v97
	v_cvt_pk_bf16_f32 v90, v91, v90
	v_add_f32_e32 v95, 1.0, v95
	v_rcp_f32_e32 v95, v95
	v_add_f32_e32 v91, 1.0, v97
	v_rcp_f32_e32 v91, v91
	v_mul_f32_e32 v94, v95, v94
	v_add_f32_e32 v95, v98, v85
	v_mul_f32_e32 v94, v94, v95
	v_mul_f32_e32 v91, v91, v96
	v_add_f32_e32 v95, v99, v85
	v_mul_f32_e32 v91, v91, v95
	s_waitcnt vmcnt(3)
	v_and_b32_e32 v96, 0xffff0000, v106
	v_cvt_pk_bf16_f32 v91, v94, v91
	v_lshlrev_b32_e32 v94, 16, v106
	v_mul_f32_e32 v97, v96, v96
	v_mul_f32_e32 v95, v94, v94
	v_fmamk_f32 v97, v97, 0xbdd2d3e7, v129
	v_fmamk_f32 v95, v95, 0xbdd2d3e7, v129
	v_mul_f32_e32 v97, v97, v96
	v_mul_f32_e32 v95, v95, v94
	v_exp_f32_e32 v97, v97
	v_exp_f32_e32 v95, v95
	global_store_dwordx2 v[92:93], v[90:91], off offset:32
	v_add_f32_e32 v90, 1.0, v97
	v_add_f32_e32 v95, 1.0, v95
	v_rcp_f32_e32 v90, v90
	v_rcp_f32_e32 v95, v95
	v_mul_f32_e32 v90, v90, v96
	v_mul_f32_e32 v91, v95, v94
	v_mul_f32_e32 v87, v90, v87
	v_lshlrev_b32_e32 v90, 16, v107
	v_and_b32_e32 v94, 0xffff0000, v107
	v_mul_f32_e32 v86, v91, v86
	v_mul_f32_e32 v91, v90, v90
	v_mul_f32_e32 v95, v94, v94
	v_fmamk_f32 v91, v91, 0xbdd2d3e7, v129
	v_fmamk_f32 v95, v95, 0xbdd2d3e7, v129
	v_mul_f32_e32 v91, v91, v90
	v_mul_f32_e32 v95, v95, v94
	v_exp_f32_e32 v91, v91
	v_exp_f32_e32 v95, v95
	v_cvt_pk_bf16_f32 v86, v86, v87
	v_add_f32_e32 v91, 1.0, v91
	v_add_f32_e32 v87, 1.0, v95
	v_rcp_f32_e32 v91, v91
	v_rcp_f32_e32 v87, v87
	v_mul_f32_e32 v90, v91, v90
	v_mul_f32_e32 v87, v87, v94
	v_mul_f32_e32 v88, v90, v88
	v_mul_f32_e32 v87, v87, v89
	s_waitcnt vmcnt(3)
	v_and_b32_e32 v90, 0xffff0000, v108
	v_cvt_pk_bf16_f32 v87, v88, v87
	v_lshlrev_b32_e32 v88, 16, v108
	v_mul_f32_e32 v91, v90, v90
	v_mul_f32_e32 v89, v88, v88
	v_fmamk_f32 v91, v91, 0xbdd2d3e7, v129
	v_fmamk_f32 v89, v89, 0xbdd2d3e7, v129
	v_mul_f32_e32 v91, v91, v90
	v_mul_f32_e32 v89, v89, v88
	v_exp_f32_e32 v91, v91
	v_exp_f32_e32 v89, v89
	global_store_dwordx2 v[92:93], v[86:87], off offset:64
	v_add_f32_e32 v86, 1.0, v91
	v_add_f32_e32 v89, 1.0, v89
	v_rcp_f32_e32 v86, v86
	v_rcp_f32_e32 v89, v89
	v_mul_f32_e32 v86, v86, v90
	v_mul_f32_e32 v87, v89, v88
	v_mul_f32_e32 v67, v86, v67
	v_lshlrev_b32_e32 v86, 16, v109
	v_and_b32_e32 v88, 0xffff0000, v109
	v_mul_f32_e32 v66, v87, v66
	v_mul_f32_e32 v87, v86, v86
	v_mul_f32_e32 v89, v88, v88
	v_fmamk_f32 v87, v87, 0xbdd2d3e7, v129
	v_fmamk_f32 v89, v89, 0xbdd2d3e7, v129
	v_mul_f32_e32 v87, v87, v86
	v_mul_f32_e32 v89, v89, v88
	v_exp_f32_e32 v87, v87
	v_exp_f32_e32 v89, v89
	v_cvt_pk_bf16_f32 v66, v66, v67
	global_load_dwordx2 v[90:91], v[78:79], off offset:32
	v_add_f32_e32 v87, 1.0, v87
	v_add_f32_e32 v67, 1.0, v89
	v_rcp_f32_e32 v87, v87
	v_rcp_f32_e32 v67, v67
	v_mul_f32_e32 v86, v87, v86
	v_mul_f32_e32 v67, v67, v88
	v_mul_f32_e32 v68, v68, v86
	v_mul_f32_e32 v67, v69, v67
	v_cvt_pk_bf16_f32 v67, v68, v67
	global_store_dwordx2 v[92:93], v[66:67], off offset:96
	global_load_dword v85, v81, s[12:13] offset:64
	ds_read_b128 v[86:89], v83 offset:8896
	global_load_dwordx2 v[92:93], v[78:79], off offset:64
	global_load_dwordx2 v[94:95], v[78:79], off offset:96
	s_waitcnt vmcnt(7)
	v_lshlrev_b32_e32 v79, 16, v76
	v_and_b32_e32 v76, 0xffff0000, v76
	v_mul_f32_e32 v67, v76, v76
	v_mul_f32_e32 v66, v79, v79
	v_fmamk_f32 v67, v67, 0xbdd2d3e7, v129
	v_fmamk_f32 v66, v66, 0xbdd2d3e7, v129
	v_mul_f32_e32 v67, v67, v76
	v_mul_f32_e32 v66, v66, v79
	v_exp_f32_e32 v96, v67
	v_exp_f32_e32 v66, v66
	v_or_b32_e32 v78, 32, v82
	v_mad_u64_u32 v[68:69], s[0:1], v78, s3, v[74:75]
	v_add_f32_e32 v96, 1.0, v96
	v_add_f32_e32 v66, 1.0, v66
	v_rcp_f32_e32 v96, v96
	v_rcp_f32_e32 v97, v66
	global_load_dwordx2 v[66:67], v[68:69], off
	s_waitcnt lgkmcnt(0)
	v_mfma_f32_16x16x32_bf16 v[38:41], v[30:33], v[86:89], v[38:41]
	v_mul_f32_e32 v76, v96, v76
	v_mul_f32_e32 v79, v97, v79
	s_waitcnt vmcnt(3)
	v_add_f32_e32 v59, v59, v85
	v_add_f32_e32 v58, v58, v85
	v_mul_f32_e32 v59, v76, v59
	v_lshlrev_b32_e32 v76, 16, v77
	v_and_b32_e32 v77, 0xffff0000, v77
	v_mul_f32_e32 v58, v79, v58
	v_mul_f32_e32 v79, v76, v76
	v_mul_f32_e32 v96, v77, v77
	v_fmamk_f32 v79, v79, 0xbdd2d3e7, v129
	v_fmamk_f32 v96, v96, 0xbdd2d3e7, v129
	v_mul_f32_e32 v79, v79, v76
	v_mul_f32_e32 v96, v96, v77
	v_exp_f32_e32 v79, v79
	v_exp_f32_e32 v96, v96
	v_cvt_pk_bf16_f32 v58, v58, v59
	v_add_f32_e32 v60, v60, v85
	v_add_f32_e32 v79, 1.0, v79
	v_add_f32_e32 v59, 1.0, v96
	v_rcp_f32_e32 v79, v79
	v_rcp_f32_e32 v59, v59
	v_add_f32_e32 v61, v61, v85
	v_add_f32_e32 v55, v55, v85
	v_mul_f32_e32 v76, v79, v76
	v_mul_f32_e32 v59, v59, v77
	v_mul_f32_e32 v60, v76, v60
	v_mul_f32_e32 v59, v59, v61
	v_and_b32_e32 v79, 0xffff0000, v90
	v_cvt_pk_bf16_f32 v59, v60, v59
	v_mad_u64_u32 v[60:61], s[0:1], v84, s3, v[72:73]
	v_lshlrev_b32_e32 v76, 16, v90
	v_mul_f32_e32 v84, v79, v79
	v_mul_f32_e32 v77, v76, v76
	v_fmamk_f32 v84, v84, 0xbdd2d3e7, v129
	v_fmamk_f32 v77, v77, 0xbdd2d3e7, v129
	v_mul_f32_e32 v84, v84, v79
	v_mul_f32_e32 v77, v77, v76
	v_exp_f32_e32 v84, v84
	v_lshl_add_u64 v[60:61], v[60:61], 0, s[8:9]
	v_exp_f32_e32 v77, v77
	v_lshl_add_u64 v[60:61], v[60:61], 0, v[0:1]
	v_lshl_add_u64 v[60:61], v[60:61], 0, v[70:71]
	global_store_dwordx2 v[60:61], v[58:59], off
	v_add_f32_e32 v58, 1.0, v84
	v_add_f32_e32 v77, 1.0, v77
	v_rcp_f32_e32 v58, v58
	v_rcp_f32_e32 v77, v77
	v_add_f32_e32 v54, v54, v85
	v_add_f32_e32 v56, v56, v85
	v_mul_f32_e32 v58, v58, v79
	v_mul_f32_e32 v59, v77, v76
	v_mul_f32_e32 v55, v58, v55
	v_lshlrev_b32_e32 v58, 16, v91
	v_and_b32_e32 v76, 0xffff0000, v91
	v_mul_f32_e32 v54, v59, v54
	v_mul_f32_e32 v59, v58, v58
	v_mul_f32_e32 v77, v76, v76
	v_fmamk_f32 v59, v59, 0xbdd2d3e7, v129
	v_fmamk_f32 v77, v77, 0xbdd2d3e7, v129
	v_mul_f32_e32 v59, v59, v58
	v_mul_f32_e32 v77, v77, v76
	v_exp_f32_e32 v59, v59
	v_exp_f32_e32 v77, v77
	v_cvt_pk_bf16_f32 v54, v54, v55
	v_add_f32_e32 v57, v57, v85
	v_add_f32_e32 v59, 1.0, v59
	v_add_f32_e32 v55, 1.0, v77
	v_rcp_f32_e32 v59, v59
	v_rcp_f32_e32 v55, v55
	v_add_f32_e32 v51, v51, v85
	v_add_f32_e32 v50, v50, v85
	v_mul_f32_e32 v58, v59, v58
	v_mul_f32_e32 v55, v55, v76
	v_mul_f32_e32 v56, v58, v56
	v_mul_f32_e32 v55, v55, v57
	s_waitcnt vmcnt(3)
	v_and_b32_e32 v58, 0xffff0000, v92
	v_cvt_pk_bf16_f32 v55, v56, v55
	v_lshlrev_b32_e32 v56, 16, v92
	v_mul_f32_e32 v59, v58, v58
	v_mul_f32_e32 v57, v56, v56
	v_fmamk_f32 v59, v59, 0xbdd2d3e7, v129
	v_fmamk_f32 v57, v57, 0xbdd2d3e7, v129
	v_mul_f32_e32 v59, v59, v58
	v_mul_f32_e32 v57, v57, v56
	v_exp_f32_e32 v59, v59
	v_exp_f32_e32 v57, v57
	global_store_dwordx2 v[60:61], v[54:55], off offset:32
	v_add_f32_e32 v52, v52, v85
	v_add_f32_e32 v54, 1.0, v59
	v_add_f32_e32 v57, 1.0, v57
	v_rcp_f32_e32 v54, v54
	v_rcp_f32_e32 v57, v57
	v_add_f32_e32 v53, v53, v85
	v_mfma_f32_16x16x32_bf16 v[34:37], v[18:21], v[86:89], v[34:37]
	v_mul_f32_e32 v54, v54, v58
	v_mul_f32_e32 v55, v57, v56
	v_mul_f32_e32 v51, v54, v51
	v_lshlrev_b32_e32 v54, 16, v93
	v_and_b32_e32 v56, 0xffff0000, v93
	v_mul_f32_e32 v50, v55, v50
	v_mul_f32_e32 v55, v54, v54
	v_mul_f32_e32 v57, v56, v56
	v_fmamk_f32 v55, v55, 0xbdd2d3e7, v129
	v_fmamk_f32 v57, v57, 0xbdd2d3e7, v129
	v_mul_f32_e32 v55, v55, v54
	v_mul_f32_e32 v57, v57, v56
	v_exp_f32_e32 v55, v55
	v_exp_f32_e32 v57, v57
	v_cvt_pk_bf16_f32 v50, v50, v51
	v_mfma_f32_16x16x32_bf16 v[46:49], v[22:25], v[86:89], v[46:49]
	v_add_f32_e32 v55, 1.0, v55
	v_add_f32_e32 v51, 1.0, v57
	v_rcp_f32_e32 v55, v55
	v_rcp_f32_e32 v51, v51
	v_mfma_f32_16x16x32_bf16 v[42:45], v[14:17], v[86:89], v[42:45]
	v_or_b32_e32 v57, 48, v82
	v_mul_f32_e32 v54, v55, v54
	v_mul_f32_e32 v51, v51, v56
	v_mul_f32_e32 v52, v54, v52
	v_mul_f32_e32 v51, v51, v53
	v_cvt_pk_bf16_f32 v51, v52, v51
	s_waitcnt vmcnt(3)
	v_lshlrev_b32_e32 v52, 16, v94
	v_mul_f32_e32 v53, v52, v52
	v_and_b32_e32 v54, 0xffff0000, v94
	v_fmamk_f32 v53, v53, 0xbdd2d3e7, v129
	v_mul_f32_e32 v55, v54, v54
	v_mul_f32_e32 v53, v53, v52
	v_fmamk_f32 v55, v55, 0xbdd2d3e7, v129
	v_mul_f32_e32 v55, v55, v54
	v_exp_f32_e32 v53, v53
	v_exp_f32_e32 v55, v55
	global_store_dwordx2 v[60:61], v[50:51], off offset:64
	v_add_f32_e32 v53, 1.0, v53
	v_rcp_f32_e32 v53, v53
	v_add_f32_e32 v50, 1.0, v55
	v_rcp_f32_e32 v50, v50
	v_mul_f32_e32 v51, v53, v52
	v_add_f32_e32 v52, v62, v85
	v_mul_f32_e32 v51, v51, v52
	v_mul_f32_e32 v50, v50, v54
	v_add_f32_e32 v52, v63, v85
	v_mul_f32_e32 v50, v50, v52
	v_lshlrev_b32_e32 v52, 16, v95
	v_mul_f32_e32 v53, v52, v52
	v_and_b32_e32 v54, 0xffff0000, v95
	v_fmamk_f32 v53, v53, 0xbdd2d3e7, v129
	v_mul_f32_e32 v55, v54, v54
	v_mul_f32_e32 v53, v53, v52
	v_fmamk_f32 v55, v55, 0xbdd2d3e7, v129
	v_mul_f32_e32 v55, v55, v54
	v_exp_f32_e32 v53, v53
	v_exp_f32_e32 v55, v55
	v_cvt_pk_bf16_f32 v50, v51, v50
	v_add_f32_e32 v53, 1.0, v53
	v_rcp_f32_e32 v53, v53
	v_add_f32_e32 v51, 1.0, v55
	v_rcp_f32_e32 v51, v51
	v_mul_f32_e32 v52, v53, v52
	v_add_f32_e32 v53, v64, v85
	v_mul_f32_e32 v52, v52, v53
	v_mul_f32_e32 v51, v51, v54
	v_add_f32_e32 v53, v65, v85
	v_mul_f32_e32 v51, v51, v53
	v_cvt_pk_bf16_f32 v51, v52, v51
	global_store_dwordx2 v[60:61], v[50:51], off offset:96
	global_load_dword v56, v81, s[12:13] offset:128
	global_load_dwordx2 v[54:55], v[68:69], off offset:32
	ds_read_b128 v[50:53], v83 offset:13248
	global_load_dwordx2 v[58:59], v[68:69], off offset:64
	global_load_dwordx2 v[60:61], v[68:69], off offset:96
	s_waitcnt vmcnt(8)
	v_lshlrev_b32_e32 v62, 16, v66
	s_waitcnt lgkmcnt(0)
	v_mfma_f32_16x16x32_bf16 v[26:29], v[30:33], v[50:53], v[26:29]
	v_mul_f32_e32 v30, v62, v62
	v_and_b32_e32 v63, 0xffff0000, v66
	v_fmamk_f32 v30, v30, 0xbdd2d3e7, v129
	v_mul_f32_e32 v31, v63, v63
	v_mul_f32_e32 v30, v30, v62
	v_fmamk_f32 v31, v31, 0xbdd2d3e7, v129
	v_mul_f32_e32 v31, v31, v63
	v_exp_f32_e32 v30, v30
	v_exp_f32_e32 v64, v31
	v_mad_u64_u32 v[32:33], s[0:1], v57, s3, v[74:75]
	v_add_f32_e32 v30, 1.0, v30
	v_rcp_f32_e32 v65, v30
	v_add_f32_e32 v64, 1.0, v64
	v_rcp_f32_e32 v64, v64
	global_load_dwordx2 v[30:31], v[32:33], off
	v_mul_f32_e32 v62, v65, v62
	v_mfma_f32_16x16x32_bf16 v[6:9], v[18:21], v[50:53], v[6:9]
	global_load_dwordx2 v[18:19], v[32:33], off offset:32
	s_waitcnt vmcnt(5)
	v_add_f32_e32 v38, v38, v56
	v_mul_f32_e32 v38, v62, v38
	v_mul_f32_e32 v62, v64, v63
	v_add_f32_e32 v39, v39, v56
	v_mul_f32_e32 v39, v62, v39
	v_lshlrev_b32_e32 v62, 16, v67
	v_mul_f32_e32 v63, v62, v62
	v_fmamk_f32 v63, v63, 0xbdd2d3e7, v129
	v_and_b32_e32 v64, 0xffff0000, v67
	v_mul_f32_e32 v63, v63, v62
	v_mul_f32_e32 v65, v64, v64
	v_fmamk_f32 v65, v65, 0xbdd2d3e7, v129
	v_mul_f32_e32 v65, v65, v64
	v_exp_f32_e32 v63, v63
	v_exp_f32_e32 v65, v65
	v_add_f32_e32 v63, 1.0, v63
	v_rcp_f32_e32 v63, v63
	v_cvt_pk_bf16_f32 v38, v38, v39
	v_add_f32_e32 v39, 1.0, v65
	v_rcp_f32_e32 v39, v39
	v_mul_f32_e32 v62, v63, v62
	v_add_f32_e32 v40, v40, v56
	v_mul_f32_e32 v40, v62, v40
	s_waitcnt vmcnt(4)
	v_lshlrev_b32_e32 v62, 16, v54
	v_and_b32_e32 v54, 0xffff0000, v54
	v_mul_f32_e32 v39, v39, v64
	v_mul_f32_e32 v64, v54, v54
	v_mul_f32_e32 v63, v62, v62
	v_fmamk_f32 v64, v64, 0xbdd2d3e7, v129
	v_fmamk_f32 v63, v63, 0xbdd2d3e7, v129
	v_mul_f32_e32 v64, v64, v54
	v_add_f32_e32 v41, v41, v56
	v_mul_f32_e32 v63, v63, v62
	v_mul_f32_e32 v39, v39, v41
	v_cvt_pk_bf16_f32 v39, v40, v39
	v_mad_u64_u32 v[40:41], s[0:1], v78, s3, v[72:73]
	v_exp_f32_e32 v64, v64
	v_lshl_add_u64 v[40:41], v[40:41], 0, s[8:9]
	v_exp_f32_e32 v63, v63
	v_lshl_add_u64 v[40:41], v[40:41], 0, v[0:1]
	v_lshl_add_u64 v[40:41], v[40:41], 0, v[70:71]
	global_store_dwordx2 v[40:41], v[38:39], off
	v_add_f32_e32 v38, 1.0, v64
	v_add_f32_e32 v63, 1.0, v63
	v_rcp_f32_e32 v38, v38
	v_rcp_f32_e32 v63, v63
	v_add_f32_e32 v35, v35, v56
	v_add_f32_e32 v34, v34, v56
	v_mul_f32_e32 v38, v38, v54
	v_mul_f32_e32 v39, v63, v62
	v_mul_f32_e32 v35, v38, v35
	v_lshlrev_b32_e32 v38, 16, v55
	v_and_b32_e32 v54, 0xffff0000, v55
	v_mul_f32_e32 v34, v39, v34
	v_mul_f32_e32 v39, v38, v38
	v_mul_f32_e32 v55, v54, v54
	v_fmamk_f32 v39, v39, 0xbdd2d3e7, v129
	v_fmamk_f32 v55, v55, 0xbdd2d3e7, v129
	v_mul_f32_e32 v39, v39, v38
	v_mul_f32_e32 v55, v55, v54
	v_exp_f32_e32 v39, v39
	v_exp_f32_e32 v55, v55
	v_cvt_pk_bf16_f32 v34, v34, v35
	v_add_f32_e32 v36, v36, v56
	v_add_f32_e32 v39, 1.0, v39
	v_add_f32_e32 v35, 1.0, v55
	v_rcp_f32_e32 v39, v39
	v_rcp_f32_e32 v35, v35
	v_add_f32_e32 v37, v37, v56
	v_mfma_f32_16x16x32_bf16 v[2:5], v[22:25], v[50:53], v[2:5]
	v_mul_f32_e32 v38, v39, v38
	v_mul_f32_e32 v35, v35, v54
	v_mul_f32_e32 v36, v38, v36
	v_mul_f32_e32 v35, v35, v37
	v_cvt_pk_bf16_f32 v35, v36, v35
	s_waitcnt vmcnt(4)
	v_lshlrev_b32_e32 v36, 16, v58
	v_mul_f32_e32 v37, v36, v36
	v_and_b32_e32 v38, 0xffff0000, v58
	v_fmamk_f32 v37, v37, 0xbdd2d3e7, v129
	v_mul_f32_e32 v39, v38, v38
	v_mul_f32_e32 v37, v37, v36
	v_fmamk_f32 v39, v39, 0xbdd2d3e7, v129
	v_mul_f32_e32 v39, v39, v38
	v_exp_f32_e32 v37, v37
	v_exp_f32_e32 v39, v39
	global_store_dwordx2 v[40:41], v[34:35], off offset:32
	v_add_f32_e32 v37, 1.0, v37
	v_rcp_f32_e32 v37, v37
	v_add_f32_e32 v34, 1.0, v39
	v_rcp_f32_e32 v34, v34
	s_waitcnt vmcnt(3)
	v_lshlrev_b32_e32 v24, 16, v30
	v_mul_f32_e32 v35, v37, v36
	v_add_f32_e32 v36, v46, v56
	v_mul_f32_e32 v35, v35, v36
	v_mul_f32_e32 v34, v34, v38
	v_add_f32_e32 v36, v47, v56
	v_mul_f32_e32 v34, v34, v36
	v_lshlrev_b32_e32 v36, 16, v59
	v_mul_f32_e32 v37, v36, v36
	v_and_b32_e32 v38, 0xffff0000, v59
	v_fmamk_f32 v37, v37, 0xbdd2d3e7, v129
	v_mul_f32_e32 v39, v38, v38
	v_mul_f32_e32 v37, v37, v36
	v_fmamk_f32 v39, v39, 0xbdd2d3e7, v129
	v_mul_f32_e32 v39, v39, v38
	v_exp_f32_e32 v37, v37
	v_exp_f32_e32 v39, v39
	v_cvt_pk_bf16_f32 v34, v35, v34
	v_add_f32_e32 v37, 1.0, v37
	v_rcp_f32_e32 v37, v37
	v_add_f32_e32 v35, 1.0, v39
	v_rcp_f32_e32 v35, v35
	v_mul_f32_e32 v25, 0x3d372713, v24
	v_mul_f32_e32 v36, v37, v36
	v_add_f32_e32 v37, v48, v56
	v_mul_f32_e32 v36, v36, v37
	v_mul_f32_e32 v35, v35, v38
	v_add_f32_e32 v37, v49, v56
	v_mul_f32_e32 v35, v35, v37
	v_cvt_pk_bf16_f32 v35, v36, v35
	v_lshlrev_b32_e32 v36, 16, v60
	v_mul_f32_e32 v37, v36, v36
	v_and_b32_e32 v38, 0xffff0000, v60
	v_fmamk_f32 v37, v37, 0xbdd2d3e7, v129
	v_mul_f32_e32 v39, v38, v38
	v_mul_f32_e32 v37, v37, v36
	v_fmamk_f32 v39, v39, 0xbdd2d3e7, v129
	v_mul_f32_e32 v39, v39, v38
	v_exp_f32_e32 v37, v37
	v_exp_f32_e32 v39, v39
	global_store_dwordx2 v[40:41], v[34:35], off offset:64
	v_add_f32_e32 v37, 1.0, v37
	v_rcp_f32_e32 v37, v37
	v_add_f32_e32 v34, 1.0, v39
	v_rcp_f32_e32 v34, v34
	v_and_b32_e32 v30, 0xffff0000, v30
	v_mul_f32_e32 v35, v37, v36
	v_add_f32_e32 v36, v42, v56
	v_mul_f32_e32 v35, v35, v36
	v_mul_f32_e32 v34, v34, v38
	v_add_f32_e32 v36, v43, v56
	v_mul_f32_e32 v34, v34, v36
	v_lshlrev_b32_e32 v36, 16, v61
	v_mul_f32_e32 v37, v36, v36
	v_and_b32_e32 v38, 0xffff0000, v61
	v_fmamk_f32 v37, v37, 0xbdd2d3e7, v129
	v_mul_f32_e32 v39, v38, v38
	v_mul_f32_e32 v37, v37, v36
	v_fmamk_f32 v39, v39, 0xbdd2d3e7, v129
	v_mul_f32_e32 v39, v39, v38
	v_exp_f32_e32 v37, v37
	v_exp_f32_e32 v39, v39
	v_cvt_pk_bf16_f32 v34, v35, v34
	v_add_f32_e32 v37, 1.0, v37
	v_rcp_f32_e32 v37, v37
	v_add_f32_e32 v35, 1.0, v39
	v_rcp_f32_e32 v35, v35
	v_mul_f32_e32 v25, v25, v24
	v_mul_f32_e32 v36, v37, v36
	v_add_f32_e32 v37, v44, v56
	v_mul_f32_e32 v36, v36, v37
	v_mul_f32_e32 v35, v35, v38
	v_add_f32_e32 v37, v45, v56
	v_mul_f32_e32 v35, v35, v37
	v_cvt_pk_bf16_f32 v35, v36, v35
	global_store_dwordx2 v[40:41], v[34:35], off offset:96
	global_load_dword v34, v81, s[12:13] offset:192
	s_nop 0
	global_load_dwordx2 v[20:21], v[32:33], off offset:64
	global_load_dwordx2 v[22:23], v[32:33], off offset:96
	v_mul_f32_e32 v32, v30, v30
	v_fma_f32 v25, v25, v24, v24
	v_fmamk_f32 v32, v32, 0xbdd2d3e7, v129
	v_mul_f32_e32 v25, 0xbfcc422a, v25
	v_mul_f32_e32 v32, v32, v30
	v_mul_f32_e32 v25, 0x3fb8aa3b, v25
	v_exp_f32_e32 v25, v25
	v_exp_f32_e32 v32, v32
	v_mfma_f32_16x16x32_bf16 v[10:13], v[14:17], v[50:53], v[10:13]
	v_add_f32_e32 v25, 1.0, v25
	v_rcp_f32_e32 v25, v25
	v_add_f32_e32 v14, 1.0, v32
	v_rcp_f32_e32 v14, v14
	v_mul_f32_e32 v15, v25, v24
	v_and_b32_e32 v24, 0xffff0000, v31
	v_mul_f32_e32 v14, v14, v30
	v_mul_f32_e32 v25, v24, v24
	v_fmamk_f32 v25, v25, 0xbdd2d3e7, v129
	v_mul_f32_e32 v25, v25, v24
	v_exp_f32_e32 v25, v25
	s_waitcnt vmcnt(2)
	v_add_f32_e32 v16, v26, v34
	v_mul_f32_e32 v15, v15, v16
	v_add_f32_e32 v16, v27, v34
	v_mul_f32_e32 v14, v14, v16
	v_lshlrev_b32_e32 v16, 16, v31
	v_mul_f32_e32 v17, v16, v16
	v_fmamk_f32 v17, v17, 0xbdd2d3e7, v129
	v_mul_f32_e32 v17, v17, v16
	v_exp_f32_e32 v17, v17
	v_cvt_pk_bf16_f32 v14, v15, v14
	v_add_f32_e32 v15, 1.0, v25
	v_rcp_f32_e32 v15, v15
	v_add_f32_e32 v17, 1.0, v17
	v_rcp_f32_e32 v17, v17
	v_add_f32_e32 v6, v6, v34
	v_mul_f32_e32 v15, v15, v24
	v_add_f32_e32 v7, v7, v34
	v_mul_f32_e32 v16, v17, v16
	v_add_f32_e32 v17, v28, v34
	v_mul_f32_e32 v16, v16, v17
	v_add_f32_e32 v17, v29, v34
	v_mul_f32_e32 v15, v15, v17
	v_cvt_pk_bf16_f32 v15, v16, v15
	v_mad_u64_u32 v[16:17], s[0:1], v57, s3, v[72:73]
	v_lshl_add_u64 v[16:17], v[16:17], 0, s[8:9]
	v_lshl_add_u64 v[16:17], v[16:17], 0, v[0:1]
	v_lshlrev_b32_e32 v0, 16, v18
	v_mul_f32_e32 v24, v0, v0
	v_and_b32_e32 v18, 0xffff0000, v18
	v_fmamk_f32 v24, v24, 0xbdd2d3e7, v129
	v_mul_f32_e32 v25, v18, v18
	v_mul_f32_e32 v24, v24, v0
	v_fmamk_f32 v25, v25, 0xbdd2d3e7, v129
	v_mul_f32_e32 v25, v25, v18
	v_exp_f32_e32 v24, v24
	v_exp_f32_e32 v25, v25
	v_lshl_add_u64 v[16:17], v[16:17], 0, v[70:71]
	v_add_f32_e32 v24, 1.0, v24
	v_rcp_f32_e32 v24, v24
	global_store_dwordx2 v[16:17], v[14:15], off
	v_add_f32_e32 v14, 1.0, v25
	v_rcp_f32_e32 v14, v14
	v_mul_f32_e32 v0, v24, v0
	v_mul_f32_e32 v0, v0, v6
	v_and_b32_e32 v15, 0xffff0000, v19
	v_mul_f32_e32 v6, v14, v18
	v_mul_f32_e32 v6, v6, v7
	v_lshlrev_b32_e32 v7, 16, v19
	v_mul_f32_e32 v14, v7, v7
	v_fmamk_f32 v14, v14, 0xbdd2d3e7, v129
	v_mul_f32_e32 v18, v15, v15
	v_mul_f32_e32 v14, v14, v7
	v_fmamk_f32 v18, v18, 0xbdd2d3e7, v129
	v_mul_f32_e32 v18, v18, v15
	v_exp_f32_e32 v14, v14
	v_exp_f32_e32 v18, v18
	v_cvt_pk_bf16_f32 v6, v0, v6
	v_add_f32_e32 v14, 1.0, v14
	v_rcp_f32_e32 v14, v14
	v_add_f32_e32 v0, 1.0, v18
	v_rcp_f32_e32 v0, v0
	v_add_f32_e32 v8, v8, v34
	v_mul_f32_e32 v7, v14, v7
	v_mul_f32_e32 v7, v7, v8
	v_mul_f32_e32 v0, v0, v15
	v_add_f32_e32 v8, v9, v34
	v_mul_f32_e32 v0, v0, v8
	v_cvt_pk_bf16_f32 v7, v7, v0
	s_waitcnt vmcnt(2)
	v_lshlrev_b32_e32 v0, 16, v20
	v_mul_f32_e32 v8, v0, v0
	v_and_b32_e32 v9, 0xffff0000, v20
	v_fmamk_f32 v8, v8, 0xbdd2d3e7, v129
	v_mul_f32_e32 v14, v9, v9
	v_mul_f32_e32 v8, v8, v0
	v_fmamk_f32 v14, v14, 0xbdd2d3e7, v129
	v_mul_f32_e32 v14, v14, v9
	v_exp_f32_e32 v8, v8
	v_exp_f32_e32 v14, v14
	global_store_dwordx2 v[16:17], v[6:7], off offset:32
	v_add_f32_e32 v8, 1.0, v8
	v_rcp_f32_e32 v8, v8
	v_add_f32_e32 v6, 1.0, v14
	v_rcp_f32_e32 v6, v6
	v_add_f32_e32 v2, v2, v34
	v_mul_f32_e32 v0, v8, v0
	v_mul_f32_e32 v0, v0, v2
	v_mul_f32_e32 v2, v6, v9
	v_add_f32_e32 v3, v3, v34
	v_mul_f32_e32 v2, v2, v3
	v_lshlrev_b32_e32 v3, 16, v21
	v_mul_f32_e32 v6, v3, v3
	v_and_b32_e32 v7, 0xffff0000, v21
	v_fmamk_f32 v6, v6, 0xbdd2d3e7, v129
	v_mul_f32_e32 v8, v7, v7
	v_mul_f32_e32 v6, v6, v3
	v_fmamk_f32 v8, v8, 0xbdd2d3e7, v129
	v_mul_f32_e32 v8, v8, v7
	v_exp_f32_e32 v6, v6
	v_exp_f32_e32 v8, v8
	v_cvt_pk_bf16_f32 v2, v0, v2
	v_add_f32_e32 v6, 1.0, v6
	v_rcp_f32_e32 v6, v6
	v_add_f32_e32 v0, 1.0, v8
	v_rcp_f32_e32 v0, v0
	v_add_f32_e32 v4, v4, v34
	v_mul_f32_e32 v3, v6, v3
	v_mul_f32_e32 v3, v3, v4
	v_mul_f32_e32 v0, v0, v7
	v_add_f32_e32 v4, v5, v34
	v_mul_f32_e32 v0, v0, v4
	v_cvt_pk_bf16_f32 v3, v3, v0
	s_waitcnt vmcnt(2)
	v_lshlrev_b32_e32 v0, 16, v22
	v_mul_f32_e32 v4, v0, v0
	v_and_b32_e32 v5, 0xffff0000, v22
	v_fmamk_f32 v4, v4, 0xbdd2d3e7, v129
	v_mul_f32_e32 v6, v5, v5
	v_mul_f32_e32 v4, v4, v0
	v_fmamk_f32 v6, v6, 0xbdd2d3e7, v129
	v_mul_f32_e32 v6, v6, v5
	v_exp_f32_e32 v4, v4
	v_exp_f32_e32 v6, v6
	global_store_dwordx2 v[16:17], v[2:3], off offset:64
	v_add_f32_e32 v4, 1.0, v4
	v_rcp_f32_e32 v4, v4
	v_add_f32_e32 v2, 1.0, v6
	v_rcp_f32_e32 v2, v2
	v_add_f32_e32 v3, v10, v34
	v_mul_f32_e32 v0, v4, v0
	v_mul_f32_e32 v0, v0, v3
	v_mul_f32_e32 v2, v2, v5
	v_add_f32_e32 v3, v11, v34
	v_mul_f32_e32 v2, v2, v3
	v_lshlrev_b32_e32 v3, 16, v23
	v_mul_f32_e32 v4, v3, v3
	v_and_b32_e32 v5, 0xffff0000, v23
	v_fmamk_f32 v4, v4, 0xbdd2d3e7, v129
	v_mul_f32_e32 v6, v5, v5
	v_mul_f32_e32 v4, v4, v3
	v_fmamk_f32 v6, v6, 0xbdd2d3e7, v129
	v_mul_f32_e32 v6, v6, v5
	v_exp_f32_e32 v4, v4
	v_exp_f32_e32 v6, v6
	v_cvt_pk_bf16_f32 v2, v0, v2
	v_add_f32_e32 v4, 1.0, v4
	v_rcp_f32_e32 v4, v4
	v_add_f32_e32 v0, 1.0, v6
	v_rcp_f32_e32 v0, v0
	v_mul_f32_e32 v3, v4, v3
	v_add_f32_e32 v4, v12, v34
	v_mul_f32_e32 v3, v3, v4
	v_mul_f32_e32 v0, v0, v5
	v_add_f32_e32 v4, v13, v34
	v_mul_f32_e32 v0, v0, v4
	v_cvt_pk_bf16_f32 v3, v3, v0
	global_store_dwordx2 v[16:17], v[2:3], off offset:96
	s_barrier
	s_cbranch_scc0 .LBB0_626
	s_mov_b32 s85, s10
	s_sub_i32 s10, s85, 0x80
	s_cmpk_lt_u32 s85, 0x180
	s_cbranch_scc1 .Lrk_entry
	s_sub_i32 s10, s85, 0x180
.Lrk_entry:
	s_and_b32 s0, s10, 3
	s_lshl_b32 s1, s10, 5
	v_mov_b32_e32 v38, v194
	v_cvt_f32_ubyte0_e32 v0, s0
	s_and_b32 s1, s1, 0x7fffff80
	v_sub_f32_e32 v37, 0xc0a00000, v0
	v_bfe_u32 v36, v38, 1, 7
	s_mov_b32 s2, 0xc2fc0000
	v_cmp_gt_f32_e32 vcc, s2, v37
	v_or_b32_e32 v0, s1, v36
	v_mov_b64_e32 v[2:3], s[50:51]
	s_and_b64 s[4:5], vcc, exec
	v_mad_u64_u32 v[34:35], s[4:5], v0, s3, v[2:3]
	v_and_b32_e32 v40, 1, v38
	s_cselect_b32 s2, 0xffffffc0, 0
	s_lshl_b32 s4, s0, 8
	s_mov_b32 s5, s89
	v_lshl_add_u64 v[2:3], v[34:35], 0, s[4:5]
	v_lshlrev_b32_e32 v4, 7, v40
	v_mov_b32_e32 v5, v1
	v_lshl_add_u64 v[2:3], v[2:3], 0, v[4:5]
	global_load_dwordx4 v[30:33], v[2:3], off offset:3072
	global_load_dwordx4 v[26:29], v[2:3], off offset:3088
	global_load_dwordx4 v[22:25], v[2:3], off offset:3104
	global_load_dwordx4 v[18:21], v[2:3], off offset:3120
	global_load_dwordx4 v[14:17], v[2:3], off offset:3136
	global_load_dwordx4 v[10:13], v[2:3], off offset:3152
	global_load_dwordx4 v[6:9], v[2:3], off offset:3168
	s_nop 0
	global_load_dwordx4 v[2:5], v[2:3], off offset:3184
	s_mov_b32 s1, s89
	s_lshl_b32 s0, s0, 7
	v_lshlrev_b32_e32 v0, 6, v40
	v_mul_u32_u24_e32 v41, 0x2200, v40
	v_cndmask_b32_e32 v42, 0, v248, vcc
	v_lshl_add_u64 v[34:35], v[34:35], 0, s[0:1]
	v_lshlrev_b32_e32 v36, 1, v36
	v_lshlrev_b32_e32 v41, 1, v41
	v_add_f32_e32 v37, v37, v42
	v_lshl_add_u64 v[42:43], v[34:35], 0, v[0:1]
	v_add3_u32 v44, s15, v41, v36
	v_add3_u32 v41, s15, v36, v41
	v_exp_f32_e32 v45, v37
	global_load_dwordx4 v[34:37], v[42:43], off offset:2560
	v_lshrrev_b32_e32 v39, 1, v38
	v_and_b32_e32 v55, 0x60, v39
	v_ldexp_f32 v0, v45, s2
	v_sub_f32_e32 v0, 1.0, v0
	v_cmp_gt_f32_e32 vcc, s11, v0
	s_and_b64 s[0:1], vcc, exec
	s_cselect_b32 s0, 32, 0
	v_ldexp_f32 v0, v0, s0
	v_log_f32_e32 v0, v0
	s_mov_b32 s0, 0x3f317217
	v_bfe_u32 v54, v38, 4, 2
	s_mov_b32 s11, s89
	s_mul_i32 s2, s10, 3
	s_movk_i32 s39, 0xd80
	s_mov_b32 s69, 0x800000
	s_waitcnt vmcnt(8)
	ds_write_b16 v44, v30
	ds_write_b16_d16_hi v41, v30 offset:272
	ds_write_b16 v44, v31 offset:544
	ds_write_b16_d16_hi v41, v31 offset:816
	ds_write_b16 v44, v32 offset:1088
	ds_write_b16_d16_hi v41, v32 offset:1360
	ds_write_b16 v44, v33 offset:1632
	ds_write_b16_d16_hi v41, v33 offset:1904
	s_waitcnt vmcnt(7)
	ds_write_b16 v44, v26 offset:2176
	ds_write_b16_d16_hi v41, v26 offset:2448
	ds_write_b16 v44, v27 offset:2720
	ds_write_b16_d16_hi v41, v27 offset:2992
	ds_write_b16 v44, v28 offset:3264
	ds_write_b16_d16_hi v41, v28 offset:3536
	ds_write_b16 v44, v29 offset:3808
	ds_write_b16_d16_hi v41, v29 offset:4080
	s_waitcnt vmcnt(6)
	ds_write_b16 v44, v22 offset:4352
	ds_write_b16_d16_hi v41, v22 offset:4624
	ds_write_b16 v44, v23 offset:4896
	ds_write_b16_d16_hi v41, v23 offset:5168
	ds_write_b16 v44, v24 offset:5440
	ds_write_b16_d16_hi v41, v24 offset:5712
	ds_write_b16 v44, v25 offset:5984
	ds_write_b16_d16_hi v41, v25 offset:6256
	s_waitcnt vmcnt(5)
	ds_write_b16 v44, v18 offset:6528
	ds_write_b16_d16_hi v41, v18 offset:6800
	ds_write_b16 v44, v19 offset:7072
	ds_write_b16_d16_hi v41, v19 offset:7344
	ds_write_b16 v44, v20 offset:7616
	ds_write_b16_d16_hi v41, v20 offset:7888
	ds_write_b16 v44, v21 offset:8160
	ds_write_b16_d16_hi v41, v21 offset:8432
	s_waitcnt vmcnt(4)
	ds_write_b16 v44, v14 offset:8704
	ds_write_b16_d16_hi v41, v14 offset:8976
	ds_write_b16 v44, v15 offset:9248
	ds_write_b16_d16_hi v41, v15 offset:9520
	ds_write_b16 v44, v16 offset:9792
	ds_write_b16_d16_hi v41, v16 offset:10064
	ds_write_b16 v44, v17 offset:10336
	ds_write_b16_d16_hi v41, v17 offset:10608
	s_waitcnt vmcnt(3)
	ds_write_b16 v44, v10 offset:10880
	ds_write_b16_d16_hi v41, v10 offset:11152
	ds_write_b16 v44, v11 offset:11424
	ds_write_b16_d16_hi v41, v11 offset:11696
	ds_write_b16 v44, v12 offset:11968
	ds_write_b16_d16_hi v41, v12 offset:12240
	ds_write_b16 v44, v13 offset:12512
	ds_write_b16_d16_hi v41, v13 offset:12784
	s_waitcnt vmcnt(2)
	ds_write_b16 v44, v6 offset:13056
	ds_write_b16_d16_hi v41, v6 offset:13328
	ds_write_b16 v44, v7 offset:13600
	ds_write_b16_d16_hi v41, v7 offset:13872
	global_load_dwordx4 v[10:13], v[42:43], off offset:2576
	ds_write_b16 v44, v8 offset:14144
	ds_write_b16_d16_hi v41, v8 offset:14416
	ds_write_b16 v44, v9 offset:14688
	ds_write_b16_d16_hi v41, v9 offset:14960
	s_waitcnt vmcnt(2)
	ds_write_b16 v44, v2 offset:15232
	ds_write_b16_d16_hi v41, v2 offset:15504
	ds_write_b16 v44, v3 offset:15776
	ds_write_b16_d16_hi v41, v3 offset:16048
	ds_write_b16 v44, v4 offset:16320
	ds_write_b16_d16_hi v41, v4 offset:16592
	global_load_dwordx4 v[6:9], v[42:43], off offset:2592
	v_mul_f32_e32 v2, 0x3f317217, v0
	v_fma_f32 v2, v0, s0, -v2
	v_fmac_f32_e32 v2, 0x3377d1cf, v0
	s_mov_b32 s0, 0x7f800000
	v_fmac_f32_e32 v2, 0x3f317217, v0
	v_cmp_lt_f32_e64 s[0:1], |v0|, s0
	ds_write_b16 v44, v5 offset:16864
	ds_write_b16_d16_hi v41, v5 offset:17136
	v_cndmask_b32_e64 v0, v0, v2, s[0:1]
	v_cndmask_b32_e32 v2, 0, v231, vcc
	s_movk_i32 s0, 0x7f
	v_sub_f32_e32 v0, v0, v2
	v_bitop3_b32 v2, v39, s0, v39 bitop3:0xc
	v_cvt_f32_ubyte0_e32 v2, v2
	v_mul_f32_e32 v2, v0, v2
	v_mul_f32_e32 v0, 0x3fb8aa3b, v2
	s_mov_b32 s0, 0x3fb8aa3b
	v_fma_f32 v3, v2, s0, -v0
	v_rndne_f32_e32 v4, v0
	v_fmac_f32_e32 v3, 0x32a5705f, v2
	v_sub_f32_e32 v0, v0, v4
	v_add_f32_e32 v0, v0, v3
	v_exp_f32_e32 v3, v0
	v_cvt_i32_f32_e32 v4, v4
	s_mov_b32 s0, 0xc2ce8ed0
	v_cmp_ngt_f32_e32 vcc, s0, v2
	s_mov_b32 s0, 0x42b17218
	v_ldexp_f32 v3, v3, v4
	v_cndmask_b32_e32 v3, 0, v3, vcc
	v_cmp_nlt_f32_e32 vcc, s0, v2
	s_waitcnt vmcnt(2)
	v_lshlrev_b32_e32 v15, 16, v34
	v_and_b32_e32 v0, 15, v38
	v_cndmask_b32_e32 v2, v195, v3, vcc
	v_mul_f32_e32 v14, 0x3e000000, v2
	global_load_dwordx4 v[2:5], v[42:43], off offset:2608
	v_mul_f32_e32 v15, v14, v15
	v_cvt_pk_bf16_f32 v15, v15, s0
	s_movk_i32 s0, 0xde00
	v_mad_i32_i24 v16, v40, s0, v44
	ds_write_b16 v16, v15 offset:34816
	v_and_b32_e32 v15, 0xffff0000, v34
	v_mul_f32_e32 v15, v14, v15
	v_cvt_pk_bf16_f32 v15, v15, s0
	v_mad_i32_i24 v17, v40, s0, v41
	ds_write_b16 v17, v15 offset:35088
	v_lshlrev_b32_e32 v15, 16, v35
	v_mul_f32_e32 v15, v14, v15
	v_cvt_pk_bf16_f32 v15, v15, s0
	ds_write_b16 v16, v15 offset:35360
	v_and_b32_e32 v15, 0xffff0000, v35
	v_mul_f32_e32 v15, v14, v15
	v_cvt_pk_bf16_f32 v15, v15, s0
	ds_write_b16 v17, v15 offset:35632
	v_lshlrev_b32_e32 v15, 16, v36
	v_mul_f32_e32 v15, v14, v15
	v_cvt_pk_bf16_f32 v15, v15, s0
	ds_write_b16 v16, v15 offset:35904
	v_and_b32_e32 v15, 0xffff0000, v36
	v_mul_f32_e32 v15, v14, v15
	v_cvt_pk_bf16_f32 v15, v15, s0
	ds_write_b16 v17, v15 offset:36176
	v_lshlrev_b32_e32 v15, 16, v37
	v_mul_f32_e32 v15, v14, v15
	v_cvt_pk_bf16_f32 v15, v15, s0
	ds_write_b16 v16, v15 offset:36448
	v_and_b32_e32 v15, 0xffff0000, v37
	v_mul_f32_e32 v15, v14, v15
	v_cvt_pk_bf16_f32 v15, v15, s0
	ds_write_b16 v17, v15 offset:36720
	s_waitcnt vmcnt(2)
	v_lshlrev_b32_e32 v15, 16, v10
	v_and_b32_e32 v10, 0xffff0000, v10
	v_mul_f32_e32 v10, v14, v10
	v_cvt_pk_bf16_f32 v10, v10, s0
	ds_write_b16 v17, v10 offset:37264
	v_lshlrev_b32_e32 v10, 16, v11
	v_mul_f32_e32 v10, v14, v10
	v_cvt_pk_bf16_f32 v10, v10, s0
	ds_write_b16 v16, v10 offset:37536
	v_and_b32_e32 v10, 0xffff0000, v11
	v_mul_f32_e32 v10, v14, v10
	v_cvt_pk_bf16_f32 v10, v10, s0
	ds_write_b16 v17, v10 offset:37808
	v_lshlrev_b32_e32 v10, 16, v12
	v_mul_f32_e32 v10, v14, v10
	v_cvt_pk_bf16_f32 v10, v10, s0
	ds_write_b16 v16, v10 offset:38080
	v_and_b32_e32 v10, 0xffff0000, v12
	v_mul_f32_e32 v10, v14, v10
	v_cvt_pk_bf16_f32 v10, v10, s0
	ds_write_b16 v17, v10 offset:38352
	v_lshlrev_b32_e32 v10, 16, v13
	v_mul_f32_e32 v10, v14, v10
	v_cvt_pk_bf16_f32 v10, v10, s0
	ds_write_b16 v16, v10 offset:38624
	v_and_b32_e32 v10, 0xffff0000, v13
	v_mul_f32_e32 v10, v14, v10
	v_cvt_pk_bf16_f32 v10, v10, s0
	ds_write_b16 v17, v10 offset:38896
	s_waitcnt vmcnt(1)
	v_lshlrev_b32_e32 v10, 16, v6
	v_and_b32_e32 v6, 0xffff0000, v6
	v_mul_f32_e32 v6, v14, v6
	v_cvt_pk_bf16_f32 v6, v6, s0
	ds_write_b16 v17, v6 offset:39440
	v_lshlrev_b32_e32 v6, 16, v7
	v_mul_f32_e32 v6, v14, v6
	v_cvt_pk_bf16_f32 v6, v6, s0
	ds_write_b16 v16, v6 offset:39712
	v_and_b32_e32 v6, 0xffff0000, v7
	v_mul_f32_e32 v6, v14, v6
	v_cvt_pk_bf16_f32 v6, v6, s0
	ds_write_b16 v17, v6 offset:39984
	v_lshlrev_b32_e32 v6, 16, v8
	v_mul_f32_e32 v6, v14, v6
	v_cvt_pk_bf16_f32 v6, v6, s0
	ds_write_b16 v16, v6 offset:40256
	v_and_b32_e32 v6, 0xffff0000, v8
	v_mul_f32_e32 v6, v14, v6
	v_cvt_pk_bf16_f32 v6, v6, s0
	ds_write_b16 v17, v6 offset:40528
	v_lshlrev_b32_e32 v6, 16, v9
	v_mul_f32_e32 v6, v14, v6
	v_cvt_pk_bf16_f32 v6, v6, s0
	ds_write_b16 v16, v6 offset:40800
	v_and_b32_e32 v6, 0xffff0000, v9
	v_mul_f32_e32 v6, v14, v6
	v_cvt_pk_bf16_f32 v6, v6, s0
	ds_write_b16 v17, v6 offset:41072
	s_waitcnt vmcnt(0)
	v_lshlrev_b32_e32 v6, 16, v2
	v_and_b32_e32 v2, 0xffff0000, v2
	v_mul_f32_e32 v2, v14, v2
	v_cvt_pk_bf16_f32 v2, v2, s0
	ds_write_b16 v17, v2 offset:41616
	v_lshlrev_b32_e32 v2, 16, v3
	v_mul_f32_e32 v2, v14, v2
	v_cvt_pk_bf16_f32 v2, v2, s0
	ds_write_b16 v16, v2 offset:41888
	v_and_b32_e32 v2, 0xffff0000, v3
	v_mul_f32_e32 v2, v14, v2
	v_cvt_pk_bf16_f32 v2, v2, s0
	ds_write_b16 v17, v2 offset:42160
	v_lshlrev_b32_e32 v2, 16, v4
	v_mul_f32_e32 v2, v14, v2
	v_cvt_pk_bf16_f32 v2, v2, s0
	ds_write_b16 v16, v2 offset:42432
	v_and_b32_e32 v2, 0xffff0000, v4
	v_mul_f32_e32 v2, v14, v2
	v_cvt_pk_bf16_f32 v2, v2, s0
	ds_write_b16 v17, v2 offset:42704
	v_lshlrev_b32_e32 v2, 16, v5
	v_mul_f32_e32 v2, v14, v2
	v_cvt_pk_bf16_f32 v2, v2, s0
	ds_write_b16 v16, v2 offset:42976
	v_and_b32_e32 v2, 0xffff0000, v5
	v_mul_f32_e32 v2, v14, v2
	v_mul_f32_e32 v6, v14, v6
	v_cvt_pk_bf16_f32 v2, v2, s0
	v_cvt_pk_bf16_f32 v6, v6, s0
	ds_write_b16 v17, v2 offset:43248
	v_or_b32_e32 v2, v55, v0
	v_mul_f32_e32 v15, v14, v15
	v_mul_f32_e32 v10, v14, v10
	ds_write_b16 v16, v6 offset:41344
	v_lshl_add_u32 v6, v54, 4, s15
	v_mul_u32_u24_e32 v2, 0x88, v2
	v_mul_u32_u24_e32 v7, 0x88, v0
	v_cvt_pk_bf16_f32 v15, v15, s0
	v_cvt_pk_bf16_f32 v10, v10, s0
	v_lshl_add_u32 v56, v2, 1, v6
	v_lshl_add_u32 v57, v7, 1, v6
	ds_write_b16 v16, v15 offset:36992
	ds_write_b16 v16, v10 offset:39168
	s_waitcnt lgkmcnt(0)
	s_barrier
	ds_read_b128 v[2:5], v56
	ds_read_b128 v[38:41], v56 offset:64
	ds_read_b128 v[6:9], v57 offset:34816
	ds_read_b128 v[34:37], v56 offset:4352
	ds_read_b128 v[14:17], v57 offset:39168
	ds_read_b128 v[22:25], v57 offset:43520
	ds_read_b128 v[30:33], v57 offset:47872
	ds_read_b128 v[46:49], v57 offset:43584
	s_waitcnt lgkmcnt(5)
	v_mfma_f32_16x16x32_bf16 v[10:13], v[2:5], v[6:9], 0
	ds_read_b128 v[42:45], v57 offset:39232
	ds_read_b128 v[50:53], v57 offset:47936
	s_lshl_b64 s[0:1], s[10:11], 15
	s_waitcnt lgkmcnt(5)
	v_mfma_f32_16x16x32_bf16 v[18:21], v[2:5], v[14:17], 0
	s_add_u32 s0, s24, s0
	s_addc_u32 s1, s25, s1
	s_add_i32 s9, s2, 0xfffffd80
	s_waitcnt lgkmcnt(4)
	v_mfma_f32_16x16x32_bf16 v[26:29], v[2:5], v[22:25], 0
	s_waitcnt lgkmcnt(3)
	v_mfma_f32_16x16x32_bf16 v[2:5], v[2:5], v[30:33], 0
	v_mfma_f32_16x16x32_bf16 v[6:9], v[34:37], v[6:9], 0
	v_mfma_f32_16x16x32_bf16 v[14:17], v[34:37], v[14:17], 0
	v_mfma_f32_16x16x32_bf16 v[22:25], v[34:37], v[22:25], 0
	v_mfma_f32_16x16x32_bf16 v[30:33], v[34:37], v[30:33], 0
	ds_read_b128 v[34:37], v57 offset:34880
	s_waitcnt lgkmcnt(0)
	v_mfma_f32_16x16x32_bf16 v[10:13], v[38:41], v[34:37], v[10:13]
	v_mfma_f32_16x16x32_bf16 v[18:21], v[38:41], v[42:45], v[18:21]
	v_mfma_f32_16x16x32_bf16 v[26:29], v[38:41], v[46:49], v[26:29]
	v_mfma_f32_16x16x32_bf16 v[2:5], v[38:41], v[50:53], v[2:5]
	ds_read_b128 v[38:41], v56 offset:4416
	s_waitcnt lgkmcnt(0)
	v_mfma_f32_16x16x32_bf16 v[6:9], v[38:41], v[34:37], v[6:9]
	ds_read_b128 v[34:37], v56 offset:128
	v_mfma_f32_16x16x32_bf16 v[14:17], v[38:41], v[42:45], v[14:17]
	ds_read_b128 v[42:45], v57 offset:39296
	v_mfma_f32_16x16x32_bf16 v[22:25], v[38:41], v[46:49], v[22:25]
	ds_read_b128 v[46:49], v57 offset:43648
	v_mfma_f32_16x16x32_bf16 v[30:33], v[38:41], v[50:53], v[30:33]
	ds_read_b128 v[38:41], v57 offset:34944
	ds_read_b128 v[50:53], v57 offset:48000
	s_waitcnt lgkmcnt(1)
	v_mfma_f32_16x16x32_bf16 v[10:13], v[34:37], v[38:41], v[10:13]
	v_mfma_f32_16x16x32_bf16 v[18:21], v[34:37], v[42:45], v[18:21]
	v_mfma_f32_16x16x32_bf16 v[26:29], v[34:37], v[46:49], v[26:29]
	s_waitcnt lgkmcnt(0)
	v_mfma_f32_16x16x32_bf16 v[2:5], v[34:37], v[50:53], v[2:5]
	ds_read_b128 v[34:37], v56 offset:4480
	s_waitcnt lgkmcnt(0)
	v_mfma_f32_16x16x32_bf16 v[6:9], v[34:37], v[38:41], v[6:9]
	ds_read_b128 v[38:41], v56 offset:192
	v_mfma_f32_16x16x32_bf16 v[14:17], v[34:37], v[42:45], v[14:17]
	ds_read_b128 v[42:45], v57 offset:39360
	v_mfma_f32_16x16x32_bf16 v[22:25], v[34:37], v[46:49], v[22:25]
	ds_read_b128 v[46:49], v57 offset:43712
	v_mfma_f32_16x16x32_bf16 v[30:33], v[34:37], v[50:53], v[30:33]
	ds_read_b128 v[34:37], v57 offset:35008
	ds_read_b128 v[50:53], v57 offset:48064
	s_waitcnt lgkmcnt(1)
	v_mfma_f32_16x16x32_bf16 v[10:13], v[38:41], v[34:37], v[10:13]
	v_mfma_f32_16x16x32_bf16 v[18:21], v[38:41], v[42:45], v[18:21]
	v_mfma_f32_16x16x32_bf16 v[26:29], v[38:41], v[46:49], v[26:29]
	s_waitcnt lgkmcnt(0)
	v_mfma_f32_16x16x32_bf16 v[2:5], v[38:41], v[50:53], v[2:5]
	ds_read_b128 v[38:41], v56 offset:4544
	s_waitcnt lgkmcnt(0)
	v_mfma_f32_16x16x32_bf16 v[6:9], v[38:41], v[34:37], v[6:9]
	v_lshlrev_b32_e32 v37, 6, v55
	v_lshl_or_b32 v37, v54, 8, v37
	v_or_b32_e32 v34, 16, v0
	v_mfma_f32_16x16x32_bf16 v[14:17], v[38:41], v[42:45], v[14:17]
	v_or_b32_e32 v35, 32, v0
	v_or_b32_e32 v36, 48, v0
	v_mfma_f32_16x16x32_bf16 v[22:25], v[38:41], v[46:49], v[22:25]
	v_mfma_f32_16x16x32_bf16 v[30:33], v[38:41], v[50:53], v[30:33]
	v_or_b32_e32 v38, v37, v0
	v_lshlrev_b32_e32 v38, 2, v38
	global_store_dword v38, v10, s[0:1]
	global_store_dword v38, v11, s[0:1] offset:256
	global_store_dword v38, v12, s[0:1] offset:512
	global_store_dword v38, v13, s[0:1] offset:768
	global_store_dword v38, v18, s[0:1] offset:64
	v_or_b32_e32 v10, v37, v34
	v_lshlrev_b32_e32 v10, 2, v10
	global_store_dword v10, v19, s[0:1] offset:256
	global_store_dword v10, v20, s[0:1] offset:512
	global_store_dword v10, v21, s[0:1] offset:768
	global_store_dword v38, v26, s[0:1] offset:128
	v_or_b32_e32 v10, v37, v35
	v_lshlrev_b32_e32 v10, 2, v10
	global_store_dword v10, v27, s[0:1] offset:256
	global_store_dword v10, v28, s[0:1] offset:512
	global_store_dword v10, v29, s[0:1] offset:768
	global_store_dword v38, v2, s[0:1] offset:192
	v_or_b32_e32 v2, v37, v36
	v_lshlrev_b32_e32 v2, 2, v2
	global_store_dword v2, v3, s[0:1] offset:256
	global_store_dword v2, v4, s[0:1] offset:512
	global_store_dword v2, v5, s[0:1] offset:768
	v_or_b32_e32 v2, 0x400, v37
	v_or_b32_e32 v3, v2, v0
	v_lshlrev_b32_e32 v3, 2, v3
	global_store_dword v3, v6, s[0:1]
	v_or_b32_e32 v3, 0x440, v37
	v_or_b32_e32 v4, v3, v0
	v_lshlrev_b32_e32 v4, 2, v4
	global_store_dword v4, v7, s[0:1]
	v_or_b32_e32 v4, 0x480, v37
	v_or_b32_e32 v5, v4, v0
	v_lshlrev_b32_e32 v5, 2, v5
	global_store_dword v5, v8, s[0:1]
	v_or_b32_e32 v5, 0x4c0, v37
	v_or_b32_e32 v0, v5, v0
	v_lshlrev_b32_e32 v0, 2, v0
	global_store_dword v0, v9, s[0:1]
	v_or_b32_e32 v0, v2, v34
	v_lshlrev_b32_e32 v0, 2, v0
	global_store_dword v0, v14, s[0:1]
	v_or_b32_e32 v0, v3, v34
	v_lshlrev_b32_e32 v0, 2, v0
	global_store_dword v0, v15, s[0:1]
	v_or_b32_e32 v0, v4, v34
	v_lshlrev_b32_e32 v0, 2, v0
	global_store_dword v0, v16, s[0:1]
	v_or_b32_e32 v0, v5, v34
	v_lshlrev_b32_e32 v0, 2, v0
	global_store_dword v0, v17, s[0:1]
	v_or_b32_e32 v0, v2, v35
	v_lshlrev_b32_e32 v0, 2, v0
	global_store_dword v0, v22, s[0:1]
	v_or_b32_e32 v0, v3, v35
	v_lshlrev_b32_e32 v0, 2, v0
	global_store_dword v0, v23, s[0:1]
	v_or_b32_e32 v0, v4, v35
	v_lshlrev_b32_e32 v0, 2, v0
	global_store_dword v0, v24, s[0:1]
	v_or_b32_e32 v0, v5, v35
	v_lshlrev_b32_e32 v0, 2, v0
	global_store_dword v0, v25, s[0:1]
	v_or_b32_e32 v0, v2, v36
	v_lshlrev_b32_e32 v0, 2, v0
	global_store_dword v0, v30, s[0:1]
	v_or_b32_e32 v0, v3, v36
	v_lshlrev_b32_e32 v0, 2, v0
	global_store_dword v0, v31, s[0:1]
	v_or_b32_e32 v0, v4, v36
	v_lshlrev_b32_e32 v0, 2, v0
	global_store_dword v0, v32, s[0:1]
	v_or_b32_e32 v0, v5, v36
	v_lshlrev_b32_e32 v0, 2, v0
	global_store_dword v0, v33, s[0:1]
	s_lshl_b32 s0, s9, 6
	s_and_b32 s11, s0, 0x3fc0
	v_mov_b32_e32 v0, v194
	s_cmpk_lt_u32 s9, 0x200
	s_barrier
	s_cmp_eq_u32 s10, s85
	s_cbranch_scc1 .Lrk_done
	s_mov_b32 s10, s85
	s_mov_b32 s11, 0x800000
	s_branch .Lrk_entry
.Lrk_done:
	s_cmpk_lt_u32 s9, 0x200
	s_cselect_b64 s[0:1], -1, 0
	s_and_b64 s[4:5], s[0:1], exec
	v_bfe_u32 v12, v0, 2, 6
	v_lshlrev_b32_e32 v0, 4, v0
	s_cselect_b32 s4, s39, 0xe80
	s_lshr_b32 s5, s9, 2
	v_and_b32_e32 v10, 48, v0
	v_or_b32_e32 v0, s11, v12
	s_and_b32 s9, s5, 64
	v_mul_u32_u24_e32 v0, 0xf80, v0
	s_or_b32 s4, s4, s9
	v_lshlrev_b32_e32 v0, 1, v0
	v_lshl_add_u64 v[2:3], s[50:51], 0, v[0:1]
	s_lshl_b32 s4, s4, 1
	s_mov_b32 s5, s89
	v_lshl_add_u64 v[2:3], v[2:3], 0, s[4:5]
	v_lshlrev_b32_e32 v0, 1, v10
	v_lshl_add_u64 v[6:7], v[2:3], 0, v[0:1]
	global_load_dwordx4 v[2:5], v[6:7], off
	s_nop 0
	global_load_dwordx4 v[6:9], v[6:7], off offset:16
	v_mul_u32_u24_e32 v10, 0x48, v10
	v_lshlrev_b32_e32 v10, 1, v10
	v_lshlrev_b32_e32 v11, 1, v12
	v_add3_u32 v13, s15, v10, v11
	v_add3_u32 v10, s15, v11, v10
	s_and_b64 s[0:1], s[0:1], exec
	s_cselect_b32 s1, s53, s55
	s_cselect_b32 s0, s52, s54
	s_waitcnt vmcnt(1)
	ds_write_b16 v13, v2
	ds_write_b16_d16_hi v10, v2 offset:144
	ds_write_b16 v13, v3 offset:288
	ds_write_b16_d16_hi v10, v3 offset:432
	ds_write_b16 v13, v4 offset:576
	ds_write_b16_d16_hi v10, v4 offset:720
	ds_write_b16 v13, v5 offset:864
	ds_write_b16_d16_hi v10, v5 offset:1008
	s_waitcnt vmcnt(0)
	ds_write_b16 v13, v6 offset:1152
	ds_write_b16_d16_hi v10, v6 offset:1296
	ds_write_b16 v13, v7 offset:1440
	ds_write_b16_d16_hi v10, v7 offset:1584
	ds_write_b16 v13, v8 offset:1728
	ds_write_b16_d16_hi v10, v8 offset:1872
	ds_write_b16 v13, v9 offset:2016
	ds_write_b16_d16_hi v10, v9 offset:2160
	v_or_b32_e32 v2, s9, v12
	v_lshlrev_b32_e32 v2, 15, v2
	v_mov_b32_e32 v3, v1
	v_lshl_add_u64 v[10:11], s[0:1], 0, v[2:3]
	v_mul_u32_u24_e32 v2, 0x90, v12
	v_add3_u32 v6, s15, v2, v0
	s_waitcnt lgkmcnt(0)
	s_barrier
	ds_read_b128 v[2:5], v6
	ds_read_b128 v[6:9], v6 offset:16
	s_lshl_b32 s0, s11, 1
	s_mov_b32 s1, s89
	s_add_i32 s9, s2, 0xfffffd81
	v_lshl_add_u64 v[10:11], v[10:11], 0, s[0:1]
	s_lshl_b32 s0, s9, 6
	s_and_b32 s11, s0, 0x3fc0
	v_lshl_add_u64 v[10:11], v[10:11], 0, v[0:1]
	v_mov_b32_e32 v0, v194
	s_cmpk_lt_u32 s9, 0x200
	s_waitcnt lgkmcnt(1)
	global_store_dwordx4 v[10:11], v[2:5], off
	s_waitcnt lgkmcnt(0)
	global_store_dwordx4 v[10:11], v[6:9], off offset:16
	s_barrier
	s_cselect_b64 s[0:1], -1, 0
	s_and_b64 s[4:5], s[0:1], exec
	v_bfe_u32 v12, v0, 2, 6
	v_lshlrev_b32_e32 v0, 4, v0
	s_cselect_b32 s4, s39, 0xe80
	s_lshr_b32 s5, s9, 2
	v_and_b32_e32 v10, 48, v0
	v_or_b32_e32 v0, s11, v12
	s_and_b32 s9, s5, 64
	v_mul_u32_u24_e32 v0, 0xf80, v0
	s_or_b32 s4, s4, s9
	v_lshlrev_b32_e32 v0, 1, v0
	v_lshl_add_u64 v[2:3], s[50:51], 0, v[0:1]
	s_lshl_b32 s4, s4, 1
	s_mov_b32 s5, s89
	v_lshl_add_u64 v[2:3], v[2:3], 0, s[4:5]
	v_lshlrev_b32_e32 v0, 1, v10
	v_lshl_add_u64 v[6:7], v[2:3], 0, v[0:1]
	global_load_dwordx4 v[2:5], v[6:7], off
	s_nop 0
	global_load_dwordx4 v[6:9], v[6:7], off offset:16
	v_mul_u32_u24_e32 v10, 0x48, v10
	v_lshlrev_b32_e32 v10, 1, v10
	v_lshlrev_b32_e32 v11, 1, v12
	v_add3_u32 v13, s15, v10, v11
	v_add3_u32 v10, s15, v11, v10
	s_and_b64 s[0:1], s[0:1], exec
	s_cselect_b32 s1, s53, s55
	s_cselect_b32 s0, s52, s54
	s_addk_i32 s2, 0xfd82
	s_waitcnt vmcnt(1)
	ds_write_b16 v13, v2
	ds_write_b16_d16_hi v10, v2 offset:144
	ds_write_b16 v13, v3 offset:288
	ds_write_b16_d16_hi v10, v3 offset:432
	ds_write_b16 v13, v4 offset:576
	ds_write_b16_d16_hi v10, v4 offset:720
	ds_write_b16 v13, v5 offset:864
	ds_write_b16_d16_hi v10, v5 offset:1008
	s_waitcnt vmcnt(0)
	ds_write_b16 v13, v6 offset:1152
	ds_write_b16_d16_hi v10, v6 offset:1296
	ds_write_b16 v13, v7 offset:1440
	ds_write_b16_d16_hi v10, v7 offset:1584
	ds_write_b16 v13, v8 offset:1728
	ds_write_b16_d16_hi v10, v8 offset:1872
	ds_write_b16 v13, v9 offset:2016
	ds_write_b16_d16_hi v10, v9 offset:2160
	v_or_b32_e32 v2, s9, v12
	v_lshlrev_b32_e32 v2, 15, v2
	v_mov_b32_e32 v3, v1
	v_lshl_add_u64 v[10:11], s[0:1], 0, v[2:3]
	v_mul_u32_u24_e32 v2, 0x90, v12
	v_add3_u32 v6, s15, v2, v0
	s_waitcnt lgkmcnt(0)
	s_barrier
	ds_read_b128 v[2:5], v6
	ds_read_b128 v[6:9], v6 offset:16
	s_lshl_b32 s0, s11, 1
	s_mov_b32 s1, s89
	v_lshl_add_u64 v[10:11], v[10:11], 0, s[0:1]
	s_lshl_b32 s0, s2, 6
	s_and_b32 s9, s0, 0x3fc0
	v_lshl_add_u64 v[10:11], v[10:11], 0, v[0:1]
	v_mov_b32_e32 v0, v194
	s_cmpk_lt_u32 s2, 0x200
	s_waitcnt lgkmcnt(1)
	global_store_dwordx4 v[10:11], v[2:5], off
	s_waitcnt lgkmcnt(0)
	global_store_dwordx4 v[10:11], v[6:9], off offset:16
	s_barrier
	s_cselect_b64 s[0:1], -1, 0
	s_and_b64 s[4:5], s[0:1], exec
	v_bfe_u32 v12, v0, 2, 6
	v_lshlrev_b32_e32 v0, 4, v0
	s_cselect_b32 s4, s39, 0xe80
	s_lshr_b32 s2, s2, 2
	v_and_b32_e32 v10, 48, v0
	v_or_b32_e32 v0, s9, v12
	s_and_b32 s2, s2, 64
	v_mul_u32_u24_e32 v0, 0xf80, v0
	s_or_b32 s4, s4, s2
	v_lshlrev_b32_e32 v0, 1, v0
	v_lshl_add_u64 v[2:3], s[50:51], 0, v[0:1]
	s_lshl_b32 s4, s4, 1
	s_mov_b32 s5, s89
	v_lshl_add_u64 v[2:3], v[2:3], 0, s[4:5]
	v_lshlrev_b32_e32 v0, 1, v10
	v_lshl_add_u64 v[6:7], v[2:3], 0, v[0:1]
	global_load_dwordx4 v[2:5], v[6:7], off
	s_nop 0
	global_load_dwordx4 v[6:9], v[6:7], off offset:16
	v_mul_u32_u24_e32 v10, 0x48, v10
	v_lshlrev_b32_e32 v10, 1, v10
	v_lshlrev_b32_e32 v11, 1, v12
	v_add3_u32 v13, s15, v10, v11
	v_add3_u32 v10, s15, v11, v10
	s_and_b64 s[0:1], s[0:1], exec
	s_cselect_b32 s1, s53, s55
	s_cselect_b32 s0, s52, s54
	s_mov_b64 s[4:5], 0
	s_waitcnt vmcnt(1)
	ds_write_b16 v13, v2
	ds_write_b16_d16_hi v10, v2 offset:144
	ds_write_b16 v13, v3 offset:288
	ds_write_b16_d16_hi v10, v3 offset:432
	ds_write_b16 v13, v4 offset:576
	ds_write_b16_d16_hi v10, v4 offset:720
	ds_write_b16 v13, v5 offset:864
	ds_write_b16_d16_hi v10, v5 offset:1008
	s_waitcnt vmcnt(0)
	ds_write_b16 v13, v6 offset:1152
	ds_write_b16_d16_hi v10, v6 offset:1296
	ds_write_b16 v13, v7 offset:1440
	ds_write_b16_d16_hi v10, v7 offset:1584
	ds_write_b16 v13, v8 offset:1728
	ds_write_b16_d16_hi v10, v8 offset:1872
	ds_write_b16 v13, v9 offset:2016
	ds_write_b16_d16_hi v10, v9 offset:2160
	v_or_b32_e32 v2, s2, v12
	v_lshlrev_b32_e32 v2, 15, v2
	v_mov_b32_e32 v3, v1
	v_lshl_add_u64 v[10:11], s[0:1], 0, v[2:3]
	v_mul_u32_u24_e32 v2, 0x90, v12
	v_add3_u32 v6, s15, v2, v0
	s_waitcnt lgkmcnt(0)
	s_barrier
	ds_read_b128 v[2:5], v6
	ds_read_b128 v[6:9], v6 offset:16
	s_lshl_b32 s0, s9, 1
	s_mov_b32 s1, s89
	v_lshl_add_u64 v[10:11], v[10:11], 0, s[0:1]
	v_lshl_add_u64 v[10:11], v[10:11], 0, v[0:1]
	s_mov_b64 s[0:1], 0
	s_cmpk_lt_u32 s10, 0x180
	s_waitcnt lgkmcnt(1)
	global_store_dwordx4 v[10:11], v[2:5], off
	s_waitcnt lgkmcnt(0)
	global_store_dwordx4 v[10:11], v[6:9], off offset:16
	s_barrier
	s_cbranch_scc0 .LBB0_627
	s_lshl_b32 s2, s10, 6
	v_mov_b32_e32 v0, v194
	s_and_b32 s2, s2, 0x3fc0
	s_xor_b32 s2, s2, 0x2000
	v_bfe_u32 v12, v0, 2, 6
	v_lshlrev_b32_e32 v0, 4, v0
	v_and_b32_e32 v10, 48, v0
	v_or_b32_e32 v0, s2, v12
	v_mul_u32_u24_e32 v0, 0xf80, v0
	v_readlane_b32 s40, v251, 54
	v_lshlrev_b32_e32 v0, 1, v0
	v_readlane_b32 s46, v251, 60
	v_readlane_b32 s47, v251, 61
	s_mov_b64 s[4:5], 0x1d80
	v_lshlrev_b32_e32 v11, 1, v12
	v_lshl_add_u64 v[2:3], s[46:47], 0, v[0:1]
	v_lshlrev_b32_e32 v0, 1, v10
	v_lshl_add_u64 v[2:3], v[2:3], 0, v[0:1]
	v_lshl_add_u64 v[6:7], v[2:3], 0, s[4:5]
	v_add_co_u32_e32 v2, vcc, s68, v2
	v_mul_u32_u24_e32 v10, 0x48, v10
	s_nop 0
	v_addc_co_u32_e32 v3, vcc, 0, v3, vcc
	global_load_dwordx4 v[2:5], v[2:3], off offset:3456
	s_nop 0
	global_load_dwordx4 v[6:9], v[6:7], off offset:16
	v_lshlrev_b32_e32 v10, 1, v10
	v_add3_u32 v13, s15, v10, v11
	v_add3_u32 v10, s15, v11, v10
	v_readlane_b32 s50, v252, 0
	v_readlane_b32 s51, v252, 1
	s_lshl_b32 s4, s2, 1
	s_mov_b32 s5, s89
	v_readlane_b32 s41, v251, 55
	v_readlane_b32 s42, v251, 56
	v_readlane_b32 s43, v251, 57
	v_readlane_b32 s44, v251, 58
	v_readlane_b32 s45, v251, 59
	v_readlane_b32 s48, v251, 62
	v_readlane_b32 s49, v251, 63
	v_readlane_b32 s52, v252, 2
	v_readlane_b32 s53, v252, 3
	v_readlane_b32 s54, v252, 4
	v_readlane_b32 s55, v252, 5
	s_waitcnt vmcnt(1)
	ds_write_b16 v13, v2
	ds_write_b16_d16_hi v10, v2 offset:144
	ds_write_b16 v13, v3 offset:288
	ds_write_b16_d16_hi v10, v3 offset:432
	ds_write_b16 v13, v4 offset:576
	ds_write_b16_d16_hi v10, v4 offset:720
	ds_write_b16 v13, v5 offset:864
	ds_write_b16_d16_hi v10, v5 offset:1008
	s_waitcnt vmcnt(0)
	ds_write_b16 v13, v6 offset:1152
	ds_write_b16_d16_hi v10, v6 offset:1296
	ds_write_b16 v13, v7 offset:1440
	ds_write_b16_d16_hi v10, v7 offset:1584
	ds_write_b16 v13, v8 offset:1728
	ds_write_b16_d16_hi v10, v8 offset:1872
	ds_write_b16 v13, v9 offset:2016
	ds_write_b16_d16_hi v10, v9 offset:2160
	v_lshlrev_b32_e32 v2, 15, v12
	v_mov_b32_e32 v3, v1
	v_lshl_add_u64 v[2:3], s[50:51], 0, v[2:3]
	v_lshl_add_u64 v[2:3], v[2:3], 0, s[4:5]
	v_lshl_add_u64 v[2:3], v[2:3], 0, v[0:1]
	v_mul_u32_u24_e32 v4, 0x90, v12
	s_mov_b64 s[4:5], 0x200000
	v_add3_u32 v0, s15, v4, v0
	v_add_co_u32_e32 v12, vcc, 0x200000, v2
	s_waitcnt lgkmcnt(0)
	s_barrier
	v_lshl_add_u64 v[10:11], v[2:3], 0, s[4:5]
	v_addc_co_u32_e32 v13, vcc, 0, v3, vcc
	ds_read_b128 v[2:5], v0
	ds_read_b128 v[6:9], v0 offset:16
	s_waitcnt lgkmcnt(1)
	global_store_dwordx4 v[12:13], v[2:5], off
	s_waitcnt lgkmcnt(0)
	global_store_dwordx4 v[10:11], v[6:9], off offset:16
	s_barrier
	s_mov_b64 s[4:5], -1
	s_branch .LBB0_627

.LBB0_635:
	ds_read2st64_b32 v[4:5], v2 offset1:64
	v_add_u32_e32 v3, 0x100, v3
	s_waitcnt lgkmcnt(0)
	v_add_f32_e32 v6, v4, v5
	ds_read2st64_b32 v[4:5], v2 offset0:128 offset1:192
	v_add_u32_e32 v2, 0x400, v2
	s_waitcnt lgkmcnt(0)
	v_add_f32_e32 v4, v6, v4
	v_add_f32_e32 v4, v4, v5
	v_mul_f32_e32 v5, 0x3d372713, v4
	v_mul_f32_e32 v5, v4, v5
	v_fma_f32 v5, v4, v5, v4
	v_mul_f32_e32 v5, 0xbfcc422a, v5
	v_mul_f32_e32 v5, 0x3fb8aa3b, v5
	v_exp_f32_e32 v5, v5
	s_nop 0
	v_add_f32_e32 v5, 1.0, v5
	v_rcp_f32_e32 v5, v5
	s_nop 0
	v_mul_f32_e32 v4, v4, v5
	v_cvt_pk_bf16_f32 v4, v4, s0
	v_cmp_lt_u32_e64 s[0:1], s71, v3
	ds_write_b16 v0, v4
	v_add_u32_e32 v0, 0x200, v0
	s_or_b64 s[4:5], s[0:1], s[4:5]
	s_andn2_b64 exec, exec, s[4:5]
	s_cbranch_execnz .LBB0_635
	s_or_b64 exec, exec, s[4:5]
	v_readlane_b32 s40, v251, 54
	s_lshl_b64 s[0:1], s[6:7], 14
	v_readlane_b32 s42, v251, 56
	v_readlane_b32 s43, v251, 57
	s_add_u32 s0, s42, s0
	v_lshlrev_b32_e32 v18, 8, v126
	s_addc_u32 s1, s43, s1
	v_lshl_or_b32 v0, v124, 12, v18
	v_lshl_add_u64 v[2:3], s[0:1], 0, v[0:1]
	v_lshlrev_b32_e32 v0, 1, v127
	v_lshl_add_u64 v[14:15], v[2:3], 0, v[0:1]
	s_waitcnt lgkmcnt(0)
	s_barrier
	global_load_dwordx4 v[2:5], v[14:15], off
	global_load_dwordx4 v[6:9], v[14:15], off offset:64
	global_load_dwordx4 v[10:13], v[14:15], off offset:128
	s_nop 0
	global_load_dwordx4 v[14:17], v[14:15], off offset:192
	v_lshl_or_b32 v19, v125, 2, s14
	v_lshl_or_b32 v26, v124, 4, v126
	v_or_b32_e32 v20, s17, v26
	v_or_b32_e32 v22, 1, v19
	v_lshlrev_b32_e32 v21, 6, v19
	v_or_b32_e32 v23, 2, v19
	v_or_b32_e32 v24, 3, v19
	v_or_b32_e32 v25, 16, v19
	s_movk_i32 s0, 0x3ec
	v_lshlrev_b32_e32 v30, 10, v20
	s_lshl_b32 s4, s16, 16
	v_lshlrev_b32_e32 v20, 6, v22
	v_add3_u32 v0, s2, v0, v18
	v_or_b32_e32 v27, 17, v19
	v_or_b32_e32 v28, 18, v19
	v_or_b32_e32 v29, 19, v19
	v_cmp_ne_u32_e64 s[8:9], s0, v19
	v_lshlrev_b32_e32 v31, 6, v23
	v_lshlrev_b32_e32 v32, 6, v24
	v_lshlrev_b32_e32 v33, 6, v25
	v_or_b32_e32 v37, v30, v19
	v_or3_b32 v38, v21, s4, v26
	v_or3_b32 v39, v20, s4, v26
	v_or_b32_e32 v40, v30, v22
	v_or_b32_e32 v42, v30, v23
	v_or_b32_e32 v44, v30, v24
	v_or_b32_e32 v46, v30, v25
	ds_read_b128 v[18:21], v0
	ds_read_b128 v[22:25], v0 offset:4096
	v_lshlrev_b32_e32 v34, 6, v27
	v_lshlrev_b32_e32 v35, 6, v28
	v_lshlrev_b32_e32 v36, 6, v29
	v_or3_b32 v41, v31, s4, v26
	v_or3_b32 v43, v32, s4, v26
	v_or3_b32 v45, v33, s4, v26
	v_or3_b32 v34, v34, s4, v26
	v_or_b32_e32 v47, v30, v27
	v_or3_b32 v35, v35, s4, v26
	v_or_b32_e32 v48, v30, v28
	v_or3_b32 v36, v36, s4, v26
	v_or_b32_e32 v49, v30, v29
	ds_read_b128 v[26:29], v0 offset:64
	ds_read_b128 v[30:33], v0 offset:4160
	v_readlane_b32 s52, v252, 2
	v_readlane_b32 s54, v252, 4
	s_and_b64 s[0:1], vcc, exec
	v_readlane_b32 s53, v252, 3
	v_readlane_b32 s55, v252, 5
	v_cndmask_b32_e32 v37, v37, v38, vcc
	s_cselect_b32 s0, s52, s54
	s_cselect_b32 s1, s53, s55
	v_cndmask_b32_e32 v38, v40, v39, vcc
	v_cndmask_b32_e32 v39, v42, v41, vcc
	v_cndmask_b32_e32 v40, v44, v43, vcc
	v_cndmask_b32_e32 v41, v46, v45, vcc
	v_readlane_b32 s46, v251, 60
	v_readlane_b32 s47, v251, 61
	s_movk_i32 s2, 0x7f
	s_mov_b32 s7, s89
	s_mov_b32 s12, 0x42b17218
	v_mov_b32_e32 v61, 0x7f800000
	s_movk_i32 s13, 0xde00
	v_mov_b32_e32 v195, 0x7f800000
	v_readlane_b32 s41, v251, 55
	v_readlane_b32 s44, v251, 58
	v_readlane_b32 s45, v251, 59
	v_readlane_b32 s48, v251, 62
	v_readlane_b32 s49, v251, 63
	s_waitcnt vmcnt(3) lgkmcnt(3)
	v_mfma_f32_16x16x32_bf16 v[18:21], v[18:21], v[2:5], 0
	v_readlane_b32 s50, v252, 0
	v_readlane_b32 s51, v252, 1
	s_waitcnt lgkmcnt(2)
	v_mfma_f32_16x16x32_bf16 v[2:5], v[22:25], v[2:5], 0
	ds_read_b128 v[22:25], v0 offset:128
	s_waitcnt vmcnt(2) lgkmcnt(2)
	v_mfma_f32_16x16x32_bf16 v[18:21], v[26:29], v[6:9], v[18:21]
	ds_read_b128 v[26:29], v0 offset:4224
	s_waitcnt lgkmcnt(2)
	v_mfma_f32_16x16x32_bf16 v[2:5], v[30:33], v[6:9], v[2:5]
	ds_read_b128 v[6:9], v0 offset:192
	v_cndmask_b32_e32 v30, v47, v34, vcc
	v_cndmask_b32_e32 v31, v48, v35, vcc
	s_waitcnt vmcnt(1) lgkmcnt(2)
	v_mfma_f32_16x16x32_bf16 v[18:21], v[22:25], v[10:13], v[18:21]
	ds_read_b128 v[22:25], v0 offset:4288
	v_cndmask_b32_e32 v32, v49, v36, vcc
	v_lshlrev_b32_e32 v0, 1, v37
	s_waitcnt lgkmcnt(2)
	v_mfma_f32_16x16x32_bf16 v[2:5], v[26:29], v[10:13], v[2:5]
	v_lshlrev_b32_e32 v10, 1, v38
	v_lshlrev_b32_e32 v11, 1, v39
	v_lshlrev_b32_e32 v12, 1, v40
	s_waitcnt vmcnt(0) lgkmcnt(1)
	v_mfma_f32_16x16x32_bf16 v[6:9], v[6:9], v[14:17], v[18:21]
	v_lshlrev_b32_e32 v13, 1, v41
	v_mov_b32_e32 v40, v194
	v_mov_b64_e32 v[38:39], s[46:47]
	s_waitcnt lgkmcnt(0)
	v_mfma_f32_16x16x32_bf16 v[2:5], v[22:25], v[14:17], v[2:5]
	v_lshlrev_b32_e32 v18, 1, v30
	s_nop 1
	v_cvt_pk_bf16_f32 v6, v6, s0
	v_lshlrev_b32_e32 v19, 1, v31
	v_cvt_pk_bf16_f32 v7, v7, s0
	v_cvt_pk_bf16_f32 v8, v8, s0
	s_nop 0
	v_cvt_pk_bf16_f32 v2, v2, s0
	v_cvt_pk_bf16_f32 v5, v5, s0
	v_cvt_pk_bf16_f32 v9, v9, s0
	v_cvt_pk_bf16_f32 v3, v3, s0
	v_cvt_pk_bf16_f32 v4, v4, s0
	global_store_short v0, v6, s[0:1]
	global_store_short v10, v7, s[0:1]
	global_store_short v11, v8, s[0:1]
	global_store_short v12, v9, s[0:1]
	global_store_short v13, v2, s[0:1]
	global_store_short v18, v3, s[0:1]
	global_store_short v19, v4, s[0:1]
	v_cndmask_b32_e64 v0, 0, v5, s[8:9]
	v_lshlrev_b32_e32 v2, 1, v32
	global_store_short v2, v0, s[0:1]
	s_and_b32 s0, s10, 3
	v_cvt_f32_ubyte0_e32 v0, s0
	v_sub_f32_e32 v0, 0xc0a00000, v0
	s_mov_b32 s1, 0xc2fc0000
	s_barrier
	s_branch .LBB0_637
	v_cmp_gt_f32_e32 vcc, s1, v0
	v_lshrrev_b32_e32 v41, 1, v40
	v_mov_b32_e32 v2, s11
	s_and_b64 s[4:5], vcc, exec
	v_bfi_b32 v2, s2, v41, v2
	v_and_b32_e32 v42, 1, v40
	s_cselect_b32 s1, 0xffffffc0, 0
	v_mad_i64_i32 v[34:35], s[4:5], v2, s3, v[38:39]
	s_lshl_b32 s6, s0, 8
	v_lshl_add_u64 v[2:3], v[34:35], 0, s[6:7]
	v_lshlrev_b32_e32 v4, 7, v42
	v_mov_b32_e32 v5, v1
	v_lshl_add_u64 v[2:3], v[2:3], 0, v[4:5]
	global_load_dwordx4 v[30:33], v[2:3], off offset:3072
	global_load_dwordx4 v[26:29], v[2:3], off offset:3088
	global_load_dwordx4 v[22:25], v[2:3], off offset:3104
	global_load_dwordx4 v[18:21], v[2:3], off offset:3120
	global_load_dwordx4 v[14:17], v[2:3], off offset:3136
	global_load_dwordx4 v[10:13], v[2:3], off offset:3152
	global_load_dwordx4 v[6:9], v[2:3], off offset:3168
	s_nop 0
	global_load_dwordx4 v[2:5], v[2:3], off offset:3184
	v_cndmask_b32_e32 v36, 0, v248, vcc
	v_add_f32_e32 v0, v0, v36
	v_exp_f32_e32 v0, v0
	s_lshl_b32 s88, s0, 7
	v_bfe_u32 v36, v40, 1, 7
	v_mul_u32_u24_e32 v37, 0x2200, v42
	v_ldexp_f32 v0, v0, s1
	v_sub_f32_e32 v43, 1.0, v0
	v_lshlrev_b32_e32 v0, 6, v42
	v_lshl_add_u64 v[34:35], v[34:35], 0, s[88:89]
	v_lshlrev_b32_e32 v36, 1, v36
	v_lshlrev_b32_e32 v37, 1, v37
	v_lshl_add_u64 v[44:45], v[34:35], 0, v[0:1]
	v_add3_u32 v46, s15, v37, v36
	v_add3_u32 v47, s15, v36, v37
	global_load_dwordx4 v[34:37], v[44:45], off offset:2560
	v_cmp_gt_f32_e32 vcc, s69, v43
	s_and_b64 s[0:1], vcc, exec
	s_cselect_b32 s0, 32, 0
	v_ldexp_f32 v0, v43, s0
	v_log_f32_e32 v0, v0
	s_mov_b32 s0, 0x3f317217
	s_mov_b32 s8, 0x3fb8aa3b
	s_mov_b32 s9, 0xc2ce8ed0
	s_ashr_i32 s11, s10, 31
	s_waitcnt vmcnt(8)
	ds_write_b16 v46, v30
	ds_write_b16_d16_hi v47, v30 offset:272
	ds_write_b16 v46, v31 offset:544
	ds_write_b16_d16_hi v47, v31 offset:816
	ds_write_b16 v46, v32 offset:1088
	ds_write_b16_d16_hi v47, v32 offset:1360
	ds_write_b16 v46, v33 offset:1632
	ds_write_b16_d16_hi v47, v33 offset:1904
	s_waitcnt vmcnt(7)
	ds_write_b16 v46, v26 offset:2176
	ds_write_b16_d16_hi v47, v26 offset:2448
	ds_write_b16 v46, v27 offset:2720
	ds_write_b16_d16_hi v47, v27 offset:2992
	ds_write_b16 v46, v28 offset:3264
	ds_write_b16_d16_hi v47, v28 offset:3536
	ds_write_b16 v46, v29 offset:3808
	ds_write_b16_d16_hi v47, v29 offset:4080
	s_waitcnt vmcnt(6)
	ds_write_b16 v46, v22 offset:4352
	ds_write_b16_d16_hi v47, v22 offset:4624
	ds_write_b16 v46, v23 offset:4896
	ds_write_b16_d16_hi v47, v23 offset:5168
	ds_write_b16 v46, v24 offset:5440
	ds_write_b16_d16_hi v47, v24 offset:5712
	ds_write_b16 v46, v25 offset:5984
	ds_write_b16_d16_hi v47, v25 offset:6256
	s_waitcnt vmcnt(5)
	ds_write_b16 v46, v18 offset:6528
	ds_write_b16_d16_hi v47, v18 offset:6800
	ds_write_b16 v46, v19 offset:7072
	ds_write_b16_d16_hi v47, v19 offset:7344
	ds_write_b16 v46, v20 offset:7616
	ds_write_b16_d16_hi v47, v20 offset:7888
	ds_write_b16 v46, v21 offset:8160
	ds_write_b16_d16_hi v47, v21 offset:8432
	s_waitcnt vmcnt(4)
	ds_write_b16 v46, v14 offset:8704
	ds_write_b16_d16_hi v47, v14 offset:8976
	ds_write_b16 v46, v15 offset:9248
	ds_write_b16_d16_hi v47, v15 offset:9520
	ds_write_b16 v46, v16 offset:9792
	ds_write_b16_d16_hi v47, v16 offset:10064
	ds_write_b16 v46, v17 offset:10336
	ds_write_b16_d16_hi v47, v17 offset:10608
	s_waitcnt vmcnt(3)
	ds_write_b16 v46, v10 offset:10880
	ds_write_b16_d16_hi v47, v10 offset:11152
	ds_write_b16 v46, v11 offset:11424
	ds_write_b16_d16_hi v47, v11 offset:11696
	ds_write_b16 v46, v12 offset:11968
	ds_write_b16_d16_hi v47, v12 offset:12240
	ds_write_b16 v46, v13 offset:12512
	ds_write_b16_d16_hi v47, v13 offset:12784
	s_waitcnt vmcnt(2)
	ds_write_b16 v46, v6 offset:13056
	ds_write_b16_d16_hi v47, v6 offset:13328
	ds_write_b16 v46, v7 offset:13600
	ds_write_b16_d16_hi v47, v7 offset:13872
	global_load_dwordx4 v[10:13], v[44:45], off offset:2576
	ds_write_b16 v46, v8 offset:14144
	ds_write_b16_d16_hi v47, v8 offset:14416
	ds_write_b16 v46, v9 offset:14688
	ds_write_b16_d16_hi v47, v9 offset:14960
	s_waitcnt vmcnt(2)
	ds_write_b16 v46, v2 offset:15232
	ds_write_b16_d16_hi v47, v2 offset:15504
	ds_write_b16 v46, v3 offset:15776
	ds_write_b16_d16_hi v47, v3 offset:16048
	ds_write_b16 v46, v4 offset:16320
	ds_write_b16_d16_hi v47, v4 offset:16592
	global_load_dwordx4 v[14:17], v[44:45], off offset:2592
	v_mul_f32_e32 v2, 0x3f317217, v0
	v_fma_f32 v2, v0, s0, -v2
	v_fmac_f32_e32 v2, 0x3377d1cf, v0
	s_mov_b32 s0, 0x7f800000
	v_fmac_f32_e32 v2, 0x3f317217, v0
	v_cmp_lt_f32_e64 s[0:1], |v0|, s0
	ds_write_b16 v46, v5 offset:16864
	ds_write_b16_d16_hi v47, v5 offset:17136
	v_cndmask_b32_e64 v0, v0, v2, s[0:1]
	v_cndmask_b32_e32 v2, 0, v231, vcc
	v_sub_f32_e32 v6, v0, v2
	v_bitop3_b32 v0, v41, s2, v41 bitop3:0xc
	v_cvt_f32_ubyte0_e32 v0, v0
	v_mul_f32_e32 v2, v6, v0
	v_mul_f32_e32 v0, 0x3fb8aa3b, v2
	v_fma_f32 v3, v2, s8, -v0
	v_rndne_f32_e32 v4, v0
	v_fmac_f32_e32 v3, 0x32a5705f, v2
	v_sub_f32_e32 v0, v0, v4
	v_add_f32_e32 v0, v0, v3
	v_exp_f32_e32 v3, v0
	v_cvt_i32_f32_e32 v4, v4
	v_cmp_ngt_f32_e32 vcc, s9, v2
	s_waitcnt vmcnt(2)
	v_lshlrev_b32_e32 v8, 16, v34
	v_mad_i32_i24 v9, v42, s13, v46
	v_ldexp_f32 v3, v3, v4
	v_cndmask_b32_e32 v3, 0, v3, vcc
	v_cmp_nlt_f32_e32 vcc, s12, v2
	v_mad_i32_i24 v18, v42, s13, v47
	v_and_b32_e32 v0, 15, v40
	v_cndmask_b32_e32 v2, v61, v3, vcc
	v_mul_f32_e32 v7, 0x3e000000, v2
	global_load_dwordx4 v[2:5], v[44:45], off offset:2608
	v_mul_f32_e32 v8, v7, v8
	v_cvt_pk_bf16_f32 v8, v8, s0
	ds_write_b16 v9, v8 offset:34816
	v_and_b32_e32 v8, 0xffff0000, v34
	v_mul_f32_e32 v8, v7, v8
	v_cvt_pk_bf16_f32 v8, v8, s0
	ds_write_b16 v18, v8 offset:35088
	v_lshlrev_b32_e32 v8, 16, v35
	v_mul_f32_e32 v8, v7, v8
	v_cvt_pk_bf16_f32 v8, v8, s0
	ds_write_b16 v9, v8 offset:35360
	v_and_b32_e32 v8, 0xffff0000, v35
	v_mul_f32_e32 v8, v7, v8
	v_cvt_pk_bf16_f32 v8, v8, s0
	ds_write_b16 v18, v8 offset:35632
	v_lshlrev_b32_e32 v8, 16, v36
	v_mul_f32_e32 v8, v7, v8
	v_cvt_pk_bf16_f32 v8, v8, s0
	ds_write_b16 v9, v8 offset:35904
	v_and_b32_e32 v8, 0xffff0000, v36
	v_mul_f32_e32 v8, v7, v8
	v_cvt_pk_bf16_f32 v8, v8, s0
	ds_write_b16 v18, v8 offset:36176
	v_lshlrev_b32_e32 v8, 16, v37
	v_mul_f32_e32 v8, v7, v8
	v_cvt_pk_bf16_f32 v8, v8, s0
	ds_write_b16 v9, v8 offset:36448
	v_and_b32_e32 v8, 0xffff0000, v37
	v_mul_f32_e32 v8, v7, v8
	v_cvt_pk_bf16_f32 v8, v8, s0
	ds_write_b16 v18, v8 offset:36720
	v_and_b32_e32 v36, 0x60, v41
	s_waitcnt vmcnt(2)
	v_lshlrev_b32_e32 v8, 16, v10
	v_mul_f32_e32 v8, v7, v8
	v_cvt_pk_bf16_f32 v8, v8, s0
	ds_write_b16 v9, v8 offset:36992
	v_and_b32_e32 v8, 0xffff0000, v10
	v_mul_f32_e32 v8, v7, v8
	v_cvt_pk_bf16_f32 v8, v8, s0
	ds_write_b16 v18, v8 offset:37264
	v_lshlrev_b32_e32 v8, 16, v11
	v_mul_f32_e32 v8, v7, v8
	v_cvt_pk_bf16_f32 v8, v8, s0
	ds_write_b16 v9, v8 offset:37536
	v_and_b32_e32 v8, 0xffff0000, v11
	v_mul_f32_e32 v8, v7, v8
	v_cvt_pk_bf16_f32 v8, v8, s0
	ds_write_b16 v18, v8 offset:37808
	v_lshlrev_b32_e32 v8, 16, v12
	v_mul_f32_e32 v8, v7, v8
	v_cvt_pk_bf16_f32 v8, v8, s0
	ds_write_b16 v9, v8 offset:38080
	v_and_b32_e32 v8, 0xffff0000, v12
	v_mul_f32_e32 v8, v7, v8
	v_cvt_pk_bf16_f32 v8, v8, s0
	ds_write_b16 v18, v8 offset:38352
	v_lshlrev_b32_e32 v8, 16, v13
	v_mul_f32_e32 v8, v7, v8
	v_cvt_pk_bf16_f32 v8, v8, s0
	ds_write_b16 v9, v8 offset:38624
	v_and_b32_e32 v8, 0xffff0000, v13
	v_mul_f32_e32 v8, v7, v8
	v_cvt_pk_bf16_f32 v8, v8, s0
	ds_write_b16 v18, v8 offset:38896
	s_waitcnt vmcnt(1)
	v_lshlrev_b32_e32 v8, 16, v14
	v_mul_f32_e32 v8, v7, v8
	v_cvt_pk_bf16_f32 v8, v8, s0
	ds_write_b16 v9, v8 offset:39168
	v_and_b32_e32 v8, 0xffff0000, v14
	v_mul_f32_e32 v8, v7, v8
	v_cvt_pk_bf16_f32 v8, v8, s0
	ds_write_b16 v18, v8 offset:39440
	v_lshlrev_b32_e32 v8, 16, v15
	v_mul_f32_e32 v8, v7, v8
	v_cvt_pk_bf16_f32 v8, v8, s0
	ds_write_b16 v9, v8 offset:39712
	v_and_b32_e32 v8, 0xffff0000, v15
	v_mul_f32_e32 v8, v7, v8
	v_cvt_pk_bf16_f32 v8, v8, s0
	ds_write_b16 v18, v8 offset:39984
	v_lshlrev_b32_e32 v8, 16, v16
	v_mul_f32_e32 v8, v7, v8
	v_cvt_pk_bf16_f32 v8, v8, s0
	ds_write_b16 v9, v8 offset:40256
	v_and_b32_e32 v8, 0xffff0000, v16
	v_mul_f32_e32 v8, v7, v8
	v_cvt_pk_bf16_f32 v8, v8, s0
	ds_write_b16 v18, v8 offset:40528
	v_lshlrev_b32_e32 v8, 16, v17
	v_mul_f32_e32 v8, v7, v8
	v_cvt_pk_bf16_f32 v8, v8, s0
	ds_write_b16 v9, v8 offset:40800
	v_and_b32_e32 v8, 0xffff0000, v17
	v_mul_f32_e32 v8, v7, v8
	v_cvt_pk_bf16_f32 v8, v8, s0
	ds_write_b16 v18, v8 offset:41072
	s_waitcnt vmcnt(0)
	v_lshlrev_b32_e32 v8, 16, v2
	v_and_b32_e32 v2, 0xffff0000, v2
	v_mul_f32_e32 v2, v7, v2
	v_cvt_pk_bf16_f32 v2, v2, s0
	ds_write_b16 v18, v2 offset:41616
	v_lshlrev_b32_e32 v2, 16, v3
	v_mul_f32_e32 v2, v7, v2
	v_cvt_pk_bf16_f32 v2, v2, s0
	ds_write_b16 v9, v2 offset:41888
	v_and_b32_e32 v2, 0xffff0000, v3
	v_mul_f32_e32 v2, v7, v2
	v_cvt_pk_bf16_f32 v2, v2, s0
	ds_write_b16 v18, v2 offset:42160
	v_lshlrev_b32_e32 v2, 16, v4
	v_mul_f32_e32 v2, v7, v2
	v_cvt_pk_bf16_f32 v2, v2, s0
	ds_write_b16 v9, v2 offset:42432
	v_and_b32_e32 v2, 0xffff0000, v4
	v_mul_f32_e32 v2, v7, v2
	v_cvt_pk_bf16_f32 v2, v2, s0
	ds_write_b16 v18, v2 offset:42704
	v_lshlrev_b32_e32 v2, 16, v5
	v_mul_f32_e32 v2, v7, v2
	v_cvt_pk_bf16_f32 v2, v2, s0
	ds_write_b16 v9, v2 offset:42976
	v_and_b32_e32 v2, 0xffff0000, v5
	v_mul_f32_e32 v2, v7, v2
	v_mul_f32_e32 v8, v7, v8
	v_cvt_pk_bf16_f32 v2, v2, s0
	v_cvt_pk_bf16_f32 v8, v8, s0
	ds_write_b16 v18, v2 offset:43248
	v_bfe_u32 v7, v40, 4, 2
	v_or_b32_e32 v2, v36, v0
	ds_write_b16 v9, v8 offset:41344
	v_lshl_add_u32 v8, v7, 4, s15
	v_mul_u32_u24_e32 v2, 0x88, v2
	v_mul_u32_u24_e32 v9, 0x88, v0
	v_lshl_add_u32 v37, v2, 1, v8
	v_lshl_add_u32 v60, v9, 1, v8
	s_waitcnt lgkmcnt(0)
	s_barrier
	ds_read_b128 v[2:5], v37
	ds_read_b128 v[44:47], v37 offset:64
	ds_read_b128 v[8:11], v60 offset:34816
	ds_read_b128 v[40:43], v37 offset:4352
	ds_read_b128 v[16:19], v60 offset:39168
	ds_read_b128 v[24:27], v60 offset:43520
	ds_read_b128 v[32:35], v60 offset:47872
	ds_read_b128 v[52:55], v60 offset:43584
	s_waitcnt lgkmcnt(5)
	v_mfma_f32_16x16x32_bf16 v[12:15], v[2:5], v[8:11], 0
	ds_read_b128 v[48:51], v60 offset:39232
	ds_read_b128 v[56:59], v60 offset:47936
	v_lshlrev_b32_e32 v36, 6, v36
	s_waitcnt lgkmcnt(5)
	v_mfma_f32_16x16x32_bf16 v[20:23], v[2:5], v[16:19], 0
	s_lshl_b64 s[0:1], s[10:11], 15
	v_lshl_or_b32 v7, v7, 8, v36
	s_add_u32 s0, s24, s0
	s_waitcnt lgkmcnt(4)
	v_mfma_f32_16x16x32_bf16 v[28:31], v[2:5], v[24:27], 0
	v_or_b32_e32 v36, v7, v0
	s_addc_u32 s1, s25, s1
	v_lshlrev_b32_e32 v36, 2, v36
	s_waitcnt lgkmcnt(3)
	v_mfma_f32_16x16x32_bf16 v[2:5], v[2:5], v[32:35], 0
	v_mfma_f32_16x16x32_bf16 v[8:11], v[40:43], v[8:11], 0
	v_mfma_f32_16x16x32_bf16 v[16:19], v[40:43], v[16:19], 0
	v_mfma_f32_16x16x32_bf16 v[24:27], v[40:43], v[24:27], 0
	v_mfma_f32_16x16x32_bf16 v[32:35], v[40:43], v[32:35], 0
	ds_read_b128 v[40:43], v60 offset:34880
	s_waitcnt lgkmcnt(0)
	v_mfma_f32_16x16x32_bf16 v[12:15], v[44:47], v[40:43], v[12:15]
	v_mfma_f32_16x16x32_bf16 v[20:23], v[44:47], v[48:51], v[20:23]
	v_mfma_f32_16x16x32_bf16 v[28:31], v[44:47], v[52:55], v[28:31]
	v_mfma_f32_16x16x32_bf16 v[2:5], v[44:47], v[56:59], v[2:5]
	ds_read_b128 v[44:47], v37 offset:4416
	s_waitcnt lgkmcnt(0)
	v_mfma_f32_16x16x32_bf16 v[8:11], v[44:47], v[40:43], v[8:11]
	ds_read_b128 v[40:43], v37 offset:128
	v_mfma_f32_16x16x32_bf16 v[16:19], v[44:47], v[48:51], v[16:19]
	ds_read_b128 v[48:51], v60 offset:39296
	v_mfma_f32_16x16x32_bf16 v[24:27], v[44:47], v[52:55], v[24:27]
	ds_read_b128 v[52:55], v60 offset:43648
	v_mfma_f32_16x16x32_bf16 v[32:35], v[44:47], v[56:59], v[32:35]
	ds_read_b128 v[44:47], v60 offset:34944
	ds_read_b128 v[56:59], v60 offset:48000
	s_waitcnt lgkmcnt(1)
	v_mfma_f32_16x16x32_bf16 v[12:15], v[40:43], v[44:47], v[12:15]
	v_mfma_f32_16x16x32_bf16 v[20:23], v[40:43], v[48:51], v[20:23]
	v_mfma_f32_16x16x32_bf16 v[28:31], v[40:43], v[52:55], v[28:31]
	s_waitcnt lgkmcnt(0)
	v_mfma_f32_16x16x32_bf16 v[2:5], v[40:43], v[56:59], v[2:5]
	ds_read_b128 v[40:43], v37 offset:4480
	s_waitcnt lgkmcnt(0)
	v_mfma_f32_16x16x32_bf16 v[8:11], v[40:43], v[44:47], v[8:11]
	ds_read_b128 v[44:47], v37 offset:192
	v_mfma_f32_16x16x32_bf16 v[16:19], v[40:43], v[48:51], v[16:19]
	ds_read_b128 v[48:51], v60 offset:39360
	v_mfma_f32_16x16x32_bf16 v[24:27], v[40:43], v[52:55], v[24:27]
	ds_read_b128 v[52:55], v60 offset:43712
	v_mfma_f32_16x16x32_bf16 v[32:35], v[40:43], v[56:59], v[32:35]
	ds_read_b128 v[40:43], v60 offset:35008
	ds_read_b128 v[56:59], v60 offset:48064
	s_waitcnt lgkmcnt(1)
	v_mfma_f32_16x16x32_bf16 v[12:15], v[44:47], v[40:43], v[12:15]
	v_mfma_f32_16x16x32_bf16 v[20:23], v[44:47], v[48:51], v[20:23]
	v_mfma_f32_16x16x32_bf16 v[28:31], v[44:47], v[52:55], v[28:31]
	s_waitcnt lgkmcnt(0)
	v_mfma_f32_16x16x32_bf16 v[2:5], v[44:47], v[56:59], v[2:5]
	ds_read_b128 v[44:47], v37 offset:4544
	v_or_b32_e32 v37, 16, v0
	s_nop 1
	global_store_dword v36, v12, s[0:1]
	global_store_dword v36, v13, s[0:1] offset:256
	global_store_dword v36, v14, s[0:1] offset:512
	global_store_dword v36, v15, s[0:1] offset:768
	global_store_dword v36, v20, s[0:1] offset:64
	v_or_b32_e32 v12, v7, v37
	s_waitcnt lgkmcnt(0)
	v_mfma_f32_16x16x32_bf16 v[8:11], v[44:47], v[40:43], v[8:11]
	v_or_b32_e32 v40, 32, v0
	v_lshlrev_b32_e32 v12, 2, v12
	global_store_dword v12, v21, s[0:1] offset:256
	global_store_dword v12, v22, s[0:1] offset:512
	global_store_dword v12, v23, s[0:1] offset:768
	global_store_dword v36, v28, s[0:1] offset:128
	v_or_b32_e32 v12, v7, v40
	v_or_b32_e32 v41, 48, v0
	v_lshlrev_b32_e32 v12, 2, v12
	global_store_dword v12, v29, s[0:1] offset:256
	global_store_dword v12, v30, s[0:1] offset:512
	global_store_dword v12, v31, s[0:1] offset:768
	global_store_dword v36, v2, s[0:1] offset:192
	v_or_b32_e32 v2, v7, v41
	v_lshlrev_b32_e32 v2, 2, v2
	global_store_dword v2, v3, s[0:1] offset:256
	global_store_dword v2, v4, s[0:1] offset:512
	global_store_dword v2, v5, s[0:1] offset:768
	v_or_b32_e32 v2, 0x400, v7
	v_or_b32_e32 v3, v2, v0
	v_lshlrev_b32_e32 v3, 2, v3
	global_store_dword v3, v8, s[0:1]
	v_or_b32_e32 v3, 0x440, v7
	v_or_b32_e32 v4, v3, v0
	v_lshlrev_b32_e32 v4, 2, v4
	global_store_dword v4, v9, s[0:1]
	v_or_b32_e32 v4, 0x480, v7
	v_or_b32_e32 v5, v4, v0
	v_lshlrev_b32_e32 v5, 2, v5
	global_store_dword v5, v10, s[0:1]
	v_or_b32_e32 v5, 0x4c0, v7
	v_mfma_f32_16x16x32_bf16 v[16:19], v[44:47], v[48:51], v[16:19]
	v_or_b32_e32 v0, v5, v0
	v_lshlrev_b32_e32 v0, 2, v0
	global_store_dword v0, v11, s[0:1]
	v_or_b32_e32 v0, v2, v37
	v_lshlrev_b32_e32 v0, 2, v0
	s_nop 2
	global_store_dword v0, v16, s[0:1]
	v_or_b32_e32 v0, v3, v37
	v_lshlrev_b32_e32 v0, 2, v0
	global_store_dword v0, v17, s[0:1]
	v_or_b32_e32 v0, v4, v37
	v_lshlrev_b32_e32 v0, 2, v0
	v_mfma_f32_16x16x32_bf16 v[24:27], v[44:47], v[52:55], v[24:27]
	global_store_dword v0, v18, s[0:1]
	v_or_b32_e32 v0, v5, v37
	v_lshlrev_b32_e32 v0, 2, v0
	global_store_dword v0, v19, s[0:1]
	v_or_b32_e32 v0, v2, v40
	v_lshlrev_b32_e32 v0, 2, v0
	s_nop 1
	global_store_dword v0, v24, s[0:1]
	v_or_b32_e32 v0, v3, v40
	v_lshlrev_b32_e32 v0, 2, v0
	global_store_dword v0, v25, s[0:1]
	v_or_b32_e32 v0, v4, v40
	v_lshlrev_b32_e32 v0, 2, v0
	v_mfma_f32_16x16x32_bf16 v[32:35], v[44:47], v[56:59], v[32:35]
	global_store_dword v0, v26, s[0:1]
	v_or_b32_e32 v0, v5, v40
	v_lshlrev_b32_e32 v0, 2, v0
	global_store_dword v0, v27, s[0:1]
	v_or_b32_e32 v0, v2, v41
	v_lshlrev_b32_e32 v0, 2, v0
	s_nop 1
	global_store_dword v0, v32, s[0:1]
	v_or_b32_e32 v0, v3, v41
	v_lshlrev_b32_e32 v0, 2, v0
	global_store_dword v0, v33, s[0:1]
	v_or_b32_e32 v0, v4, v41
	v_lshlrev_b32_e32 v0, 2, v0
	global_store_dword v0, v34, s[0:1]
	v_or_b32_e32 v0, v5, v41
	v_lshlrev_b32_e32 v0, 2, v0
	global_store_dword v0, v35, s[0:1]
	s_add_i32 s0, s10, 0x80
	s_lshl_b32 s1, s0, 5
	v_mov_b32_e32 v7, v194
	s_barrier
	v_mov_b32_e32 v0, s1
	v_lshrrev_b32_e32 v8, 1, v7
	v_bfi_b32 v0, s2, v8, v0
	v_and_b32_e32 v9, 1, v7
	v_mad_i64_i32 v[38:39], s[4:5], v0, s3, v[38:39]
	v_lshl_add_u64 v[2:3], v[38:39], 0, s[6:7]
	v_lshlrev_b32_e32 v4, 7, v9
	v_mov_b32_e32 v5, v1
	v_lshl_add_u64 v[34:35], v[2:3], 0, v[4:5]
	global_load_dwordx4 v[10:13], v[34:35], off offset:3072
	global_load_dwordx4 v[14:17], v[34:35], off offset:3088
	global_load_dwordx4 v[18:21], v[34:35], off offset:3104
	global_load_dwordx4 v[2:5], v[34:35], off offset:3120
	global_load_dwordx4 v[22:25], v[34:35], off offset:3136
	global_load_dwordx4 v[26:29], v[34:35], off offset:3152
	global_load_dwordx4 v[30:33], v[34:35], off offset:3168
	s_nop 0
	global_load_dwordx4 v[34:37], v[34:35], off offset:3184
	v_bfe_u32 v40, v7, 1, 7
	v_mul_u32_u24_e32 v41, 0x2200, v9
	v_lshlrev_b32_e32 v41, 1, v41
	v_lshlrev_b32_e32 v40, 1, v40
	v_add3_u32 v44, s15, v41, v40
	v_add3_u32 v45, s15, v40, v41
	v_lshlrev_b32_e32 v0, 6, v9
	v_and_b32_e32 v55, 0x60, v8
	v_bfe_u32 v54, v7, 4, 2
	s_ashr_i32 s1, s0, 31
	s_mov_b64 s[4:5], -1
	s_waitcnt vmcnt(7)
	ds_write_b16 v44, v10
	ds_write_b16_d16_hi v45, v10 offset:272
	ds_write_b16 v44, v11 offset:544
	ds_write_b16_d16_hi v45, v11 offset:816
	ds_write_b16 v44, v12 offset:1088
	ds_write_b16_d16_hi v45, v12 offset:1360
	v_lshl_add_u64 v[10:11], v[38:39], 0, s[88:89]
	v_lshl_add_u64 v[42:43], v[10:11], 0, v[0:1]
	global_load_dwordx4 v[38:41], v[42:43], off offset:2560
	ds_write_b16 v44, v13 offset:1632
	ds_write_b16_d16_hi v45, v13 offset:1904
	s_waitcnt vmcnt(7)
	ds_write_b16 v44, v14 offset:2176
	ds_write_b16_d16_hi v45, v14 offset:2448
	ds_write_b16 v44, v15 offset:2720
	ds_write_b16_d16_hi v45, v15 offset:2992
	ds_write_b16 v44, v16 offset:3264
	ds_write_b16_d16_hi v45, v16 offset:3536
	ds_write_b16 v44, v17 offset:3808
	ds_write_b16_d16_hi v45, v17 offset:4080
	s_waitcnt vmcnt(6)
	ds_write_b16 v44, v18 offset:4352
	ds_write_b16_d16_hi v45, v18 offset:4624
	ds_write_b16 v44, v19 offset:4896
	ds_write_b16_d16_hi v45, v19 offset:5168
	ds_write_b16 v44, v20 offset:5440
	ds_write_b16_d16_hi v45, v20 offset:5712
	ds_write_b16 v44, v21 offset:5984
	ds_write_b16_d16_hi v45, v21 offset:6256
	s_waitcnt vmcnt(5)
	ds_write_b16 v44, v2 offset:6528
	ds_write_b16_d16_hi v45, v2 offset:6800
	ds_write_b16 v44, v3 offset:7072
	ds_write_b16_d16_hi v45, v3 offset:7344
	ds_write_b16 v44, v4 offset:7616
	ds_write_b16_d16_hi v45, v4 offset:7888
	ds_write_b16 v44, v5 offset:8160
	ds_write_b16_d16_hi v45, v5 offset:8432
	s_waitcnt vmcnt(4)
	ds_write_b16 v44, v22 offset:8704
	ds_write_b16_d16_hi v45, v22 offset:8976
	ds_write_b16 v44, v23 offset:9248
	ds_write_b16_d16_hi v45, v23 offset:9520
	ds_write_b16 v44, v24 offset:9792
	ds_write_b16_d16_hi v45, v24 offset:10064
	ds_write_b16 v44, v25 offset:10336
	global_load_dwordx4 v[2:5], v[42:43], off offset:2576
	ds_write_b16_d16_hi v45, v25 offset:10608
	s_waitcnt vmcnt(4)
	ds_write_b16 v44, v26 offset:10880
	ds_write_b16_d16_hi v45, v26 offset:11152
	ds_write_b16 v44, v27 offset:11424
	ds_write_b16_d16_hi v45, v27 offset:11696
	ds_write_b16 v44, v28 offset:11968
	ds_write_b16_d16_hi v45, v28 offset:12240
	ds_write_b16 v44, v29 offset:12512
	ds_write_b16_d16_hi v45, v29 offset:12784
	s_waitcnt vmcnt(3)
	ds_write_b16 v44, v30 offset:13056
	ds_write_b16_d16_hi v45, v30 offset:13328
	ds_write_b16 v44, v31 offset:13600
	ds_write_b16_d16_hi v45, v31 offset:13872
	ds_write_b16 v44, v32 offset:14144
	ds_write_b16_d16_hi v45, v32 offset:14416
	ds_write_b16 v44, v33 offset:14688
	ds_write_b16_d16_hi v45, v33 offset:14960
	s_waitcnt vmcnt(2)
	ds_write_b16 v44, v34 offset:15232
	ds_write_b16_d16_hi v45, v34 offset:15504
	ds_write_b16 v44, v35 offset:15776
	ds_write_b16_d16_hi v45, v35 offset:16048
	ds_write_b16 v44, v36 offset:16320
	ds_write_b16_d16_hi v45, v36 offset:16592
	global_load_dwordx4 v[10:13], v[42:43], off offset:2592
	v_bitop3_b32 v0, v8, s2, v8 bitop3:0xc
	v_cvt_f32_ubyte0_e32 v0, v0
	v_mul_f32_e32 v6, v6, v0
	v_mul_f32_e32 v0, 0x3fb8aa3b, v6
	v_fma_f32 v14, v6, s8, -v0
	v_rndne_f32_e32 v15, v0
	v_fmac_f32_e32 v14, 0x32a5705f, v6
	v_sub_f32_e32 v0, v0, v15
	v_add_f32_e32 v0, v0, v14
	v_exp_f32_e32 v14, v0
	v_cvt_i32_f32_e32 v15, v15
	v_cmp_ngt_f32_e32 vcc, s9, v6
	ds_write_b16 v44, v37 offset:16864
	ds_write_b16_d16_hi v45, v37 offset:17136
	v_mad_i32_i24 v19, v9, s13, v44
	v_ldexp_f32 v14, v14, v15
	v_cndmask_b32_e32 v14, 0, v14, vcc
	v_cmp_nlt_f32_e32 vcc, s12, v6
	v_mad_i32_i24 v9, v9, s13, v45
	v_and_b32_e32 v0, 15, v7
	v_cndmask_b32_e32 v6, v61, v14, vcc
	global_load_dwordx4 v[14:17], v[42:43], off offset:2608
	v_mul_f32_e32 v6, 0x3e000000, v6
	v_mul_u32_u24_e32 v7, 0x88, v0
	s_waitcnt vmcnt(3)
	v_lshlrev_b32_e32 v18, 16, v38
	v_mul_f32_e32 v18, v6, v18
	v_cvt_pk_bf16_f32 v18, v18, s0
	ds_write_b16 v19, v18 offset:34816
	v_and_b32_e32 v18, 0xffff0000, v38
	v_mul_f32_e32 v18, v6, v18
	v_cvt_pk_bf16_f32 v18, v18, s0
	ds_write_b16 v9, v18 offset:35088
	v_lshlrev_b32_e32 v18, 16, v39
	v_mul_f32_e32 v18, v6, v18
	v_cvt_pk_bf16_f32 v18, v18, s0
	ds_write_b16 v19, v18 offset:35360
	v_and_b32_e32 v18, 0xffff0000, v39
	v_mul_f32_e32 v18, v6, v18
	v_cvt_pk_bf16_f32 v18, v18, s0
	ds_write_b16 v9, v18 offset:35632
	v_lshlrev_b32_e32 v18, 16, v40
	v_mul_f32_e32 v18, v6, v18
	v_cvt_pk_bf16_f32 v18, v18, s0
	ds_write_b16 v19, v18 offset:35904
	v_and_b32_e32 v18, 0xffff0000, v40
	v_mul_f32_e32 v18, v6, v18
	v_cvt_pk_bf16_f32 v18, v18, s0
	ds_write_b16 v9, v18 offset:36176
	v_lshlrev_b32_e32 v18, 16, v41
	v_mul_f32_e32 v18, v6, v18
	v_cvt_pk_bf16_f32 v18, v18, s0
	ds_write_b16 v19, v18 offset:36448
	v_and_b32_e32 v18, 0xffff0000, v41
	v_mul_f32_e32 v18, v6, v18
	v_cvt_pk_bf16_f32 v18, v18, s0
	ds_write_b16 v9, v18 offset:36720
	s_waitcnt vmcnt(2)
	v_lshlrev_b32_e32 v18, 16, v2
	v_and_b32_e32 v2, 0xffff0000, v2
	v_mul_f32_e32 v2, v6, v2
	v_cvt_pk_bf16_f32 v2, v2, s0
	ds_write_b16 v9, v2 offset:37264
	v_lshlrev_b32_e32 v2, 16, v3
	v_mul_f32_e32 v2, v6, v2
	v_cvt_pk_bf16_f32 v2, v2, s0
	ds_write_b16 v19, v2 offset:37536
	v_and_b32_e32 v2, 0xffff0000, v3
	v_mul_f32_e32 v2, v6, v2
	v_cvt_pk_bf16_f32 v2, v2, s0
	ds_write_b16 v9, v2 offset:37808
	v_lshlrev_b32_e32 v2, 16, v4
	v_mul_f32_e32 v2, v6, v2
	v_cvt_pk_bf16_f32 v2, v2, s0
	ds_write_b16 v19, v2 offset:38080
	v_and_b32_e32 v2, 0xffff0000, v4
	v_mul_f32_e32 v2, v6, v2
	v_cvt_pk_bf16_f32 v2, v2, s0
	ds_write_b16 v9, v2 offset:38352
	v_lshlrev_b32_e32 v2, 16, v5
	v_mul_f32_e32 v2, v6, v2
	v_cvt_pk_bf16_f32 v2, v2, s0
	ds_write_b16 v19, v2 offset:38624
	v_and_b32_e32 v2, 0xffff0000, v5
	v_mul_f32_e32 v2, v6, v2
	v_cvt_pk_bf16_f32 v2, v2, s0
	ds_write_b16 v9, v2 offset:38896
	s_waitcnt vmcnt(1)
	v_lshlrev_b32_e32 v2, 16, v10
	v_mul_f32_e32 v2, v6, v2
	v_cvt_pk_bf16_f32 v2, v2, s0
	ds_write_b16 v19, v2 offset:39168
	v_and_b32_e32 v2, 0xffff0000, v10
	v_mul_f32_e32 v2, v6, v2
	v_cvt_pk_bf16_f32 v2, v2, s0
	ds_write_b16 v9, v2 offset:39440
	v_lshlrev_b32_e32 v2, 16, v11
	v_mul_f32_e32 v2, v6, v2
	v_cvt_pk_bf16_f32 v2, v2, s0
	ds_write_b16 v19, v2 offset:39712
	v_and_b32_e32 v2, 0xffff0000, v11
	v_mul_f32_e32 v2, v6, v2
	v_cvt_pk_bf16_f32 v2, v2, s0
	ds_write_b16 v9, v2 offset:39984
	v_lshlrev_b32_e32 v2, 16, v12
	v_mul_f32_e32 v2, v6, v2
	v_cvt_pk_bf16_f32 v2, v2, s0
	ds_write_b16 v19, v2 offset:40256
	v_and_b32_e32 v2, 0xffff0000, v12
	v_mul_f32_e32 v2, v6, v2
	v_cvt_pk_bf16_f32 v2, v2, s0
	ds_write_b16 v9, v2 offset:40528
	v_lshlrev_b32_e32 v2, 16, v13
	v_mul_f32_e32 v2, v6, v2
	v_cvt_pk_bf16_f32 v2, v2, s0
	ds_write_b16 v19, v2 offset:40800
	v_and_b32_e32 v2, 0xffff0000, v13
	v_mul_f32_e32 v2, v6, v2
	v_cvt_pk_bf16_f32 v2, v2, s0
	ds_write_b16 v9, v2 offset:41072
	s_waitcnt vmcnt(0)
	v_lshlrev_b32_e32 v2, 16, v14
	v_mul_f32_e32 v2, v6, v2
	v_cvt_pk_bf16_f32 v2, v2, s0
	ds_write_b16 v19, v2 offset:41344
	v_and_b32_e32 v2, 0xffff0000, v14
	v_mul_f32_e32 v2, v6, v2
	v_cvt_pk_bf16_f32 v2, v2, s0
	ds_write_b16 v9, v2 offset:41616
	v_lshlrev_b32_e32 v2, 16, v15
	v_mul_f32_e32 v2, v6, v2
	v_cvt_pk_bf16_f32 v2, v2, s0
	ds_write_b16 v19, v2 offset:41888
	v_and_b32_e32 v2, 0xffff0000, v15
	v_mul_f32_e32 v2, v6, v2
	v_cvt_pk_bf16_f32 v2, v2, s0
	ds_write_b16 v9, v2 offset:42160
	v_lshlrev_b32_e32 v2, 16, v16
	v_mul_f32_e32 v2, v6, v2
	v_cvt_pk_bf16_f32 v2, v2, s0
	ds_write_b16 v19, v2 offset:42432
	v_and_b32_e32 v2, 0xffff0000, v16
	v_mul_f32_e32 v2, v6, v2
	v_cvt_pk_bf16_f32 v2, v2, s0
	ds_write_b16 v9, v2 offset:42704
	v_lshlrev_b32_e32 v2, 16, v17
	v_mul_f32_e32 v2, v6, v2
	v_cvt_pk_bf16_f32 v2, v2, s0
	ds_write_b16 v19, v2 offset:42976
	v_and_b32_e32 v2, 0xffff0000, v17
	v_mul_f32_e32 v2, v6, v2
	v_cvt_pk_bf16_f32 v2, v2, s0
	ds_write_b16 v9, v2 offset:43248
	v_or_b32_e32 v2, v55, v0
	v_mul_f32_e32 v18, v6, v18
	v_lshl_add_u32 v6, v54, 4, s15
	v_mul_u32_u24_e32 v2, 0x88, v2
	v_cvt_pk_bf16_f32 v18, v18, s0
	v_lshl_add_u32 v56, v2, 1, v6
	v_lshl_add_u32 v57, v7, 1, v6
	ds_write_b16 v19, v18 offset:36992
	s_waitcnt lgkmcnt(0)
	s_barrier
	ds_read_b128 v[2:5], v56
	ds_read_b128 v[38:41], v56 offset:64
	ds_read_b128 v[6:9], v57 offset:34816
	ds_read_b128 v[34:37], v56 offset:4352
	ds_read_b128 v[14:17], v57 offset:39168
	ds_read_b128 v[22:25], v57 offset:43520
	ds_read_b128 v[30:33], v57 offset:47872
	ds_read_b128 v[46:49], v57 offset:43584
	s_waitcnt lgkmcnt(5)
	v_mfma_f32_16x16x32_bf16 v[10:13], v[2:5], v[6:9], 0
	ds_read_b128 v[42:45], v57 offset:39232
	ds_read_b128 v[50:53], v57 offset:47936
	s_lshl_b64 s[0:1], s[0:1], 15
	s_waitcnt lgkmcnt(5)
	v_mfma_f32_16x16x32_bf16 v[18:21], v[2:5], v[14:17], 0
	s_add_u32 s0, s24, s0
	s_addc_u32 s1, s25, s1
	s_waitcnt lgkmcnt(4)
	v_mfma_f32_16x16x32_bf16 v[26:29], v[2:5], v[22:25], 0
	s_waitcnt lgkmcnt(3)
	v_mfma_f32_16x16x32_bf16 v[2:5], v[2:5], v[30:33], 0
	v_mfma_f32_16x16x32_bf16 v[6:9], v[34:37], v[6:9], 0
	v_mfma_f32_16x16x32_bf16 v[14:17], v[34:37], v[14:17], 0
	v_mfma_f32_16x16x32_bf16 v[22:25], v[34:37], v[22:25], 0
	v_mfma_f32_16x16x32_bf16 v[30:33], v[34:37], v[30:33], 0
	ds_read_b128 v[34:37], v57 offset:34880
	s_waitcnt lgkmcnt(0)
	v_mfma_f32_16x16x32_bf16 v[10:13], v[38:41], v[34:37], v[10:13]
	v_mfma_f32_16x16x32_bf16 v[18:21], v[38:41], v[42:45], v[18:21]
	v_mfma_f32_16x16x32_bf16 v[26:29], v[38:41], v[46:49], v[26:29]
	v_mfma_f32_16x16x32_bf16 v[2:5], v[38:41], v[50:53], v[2:5]
	ds_read_b128 v[38:41], v56 offset:4416
	s_waitcnt lgkmcnt(0)
	v_mfma_f32_16x16x32_bf16 v[6:9], v[38:41], v[34:37], v[6:9]
	ds_read_b128 v[34:37], v56 offset:128
	v_mfma_f32_16x16x32_bf16 v[14:17], v[38:41], v[42:45], v[14:17]
	ds_read_b128 v[42:45], v57 offset:39296
	v_mfma_f32_16x16x32_bf16 v[22:25], v[38:41], v[46:49], v[22:25]
	ds_read_b128 v[46:49], v57 offset:43648
	v_mfma_f32_16x16x32_bf16 v[30:33], v[38:41], v[50:53], v[30:33]
	ds_read_b128 v[38:41], v57 offset:34944
	ds_read_b128 v[50:53], v57 offset:48000
	s_waitcnt lgkmcnt(1)
	v_mfma_f32_16x16x32_bf16 v[10:13], v[34:37], v[38:41], v[10:13]
	v_mfma_f32_16x16x32_bf16 v[18:21], v[34:37], v[42:45], v[18:21]
	v_mfma_f32_16x16x32_bf16 v[26:29], v[34:37], v[46:49], v[26:29]
	s_waitcnt lgkmcnt(0)
	v_mfma_f32_16x16x32_bf16 v[2:5], v[34:37], v[50:53], v[2:5]
	ds_read_b128 v[34:37], v56 offset:4480
	s_waitcnt lgkmcnt(0)
	v_mfma_f32_16x16x32_bf16 v[6:9], v[34:37], v[38:41], v[6:9]
	ds_read_b128 v[38:41], v56 offset:192
	v_mfma_f32_16x16x32_bf16 v[14:17], v[34:37], v[42:45], v[14:17]
	ds_read_b128 v[42:45], v57 offset:39360
	v_mfma_f32_16x16x32_bf16 v[22:25], v[34:37], v[46:49], v[22:25]
	ds_read_b128 v[46:49], v57 offset:43712
	v_mfma_f32_16x16x32_bf16 v[30:33], v[34:37], v[50:53], v[30:33]
	ds_read_b128 v[34:37], v57 offset:35008
	ds_read_b128 v[50:53], v57 offset:48064
	s_waitcnt lgkmcnt(1)
	v_mfma_f32_16x16x32_bf16 v[10:13], v[38:41], v[34:37], v[10:13]
	v_mfma_f32_16x16x32_bf16 v[18:21], v[38:41], v[42:45], v[18:21]
	v_mfma_f32_16x16x32_bf16 v[26:29], v[38:41], v[46:49], v[26:29]
	s_waitcnt lgkmcnt(0)
	v_mfma_f32_16x16x32_bf16 v[2:5], v[38:41], v[50:53], v[2:5]
	ds_read_b128 v[38:41], v56 offset:4544
	s_waitcnt lgkmcnt(0)
	v_mfma_f32_16x16x32_bf16 v[6:9], v[38:41], v[34:37], v[6:9]
	v_lshlrev_b32_e32 v37, 6, v55
	v_lshl_or_b32 v37, v54, 8, v37
	v_or_b32_e32 v34, 16, v0
	v_mfma_f32_16x16x32_bf16 v[14:17], v[38:41], v[42:45], v[14:17]
	v_or_b32_e32 v35, 32, v0
	v_or_b32_e32 v36, 48, v0
	v_mfma_f32_16x16x32_bf16 v[22:25], v[38:41], v[46:49], v[22:25]
	v_mfma_f32_16x16x32_bf16 v[30:33], v[38:41], v[50:53], v[30:33]
	v_or_b32_e32 v38, v37, v0
	v_lshlrev_b32_e32 v38, 2, v38
	global_store_dword v38, v10, s[0:1]
	global_store_dword v38, v11, s[0:1] offset:256
	global_store_dword v38, v12, s[0:1] offset:512
	global_store_dword v38, v13, s[0:1] offset:768
	global_store_dword v38, v18, s[0:1] offset:64
	v_or_b32_e32 v10, v37, v34
	v_lshlrev_b32_e32 v10, 2, v10
	global_store_dword v10, v19, s[0:1] offset:256
	global_store_dword v10, v20, s[0:1] offset:512
	global_store_dword v10, v21, s[0:1] offset:768
	global_store_dword v38, v26, s[0:1] offset:128
	v_or_b32_e32 v10, v37, v35
	v_lshlrev_b32_e32 v10, 2, v10
	global_store_dword v10, v27, s[0:1] offset:256
	global_store_dword v10, v28, s[0:1] offset:512
	global_store_dword v10, v29, s[0:1] offset:768
	global_store_dword v38, v2, s[0:1] offset:192
	v_or_b32_e32 v2, v37, v36
	v_lshlrev_b32_e32 v2, 2, v2
	global_store_dword v2, v3, s[0:1] offset:256
	global_store_dword v2, v4, s[0:1] offset:512
	global_store_dword v2, v5, s[0:1] offset:768
	v_or_b32_e32 v2, 0x400, v37
	v_or_b32_e32 v3, v2, v0
	v_lshlrev_b32_e32 v3, 2, v3
	global_store_dword v3, v6, s[0:1]
	v_or_b32_e32 v3, 0x440, v37
	v_or_b32_e32 v4, v3, v0
	v_lshlrev_b32_e32 v4, 2, v4
	global_store_dword v4, v7, s[0:1]
	v_or_b32_e32 v4, 0x480, v37
	v_or_b32_e32 v5, v4, v0
	v_lshlrev_b32_e32 v5, 2, v5
	global_store_dword v5, v8, s[0:1]
	v_or_b32_e32 v5, 0x4c0, v37
	v_or_b32_e32 v0, v5, v0
	v_lshlrev_b32_e32 v0, 2, v0
	global_store_dword v0, v9, s[0:1]
	v_or_b32_e32 v0, v2, v34
	v_lshlrev_b32_e32 v0, 2, v0
	global_store_dword v0, v14, s[0:1]
	v_or_b32_e32 v0, v3, v34
	v_lshlrev_b32_e32 v0, 2, v0
	global_store_dword v0, v15, s[0:1]
	v_or_b32_e32 v0, v4, v34
	v_lshlrev_b32_e32 v0, 2, v0
	global_store_dword v0, v16, s[0:1]
	v_or_b32_e32 v0, v5, v34
	v_lshlrev_b32_e32 v0, 2, v0
	global_store_dword v0, v17, s[0:1]
	v_or_b32_e32 v0, v2, v35
	v_lshlrev_b32_e32 v0, 2, v0
	global_store_dword v0, v22, s[0:1]
	v_or_b32_e32 v0, v3, v35
	v_lshlrev_b32_e32 v0, 2, v0
	global_store_dword v0, v23, s[0:1]
	v_or_b32_e32 v0, v4, v35
	v_lshlrev_b32_e32 v0, 2, v0
	global_store_dword v0, v24, s[0:1]
	v_or_b32_e32 v0, v5, v35
	v_lshlrev_b32_e32 v0, 2, v0
	global_store_dword v0, v25, s[0:1]
	v_or_b32_e32 v0, v2, v36
	v_lshlrev_b32_e32 v0, 2, v0
	global_store_dword v0, v30, s[0:1]
	v_or_b32_e32 v0, v3, v36
	v_lshlrev_b32_e32 v0, 2, v0
	global_store_dword v0, v31, s[0:1]
	v_or_b32_e32 v0, v4, v36
	v_lshlrev_b32_e32 v0, 2, v0
	global_store_dword v0, v32, s[0:1]
	v_or_b32_e32 v0, v5, v36
	v_lshlrev_b32_e32 v0, 2, v0
	global_store_dword v0, v33, s[0:1]
	s_barrier
